# hand-written DSA attention: logits on 4x4x4 f16 MFMA with 4 lanes sharing each gathered K row (permlane reduce-scatter), packed-f32 PV, one index lookup per query for both KV groups, K/q prefetch acro
# speedup vs baseline: 1.0783x; 1.0090x over previous
.LBB0_284:
	s_waitcnt vmcnt(0) lgkmcnt(0)
	v_readlane_b32 s56, v255, 41
	v_readlane_b32 s57, v255, 42
	v_readlane_b32 s2, v253, 22
	v_mbcnt_lo_u32_b32 v0, -1, 0
	v_mbcnt_hi_u32_b32 v0, -1, v0
	s_lshr_b32 s15, s2, 3
	v_and_b32_e32 v1, 7, v0
	v_lshrrev_b32_e32 v2, 3, v0
	v_lshlrev_b32_e32 v2, 4, v2
	v_and_b32_e32 v3, 3, v0
	v_lshlrev_b32_e32 v3, 7, v3
	v_lshrrev_b32_e32 v25, 4, v0
	v_lshlrev_b32_e32 v25, 5, v25
	v_add_u32_e32 v3, v3, v25
	v_and_b32_e32 v24, 15, v0
	v_bfe_u32 v26, v0, 4, 1
	v_lshlrev_b32_e32 v26, 5, v26
	v_lshrrev_b32_e32 v40, 5, v0
	v_lshl_add_u32 v26, v40, 6, v26
	v_add_u32_e32 v26, v26, v24
	v_mov_b32_e32 v72, 0xff800000
	s_mul_i32 s3, s15, 0xc00
	v_lshl_add_u32 v73, v26, 4, s3
	v_lshl_add_u32 v74, v1, 4, s3
	v_add_u32_e32 v75, 0x1200, v2
	v_cmp_eq_u32_e64 s[4:5], 0, v1
	s_mov_b32 s6, 0
	s_mov_b32 s2, s15
	s_add_i32 s14, s62, s2
	s_mul_i32 s8, s2, 0x600
	s_add_i32 s8, s8, 0x18000
	s_lshl_b32 s3, s2, 2
	s_add_i32 s3, s3, 0x24000
	v_mov_b32_e32 v40, s3
	ds_read_b32 v40, v40
	s_mul_i32 s2, s14, s68
	s_mul_hi_u32 s3, s14, s68
	s_add_u32 s12, s56, s2
	s_addc_u32 s13, s57, s3
	s_mul_i32 s2, s14, s64
	v_add_u32_e32 v71, s2, v2
	s_waitcnt lgkmcnt(0)
	v_readfirstlane_b32 s7, v40
	s_min_i32 s7, s7, 0x100
	s_add_i32 s9, s7, -1
	v_min_u32_e32 v40, s9, v24
	v_lshl_add_u32 v40, v40, 1, s8
	ds_read_u16 v8, v40
	v_add_u32_e32 v42, 16, v24
	v_min_u32_e32 v42, s9, v42
	v_lshl_add_u32 v42, v42, 1, s8
	ds_read_u16 v9, v42
	v_add_u32_e32 v43, 32, v24
	v_min_u32_e32 v43, s9, v43
	v_lshl_add_u32 v43, v43, 1, s8
	ds_read_u16 v10, v43
	v_add_u32_e32 v40, 48, v24
	v_min_u32_e32 v40, s9, v40
	v_lshl_add_u32 v40, v40, 1, s8
	ds_read_u16 v11, v40
	v_add_u32_e32 v42, 64, v24
	v_min_u32_e32 v42, s9, v42
	v_lshl_add_u32 v42, v42, 1, s8
	ds_read_u16 v12, v42
	v_add_u32_e32 v43, 80, v24
	v_min_u32_e32 v43, s9, v43
	v_lshl_add_u32 v43, v43, 1, s8
	ds_read_u16 v13, v43
	v_add_u32_e32 v40, 96, v24
	v_min_u32_e32 v40, s9, v40
	v_lshl_add_u32 v40, v40, 1, s8
	ds_read_u16 v14, v40
	v_add_u32_e32 v42, 112, v24
	v_min_u32_e32 v42, s9, v42
	v_lshl_add_u32 v42, v42, 1, s8
	ds_read_u16 v15, v42
	v_add_u32_e32 v43, 128, v24
	v_min_u32_e32 v43, s9, v43
	v_lshl_add_u32 v43, v43, 1, s8
	ds_read_u16 v16, v43
	v_add_u32_e32 v40, 144, v24
	v_min_u32_e32 v40, s9, v40
	v_lshl_add_u32 v40, v40, 1, s8
	ds_read_u16 v17, v40
	v_add_u32_e32 v42, 160, v24
	v_min_u32_e32 v42, s9, v42
	v_lshl_add_u32 v42, v42, 1, s8
	ds_read_u16 v18, v42
	v_add_u32_e32 v43, 176, v24
	v_min_u32_e32 v43, s9, v43
	v_lshl_add_u32 v43, v43, 1, s8
	ds_read_u16 v19, v43
	v_add_u32_e32 v40, 192, v24
	v_min_u32_e32 v40, s9, v40
	v_lshl_add_u32 v40, v40, 1, s8
	ds_read_u16 v20, v40
	v_add_u32_e32 v42, 208, v24
	v_min_u32_e32 v42, s9, v42
	v_lshl_add_u32 v42, v42, 1, s8
	ds_read_u16 v21, v42
	v_add_u32_e32 v43, 224, v24
	v_min_u32_e32 v43, s9, v43
	v_lshl_add_u32 v43, v43, 1, s8
	ds_read_u16 v22, v43
	v_add_u32_e32 v40, 240, v24
	v_min_u32_e32 v40, s9, v40
	v_lshl_add_u32 v40, v40, 1, s8
	ds_read_u16 v23, v40
	v_min_u32_e32 v42, s9, v1
	v_lshl_add_u32 v42, v42, 1, s8
	ds_read_u16 v44, v42
	v_add_u32_e32 v43, 8, v1
	v_min_u32_e32 v43, s9, v43
	v_lshl_add_u32 v43, v43, 1, s8
	ds_read_u16 v45, v43
	v_add_u32_e32 v40, 16, v1
	v_min_u32_e32 v40, s9, v40
	v_lshl_add_u32 v40, v40, 1, s8
	ds_read_u16 v46, v40
	v_add_u32_e32 v42, 24, v1
	v_min_u32_e32 v42, s9, v42
	v_lshl_add_u32 v42, v42, 1, s8
	ds_read_u16 v47, v42
	v_add_u32_e32 v43, 32, v1
	v_min_u32_e32 v43, s9, v43
	v_lshl_add_u32 v43, v43, 1, s8
	ds_read_u16 v48, v43
	v_add_u32_e32 v40, 40, v1
	v_min_u32_e32 v40, s9, v40
	v_lshl_add_u32 v40, v40, 1, s8
	ds_read_u16 v49, v40
	v_add_u32_e32 v42, 48, v1
	v_min_u32_e32 v42, s9, v42
	v_lshl_add_u32 v42, v42, 1, s8
	ds_read_u16 v50, v42
	v_add_u32_e32 v43, 56, v1
	v_min_u32_e32 v43, s9, v43
	v_lshl_add_u32 v43, v43, 1, s8
	ds_read_u16 v51, v43
	v_add_u32_e32 v40, 64, v1
	v_min_u32_e32 v40, s9, v40
	v_lshl_add_u32 v40, v40, 1, s8
	ds_read_u16 v52, v40
	v_add_u32_e32 v42, 72, v1
	v_min_u32_e32 v42, s9, v42
	v_lshl_add_u32 v42, v42, 1, s8
	ds_read_u16 v53, v42
	v_add_u32_e32 v43, 80, v1
	v_min_u32_e32 v43, s9, v43
	v_lshl_add_u32 v43, v43, 1, s8
	ds_read_u16 v54, v43
	v_add_u32_e32 v40, 88, v1
	v_min_u32_e32 v40, s9, v40
	v_lshl_add_u32 v40, v40, 1, s8
	ds_read_u16 v55, v40
	v_add_u32_e32 v42, 96, v1
	v_min_u32_e32 v42, s9, v42
	v_lshl_add_u32 v42, v42, 1, s8
	ds_read_u16 v56, v42
	v_add_u32_e32 v43, 104, v1
	v_min_u32_e32 v43, s9, v43
	v_lshl_add_u32 v43, v43, 1, s8
	ds_read_u16 v57, v43
	v_add_u32_e32 v40, 112, v1
	v_min_u32_e32 v40, s9, v40
	v_lshl_add_u32 v40, v40, 1, s8
	ds_read_u16 v58, v40
	v_add_u32_e32 v42, 120, v1
	v_min_u32_e32 v42, s9, v42
	v_lshl_add_u32 v42, v42, 1, s8
	ds_read_u16 v59, v42
	s_waitcnt lgkmcnt(0)
	v_mad_u32_u24 v8, v8, s64, v25
	v_mad_u32_u24 v9, v9, s64, v25
	v_mad_u32_u24 v10, v10, s64, v25
	v_mad_u32_u24 v11, v11, s64, v25
	v_mad_u32_u24 v12, v12, s64, v25
	v_mad_u32_u24 v13, v13, s64, v25
	v_mad_u32_u24 v14, v14, s64, v25
	v_mad_u32_u24 v15, v15, s64, v25
	v_mad_u32_u24 v16, v16, s64, v25
	v_mad_u32_u24 v17, v17, s64, v25
	v_mad_u32_u24 v18, v18, s64, v25
	v_mad_u32_u24 v19, v19, s64, v25
	v_mad_u32_u24 v20, v20, s64, v25
	v_mad_u32_u24 v21, v21, s64, v25
	v_mad_u32_u24 v22, v22, s64, v25
	v_mad_u32_u24 v23, v23, s64, v25
	v_mad_u32_u24 v44, v44, s64, v2
	v_mad_u32_u24 v45, v45, s64, v2
	v_mad_u32_u24 v46, v46, s64, v2
	v_mad_u32_u24 v47, v47, s64, v2
	v_mad_u32_u24 v48, v48, s64, v2
	v_mad_u32_u24 v49, v49, s64, v2
	v_mad_u32_u24 v50, v50, s64, v2
	v_mad_u32_u24 v51, v51, s64, v2
	v_mad_u32_u24 v52, v52, s64, v2
	v_mad_u32_u24 v53, v53, s64, v2
	v_mad_u32_u24 v54, v54, s64, v2
	v_mad_u32_u24 v55, v55, s64, v2
	v_mad_u32_u24 v56, v56, s64, v2
	v_mad_u32_u24 v57, v57, s64, v2
	v_mad_u32_u24 v58, v58, s64, v2
	v_mad_u32_u24 v59, v59, s64, v2
	v_accvgpr_write_b32 a160, v44
	v_accvgpr_write_b32 a161, v45
	v_accvgpr_write_b32 a162, v46
	v_accvgpr_write_b32 a163, v47
	v_accvgpr_write_b32 a164, v48
	v_accvgpr_write_b32 a165, v49
	v_accvgpr_write_b32 a166, v50
	v_accvgpr_write_b32 a167, v51
	v_accvgpr_write_b32 a168, v52
	v_accvgpr_write_b32 a169, v53
	v_accvgpr_write_b32 a170, v54
	v_accvgpr_write_b32 a171, v55
	v_accvgpr_write_b32 a172, v56
	v_accvgpr_write_b32 a173, v57
	v_accvgpr_write_b32 a174, v58
	v_accvgpr_write_b32 a175, v59
	v_add_u32_e32 v43, 128, v1
	v_min_u32_e32 v43, s9, v43
	v_lshl_add_u32 v43, v43, 1, s8
	ds_read_u16 v44, v43
	v_add_u32_e32 v40, 136, v1
	v_min_u32_e32 v40, s9, v40
	v_lshl_add_u32 v40, v40, 1, s8
	ds_read_u16 v45, v40
	v_add_u32_e32 v42, 144, v1
	v_min_u32_e32 v42, s9, v42
	v_lshl_add_u32 v42, v42, 1, s8
	ds_read_u16 v46, v42
	v_add_u32_e32 v43, 152, v1
	v_min_u32_e32 v43, s9, v43
	v_lshl_add_u32 v43, v43, 1, s8
	ds_read_u16 v47, v43
	v_add_u32_e32 v40, 160, v1
	v_min_u32_e32 v40, s9, v40
	v_lshl_add_u32 v40, v40, 1, s8
	ds_read_u16 v48, v40
	v_add_u32_e32 v42, 168, v1
	v_min_u32_e32 v42, s9, v42
	v_lshl_add_u32 v42, v42, 1, s8
	ds_read_u16 v49, v42
	v_add_u32_e32 v43, 176, v1
	v_min_u32_e32 v43, s9, v43
	v_lshl_add_u32 v43, v43, 1, s8
	ds_read_u16 v50, v43
	v_add_u32_e32 v40, 184, v1
	v_min_u32_e32 v40, s9, v40
	v_lshl_add_u32 v40, v40, 1, s8
	ds_read_u16 v51, v40
	v_add_u32_e32 v42, 192, v1
	v_min_u32_e32 v42, s9, v42
	v_lshl_add_u32 v42, v42, 1, s8
	ds_read_u16 v52, v42
	v_add_u32_e32 v43, 200, v1
	v_min_u32_e32 v43, s9, v43
	v_lshl_add_u32 v43, v43, 1, s8
	ds_read_u16 v53, v43
	v_add_u32_e32 v40, 208, v1
	v_min_u32_e32 v40, s9, v40
	v_lshl_add_u32 v40, v40, 1, s8
	ds_read_u16 v54, v40
	v_add_u32_e32 v42, 216, v1
	v_min_u32_e32 v42, s9, v42
	v_lshl_add_u32 v42, v42, 1, s8
	ds_read_u16 v55, v42
	v_add_u32_e32 v43, 224, v1
	v_min_u32_e32 v43, s9, v43
	v_lshl_add_u32 v43, v43, 1, s8
	ds_read_u16 v56, v43
	v_add_u32_e32 v40, 232, v1
	v_min_u32_e32 v40, s9, v40
	v_lshl_add_u32 v40, v40, 1, s8
	ds_read_u16 v57, v40
	v_add_u32_e32 v42, 240, v1
	v_min_u32_e32 v42, s9, v42
	v_lshl_add_u32 v42, v42, 1, s8
	ds_read_u16 v58, v42
	v_add_u32_e32 v43, 248, v1
	v_min_u32_e32 v43, s9, v43
	v_lshl_add_u32 v43, v43, 1, s8
	ds_read_u16 v59, v43
	s_waitcnt lgkmcnt(0)
	v_mad_u32_u24 v44, v44, s64, v2
	v_mad_u32_u24 v45, v45, s64, v2
	v_mad_u32_u24 v46, v46, s64, v2
	v_mad_u32_u24 v47, v47, s64, v2
	v_mad_u32_u24 v48, v48, s64, v2
	v_mad_u32_u24 v49, v49, s64, v2
	v_mad_u32_u24 v50, v50, s64, v2
	v_mad_u32_u24 v51, v51, s64, v2
	v_mad_u32_u24 v52, v52, s64, v2
	v_mad_u32_u24 v53, v53, s64, v2
	v_mad_u32_u24 v54, v54, s64, v2
	v_mad_u32_u24 v55, v55, s64, v2
	v_mad_u32_u24 v56, v56, s64, v2
	v_mad_u32_u24 v57, v57, s64, v2
	v_mad_u32_u24 v58, v58, s64, v2
	v_mad_u32_u24 v59, v59, s64, v2
	v_accvgpr_write_b32 a176, v44
	v_accvgpr_write_b32 a177, v45
	v_accvgpr_write_b32 a178, v46
	v_accvgpr_write_b32 a179, v47
	v_accvgpr_write_b32 a180, v48
	v_accvgpr_write_b32 a181, v49
	v_accvgpr_write_b32 a182, v50
	v_accvgpr_write_b32 a183, v51
	v_accvgpr_write_b32 a184, v52
	v_accvgpr_write_b32 a185, v53
	v_accvgpr_write_b32 a186, v54
	v_accvgpr_write_b32 a187, v55
	v_accvgpr_write_b32 a188, v56
	v_accvgpr_write_b32 a189, v57
	v_accvgpr_write_b32 a190, v58
	v_accvgpr_write_b32 a191, v59
	v_mov_b32_e32 v70, v71
	global_load_dwordx4 a[0:3], v8, s[96:97] offset:0
	global_load_dwordx4 a[4:7], v8, s[96:97] offset:16
	global_load_dwordx4 a[8:11], v9, s[96:97] offset:0
	global_load_dwordx4 a[12:15], v9, s[96:97] offset:16
	global_load_dwordx4 a[16:19], v10, s[96:97] offset:0
	global_load_dwordx4 a[20:23], v10, s[96:97] offset:16
	global_load_dwordx4 a[24:27], v11, s[96:97] offset:0
	global_load_dwordx4 a[28:31], v11, s[96:97] offset:16
	global_load_dwordx4 a[32:35], v12, s[96:97] offset:0
	global_load_dwordx4 a[36:39], v12, s[96:97] offset:16
	global_load_dwordx4 a[40:43], v13, s[96:97] offset:0
	global_load_dwordx4 a[44:47], v13, s[96:97] offset:16
	global_load_dwordx4 a[48:51], v14, s[96:97] offset:0
	global_load_dwordx4 a[52:55], v14, s[96:97] offset:16
	global_load_dwordx4 a[56:59], v15, s[96:97] offset:0
	global_load_dwordx4 a[60:63], v15, s[96:97] offset:16
	global_load_dwordx4 a[64:67], v16, s[96:97] offset:0
	global_load_dwordx4 a[68:71], v16, s[96:97] offset:16
	global_load_dwordx4 a[72:75], v17, s[96:97] offset:0
	global_load_dwordx4 a[76:79], v17, s[96:97] offset:16
	global_load_dwordx4 a[80:83], v18, s[96:97] offset:0
	global_load_dwordx4 a[84:87], v18, s[96:97] offset:16
	global_load_dwordx4 a[88:91], v19, s[96:97] offset:0
	global_load_dwordx4 a[92:95], v19, s[96:97] offset:16
	global_load_dwordx4 a[96:99], v20, s[96:97] offset:0
	global_load_dwordx4 a[100:103], v20, s[96:97] offset:16
	global_load_dwordx4 a[104:107], v21, s[96:97] offset:0
	global_load_dwordx4 a[108:111], v21, s[96:97] offset:16
	global_load_dwordx4 a[112:115], v22, s[96:97] offset:0
	global_load_dwordx4 a[116:119], v22, s[96:97] offset:16
	global_load_dwordx4 a[120:123], v23, s[96:97] offset:0
	global_load_dwordx4 a[124:127], v23, s[96:97] offset:16
	global_load_dwordx4 a[144:147], v3, s[12:13] offset:3072
	global_load_dwordx4 a[148:151], v3, s[12:13] offset:3088
.Latt_query:
	v_accvgpr_read_b32 v27, a160
	global_load_dwordx4 v[124:127], v27, s[96:97] offset:256
	v_accvgpr_read_b32 v28, a161
	global_load_dwordx4 v[128:131], v28, s[96:97] offset:256
	v_accvgpr_read_b32 v29, a162
	global_load_dwordx4 v[132:135], v29, s[96:97] offset:256
	v_accvgpr_read_b32 v30, a163
	global_load_dwordx4 v[136:139], v30, s[96:97] offset:256
	v_accvgpr_read_b32 v27, a164
	global_load_dwordx4 v[140:143], v27, s[96:97] offset:256
	v_accvgpr_read_b32 v28, a165
	global_load_dwordx4 v[144:147], v28, s[96:97] offset:256
	v_accvgpr_read_b32 v29, a166
	global_load_dwordx4 v[148:151], v29, s[96:97] offset:256
	v_accvgpr_read_b32 v30, a167
	global_load_dwordx4 v[152:155], v30, s[96:97] offset:256
	v_accvgpr_read_b32 v27, a168
	global_load_dwordx4 v[156:159], v27, s[96:97] offset:256
	v_accvgpr_read_b32 v28, a169
	global_load_dwordx4 v[160:163], v28, s[96:97] offset:256
	v_accvgpr_read_b32 v29, a170
	global_load_dwordx4 v[164:167], v29, s[96:97] offset:256
	v_accvgpr_read_b32 v30, a171
	global_load_dwordx4 v[168:171], v30, s[96:97] offset:256
	v_accvgpr_read_b32 v27, a172
	global_load_dwordx4 v[172:175], v27, s[96:97] offset:256
	v_accvgpr_read_b32 v28, a173
	global_load_dwordx4 v[176:179], v28, s[96:97] offset:256
	v_accvgpr_read_b32 v29, a174
	global_load_dwordx4 v[180:183], v29, s[96:97] offset:256
	v_accvgpr_read_b32 v30, a175
	global_load_dwordx4 v[184:187], v30, s[96:97] offset:256
	s_waitcnt vmcnt(16)
	v_mfma_f32_4x4x4_16b_f16 v[92:95], a[144:145], a[0:1], 0
	v_mfma_f32_4x4x4_16b_f16 v[96:99], a[144:145], a[8:9], 0
	v_mfma_f32_4x4x4_16b_f16 v[100:103], a[144:145], a[16:17], 0
	v_mfma_f32_4x4x4_16b_f16 v[104:107], a[144:145], a[24:25], 0
	v_mfma_f32_4x4x4_16b_f16 v[108:111], a[144:145], a[32:33], 0
	v_mfma_f32_4x4x4_16b_f16 v[112:115], a[144:145], a[40:41], 0
	v_mfma_f32_4x4x4_16b_f16 v[116:119], a[144:145], a[48:49], 0
	v_mfma_f32_4x4x4_16b_f16 v[120:123], a[144:145], a[56:57], 0
	v_mfma_f32_4x4x4_16b_f16 v[92:95], a[146:147], a[2:3], v[92:95]
	v_mfma_f32_4x4x4_16b_f16 v[96:99], a[146:147], a[10:11], v[96:99]
	v_mfma_f32_4x4x4_16b_f16 v[100:103], a[146:147], a[18:19], v[100:103]
	v_mfma_f32_4x4x4_16b_f16 v[104:107], a[146:147], a[26:27], v[104:107]
	v_mfma_f32_4x4x4_16b_f16 v[108:111], a[146:147], a[34:35], v[108:111]
	v_mfma_f32_4x4x4_16b_f16 v[112:115], a[146:147], a[42:43], v[112:115]
	v_mfma_f32_4x4x4_16b_f16 v[116:119], a[146:147], a[50:51], v[116:119]
	v_mfma_f32_4x4x4_16b_f16 v[120:123], a[146:147], a[58:59], v[120:123]
	v_mfma_f32_4x4x4_16b_f16 v[92:95], a[148:149], a[4:5], v[92:95]
	v_mfma_f32_4x4x4_16b_f16 v[96:99], a[148:149], a[12:13], v[96:99]
	v_mfma_f32_4x4x4_16b_f16 v[100:103], a[148:149], a[20:21], v[100:103]
	v_mfma_f32_4x4x4_16b_f16 v[104:107], a[148:149], a[28:29], v[104:107]
	v_mfma_f32_4x4x4_16b_f16 v[108:111], a[148:149], a[36:37], v[108:111]
	v_mfma_f32_4x4x4_16b_f16 v[112:115], a[148:149], a[44:45], v[112:115]
	v_mfma_f32_4x4x4_16b_f16 v[116:119], a[148:149], a[52:53], v[116:119]
	v_mfma_f32_4x4x4_16b_f16 v[120:123], a[148:149], a[60:61], v[120:123]
	v_mfma_f32_4x4x4_16b_f16 v[92:95], a[150:151], a[6:7], v[92:95]
	v_mfma_f32_4x4x4_16b_f16 v[96:99], a[150:151], a[14:15], v[96:99]
	v_mfma_f32_4x4x4_16b_f16 v[100:103], a[150:151], a[22:23], v[100:103]
	v_mfma_f32_4x4x4_16b_f16 v[104:107], a[150:151], a[30:31], v[104:107]
	v_mfma_f32_4x4x4_16b_f16 v[108:111], a[150:151], a[38:39], v[108:111]
	v_mfma_f32_4x4x4_16b_f16 v[112:115], a[150:151], a[46:47], v[112:115]
	v_mfma_f32_4x4x4_16b_f16 v[116:119], a[150:151], a[54:55], v[116:119]
	v_mfma_f32_4x4x4_16b_f16 v[120:123], a[150:151], a[62:63], v[120:123]
	s_nop 4
	v_permlane32_swap_b32 v92, v108
	v_permlane32_swap_b32 v93, v109
	v_permlane32_swap_b32 v94, v110
	v_permlane32_swap_b32 v95, v111
	v_permlane32_swap_b32 v96, v112
	v_permlane32_swap_b32 v97, v113
	v_permlane32_swap_b32 v98, v114
	v_permlane32_swap_b32 v99, v115
	v_permlane32_swap_b32 v100, v116
	v_permlane32_swap_b32 v101, v117
	v_permlane32_swap_b32 v102, v118
	v_permlane32_swap_b32 v103, v119
	v_permlane32_swap_b32 v104, v120
	v_permlane32_swap_b32 v105, v121
	v_permlane32_swap_b32 v106, v122
	v_permlane32_swap_b32 v107, v123
	v_add_f32_e32 v92, v92, v108
	v_add_f32_e32 v93, v93, v109
	v_add_f32_e32 v94, v94, v110
	v_add_f32_e32 v95, v95, v111
	v_add_f32_e32 v96, v96, v112
	v_add_f32_e32 v97, v97, v113
	v_add_f32_e32 v98, v98, v114
	v_add_f32_e32 v99, v99, v115
	v_add_f32_e32 v100, v100, v116
	v_add_f32_e32 v101, v101, v117
	v_add_f32_e32 v102, v102, v118
	v_add_f32_e32 v103, v103, v119
	v_add_f32_e32 v104, v104, v120
	v_add_f32_e32 v105, v105, v121
	v_add_f32_e32 v106, v106, v122
	v_add_f32_e32 v107, v107, v123
	v_permlane16_swap_b32 v92, v100
	v_permlane16_swap_b32 v93, v101
	v_permlane16_swap_b32 v94, v102
	v_permlane16_swap_b32 v95, v103
	v_permlane16_swap_b32 v96, v104
	v_permlane16_swap_b32 v97, v105
	v_permlane16_swap_b32 v98, v106
	v_permlane16_swap_b32 v99, v107
	v_add_f32_e32 v76, v92, v100
	v_add_f32_e32 v77, v93, v101
	v_add_f32_e32 v78, v94, v102
	v_add_f32_e32 v79, v95, v103
	v_add_f32_e32 v80, v96, v104
	v_add_f32_e32 v81, v97, v105
	v_add_f32_e32 v82, v98, v106
	v_add_f32_e32 v83, v99, v107
	v_mfma_f32_4x4x4_16b_f16 v[92:95], a[144:145], a[64:65], 0
	v_mfma_f32_4x4x4_16b_f16 v[96:99], a[144:145], a[72:73], 0
	v_mfma_f32_4x4x4_16b_f16 v[100:103], a[144:145], a[80:81], 0
	v_mfma_f32_4x4x4_16b_f16 v[104:107], a[144:145], a[88:89], 0
	v_mfma_f32_4x4x4_16b_f16 v[108:111], a[144:145], a[96:97], 0
	v_mfma_f32_4x4x4_16b_f16 v[112:115], a[144:145], a[104:105], 0
	v_mfma_f32_4x4x4_16b_f16 v[116:119], a[144:145], a[112:113], 0
	v_mfma_f32_4x4x4_16b_f16 v[120:123], a[144:145], a[120:121], 0
	v_mfma_f32_4x4x4_16b_f16 v[92:95], a[146:147], a[66:67], v[92:95]
	v_mfma_f32_4x4x4_16b_f16 v[96:99], a[146:147], a[74:75], v[96:99]
	v_mfma_f32_4x4x4_16b_f16 v[100:103], a[146:147], a[82:83], v[100:103]
	v_mfma_f32_4x4x4_16b_f16 v[104:107], a[146:147], a[90:91], v[104:107]
	v_mfma_f32_4x4x4_16b_f16 v[108:111], a[146:147], a[98:99], v[108:111]
	v_mfma_f32_4x4x4_16b_f16 v[112:115], a[146:147], a[106:107], v[112:115]
	v_mfma_f32_4x4x4_16b_f16 v[116:119], a[146:147], a[114:115], v[116:119]
	v_mfma_f32_4x4x4_16b_f16 v[120:123], a[146:147], a[122:123], v[120:123]
	v_mfma_f32_4x4x4_16b_f16 v[92:95], a[148:149], a[68:69], v[92:95]
	v_mfma_f32_4x4x4_16b_f16 v[96:99], a[148:149], a[76:77], v[96:99]
	v_mfma_f32_4x4x4_16b_f16 v[100:103], a[148:149], a[84:85], v[100:103]
	v_mfma_f32_4x4x4_16b_f16 v[104:107], a[148:149], a[92:93], v[104:107]
	v_mfma_f32_4x4x4_16b_f16 v[108:111], a[148:149], a[100:101], v[108:111]
	v_mfma_f32_4x4x4_16b_f16 v[112:115], a[148:149], a[108:109], v[112:115]
	v_mfma_f32_4x4x4_16b_f16 v[116:119], a[148:149], a[116:117], v[116:119]
	v_mfma_f32_4x4x4_16b_f16 v[120:123], a[148:149], a[124:125], v[120:123]
	v_mfma_f32_4x4x4_16b_f16 v[92:95], a[150:151], a[70:71], v[92:95]
	v_mfma_f32_4x4x4_16b_f16 v[96:99], a[150:151], a[78:79], v[96:99]
	v_mfma_f32_4x4x4_16b_f16 v[100:103], a[150:151], a[86:87], v[100:103]
	v_mfma_f32_4x4x4_16b_f16 v[104:107], a[150:151], a[94:95], v[104:107]
	v_mfma_f32_4x4x4_16b_f16 v[108:111], a[150:151], a[102:103], v[108:111]
	v_mfma_f32_4x4x4_16b_f16 v[112:115], a[150:151], a[110:111], v[112:115]
	v_mfma_f32_4x4x4_16b_f16 v[116:119], a[150:151], a[118:119], v[116:119]
	v_mfma_f32_4x4x4_16b_f16 v[120:123], a[150:151], a[126:127], v[120:123]
	s_nop 4
	v_permlane32_swap_b32 v92, v108
	v_permlane32_swap_b32 v93, v109
	v_permlane32_swap_b32 v94, v110
	v_permlane32_swap_b32 v95, v111
	v_permlane32_swap_b32 v96, v112
	v_permlane32_swap_b32 v97, v113
	v_permlane32_swap_b32 v98, v114
	v_permlane32_swap_b32 v99, v115
	v_permlane32_swap_b32 v100, v116
	v_permlane32_swap_b32 v101, v117
	v_permlane32_swap_b32 v102, v118
	v_permlane32_swap_b32 v103, v119
	v_permlane32_swap_b32 v104, v120
	v_permlane32_swap_b32 v105, v121
	v_permlane32_swap_b32 v106, v122
	v_permlane32_swap_b32 v107, v123
	v_add_f32_e32 v92, v92, v108
	v_add_f32_e32 v93, v93, v109
	v_add_f32_e32 v94, v94, v110
	v_add_f32_e32 v95, v95, v111
	v_add_f32_e32 v96, v96, v112
	v_add_f32_e32 v97, v97, v113
	v_add_f32_e32 v98, v98, v114
	v_add_f32_e32 v99, v99, v115
	v_add_f32_e32 v100, v100, v116
	v_add_f32_e32 v101, v101, v117
	v_add_f32_e32 v102, v102, v118
	v_add_f32_e32 v103, v103, v119
	v_add_f32_e32 v104, v104, v120
	v_add_f32_e32 v105, v105, v121
	v_add_f32_e32 v106, v106, v122
	v_add_f32_e32 v107, v107, v123
	v_permlane16_swap_b32 v92, v100
	v_permlane16_swap_b32 v93, v101
	v_permlane16_swap_b32 v94, v102
	v_permlane16_swap_b32 v95, v103
	v_permlane16_swap_b32 v96, v104
	v_permlane16_swap_b32 v97, v105
	v_permlane16_swap_b32 v98, v106
	v_permlane16_swap_b32 v99, v107
	v_add_f32_e32 v84, v92, v100
	v_add_f32_e32 v85, v93, v101
	v_add_f32_e32 v86, v94, v102
	v_add_f32_e32 v87, v95, v103
	v_add_f32_e32 v88, v96, v104
	v_add_f32_e32 v89, v97, v105
	v_add_f32_e32 v90, v98, v106
	v_add_f32_e32 v91, v99, v107
	v_accvgpr_read_b32 v27, a176
	global_load_dwordx4 v[188:191], v27, s[96:97] offset:256
	v_accvgpr_read_b32 v28, a177
	global_load_dwordx4 v[192:195], v28, s[96:97] offset:256
	v_accvgpr_read_b32 v29, a178
	global_load_dwordx4 v[196:199], v29, s[96:97] offset:256
	v_accvgpr_read_b32 v30, a179
	global_load_dwordx4 v[200:203], v30, s[96:97] offset:256
	v_accvgpr_read_b32 v27, a180
	global_load_dwordx4 v[204:207], v27, s[96:97] offset:256
	v_accvgpr_read_b32 v28, a181
	global_load_dwordx4 v[208:211], v28, s[96:97] offset:256
	v_accvgpr_read_b32 v29, a182
	global_load_dwordx4 v[212:215], v29, s[96:97] offset:256
	v_accvgpr_read_b32 v30, a183
	global_load_dwordx4 v[216:219], v30, s[96:97] offset:256
	v_accvgpr_read_b32 v27, a184
	global_load_dwordx4 v[220:223], v27, s[96:97] offset:256
	v_accvgpr_read_b32 v28, a185
	global_load_dwordx4 v[224:227], v28, s[96:97] offset:256
	v_accvgpr_read_b32 v29, a186
	global_load_dwordx4 v[228:231], v29, s[96:97] offset:256
	v_accvgpr_read_b32 v30, a187
	global_load_dwordx4 v[232:235], v30, s[96:97] offset:256
	v_accvgpr_read_b32 v27, a188
	global_load_dwordx4 v[236:239], v27, s[96:97] offset:256
	v_accvgpr_read_b32 v28, a189
	global_load_dwordx4 v[240:243], v28, s[96:97] offset:256
	v_accvgpr_read_b32 v29, a190
	global_load_dwordx4 v[244:247], v29, s[96:97] offset:256
	v_accvgpr_read_b32 v30, a191
	global_load_dwordx4 v[248:251], v30, s[96:97] offset:256
	global_load_dwordx4 a[128:131], v75, s[12:13] offset:0
	global_load_dwordx4 a[132:135], v75, s[12:13] offset:128
	global_load_dwordx4 a[136:139], v75, s[12:13] offset:256
	global_load_dwordx4 a[140:143], v75, s[12:13] offset:384
	s_nop 3
	v_cmp_le_i32_e32 vcc, s7, v26
	v_add_u32_e32 v40, 16, v26
	v_add_u32_e32 v42, 0x80, v26
	v_add_u32_e32 v43, 0x90, v26
	v_cmp_le_i32_e64 s[2:3], s7, v40
	v_cmp_le_i32_e64 s[10:11], s7, v42
	v_cndmask_b32_e32 v76, v76, v72, vcc
	v_cndmask_b32_e32 v77, v77, v72, vcc
	v_cndmask_b32_e32 v78, v78, v72, vcc
	v_cndmask_b32_e32 v79, v79, v72, vcc
	v_cmp_le_i32_e32 vcc, s7, v43
	v_cndmask_b32_e64 v80, v80, v72, s[2:3]
	v_cndmask_b32_e64 v81, v81, v72, s[2:3]
	v_cndmask_b32_e64 v82, v82, v72, s[2:3]
	v_cndmask_b32_e64 v83, v83, v72, s[2:3]
	v_cndmask_b32_e64 v84, v84, v72, s[10:11]
	v_cndmask_b32_e64 v85, v85, v72, s[10:11]
	v_cndmask_b32_e64 v86, v86, v72, s[10:11]
	v_cndmask_b32_e64 v87, v87, v72, s[10:11]
	v_cndmask_b32_e32 v88, v88, v72, vcc
	v_cndmask_b32_e32 v89, v89, v72, vcc
	v_cndmask_b32_e32 v90, v90, v72, vcc
	v_cndmask_b32_e32 v91, v91, v72, vcc
	v_max_f32_e32 v44, v76, v80
	v_max_f32_e32 v45, v77, v81
	v_max_f32_e32 v46, v78, v82
	v_max_f32_e32 v47, v79, v83
	v_max3_f32 v44, v84, v88, v44
	v_max3_f32 v45, v85, v89, v45
	v_max3_f32 v46, v86, v90, v46
	v_max3_f32 v47, v87, v91, v47
	v_max_f32_dpp v44, v44, v44 quad_perm:[1,0,3,2] row_mask:0xf bank_mask:0xf bound_ctrl:1
	v_max_f32_dpp v45, v45, v45 quad_perm:[1,0,3,2] row_mask:0xf bank_mask:0xf bound_ctrl:1
	v_max_f32_dpp v46, v46, v46 quad_perm:[1,0,3,2] row_mask:0xf bank_mask:0xf bound_ctrl:1
	v_max_f32_dpp v47, v47, v47 quad_perm:[1,0,3,2] row_mask:0xf bank_mask:0xf bound_ctrl:1
	v_max_f32_dpp v44, v44, v44 quad_perm:[2,3,0,1] row_mask:0xf bank_mask:0xf bound_ctrl:1
	v_max_f32_dpp v45, v45, v45 quad_perm:[2,3,0,1] row_mask:0xf bank_mask:0xf bound_ctrl:1
	v_max_f32_dpp v46, v46, v46 quad_perm:[2,3,0,1] row_mask:0xf bank_mask:0xf bound_ctrl:1
	v_max_f32_dpp v47, v47, v47 quad_perm:[2,3,0,1] row_mask:0xf bank_mask:0xf bound_ctrl:1
	v_max_f32_dpp v44, v44, v44 row_half_mirror row_mask:0xf bank_mask:0xf bound_ctrl:1
	v_max_f32_dpp v45, v45, v45 row_half_mirror row_mask:0xf bank_mask:0xf bound_ctrl:1
	v_max_f32_dpp v46, v46, v46 row_half_mirror row_mask:0xf bank_mask:0xf bound_ctrl:1
	v_max_f32_dpp v47, v47, v47 row_half_mirror row_mask:0xf bank_mask:0xf bound_ctrl:1
	v_max_f32_dpp v44, v44, v44 row_mirror row_mask:0xf bank_mask:0xf bound_ctrl:1
	v_max_f32_dpp v45, v45, v45 row_mirror row_mask:0xf bank_mask:0xf bound_ctrl:1
	v_max_f32_dpp v46, v46, v46 row_mirror row_mask:0xf bank_mask:0xf bound_ctrl:1
	v_max_f32_dpp v47, v47, v47 row_mirror row_mask:0xf bank_mask:0xf bound_ctrl:1
	s_nop 1
	v_readlane_b32 s2, v44, 0
	v_readlane_b32 s3, v44, 16
	v_readlane_b32 s10, v44, 32
	v_readlane_b32 s11, v44, 48
	v_mov_b32_e32 v48, s3
	v_max_f32_e32 v48, s2, v48
	v_mov_b32_e32 v40, s11
	v_max_f32_e32 v40, s10, v40
	v_max_f32_e32 v48, v48, v40
	v_readlane_b32 s2, v45, 0
	v_readlane_b32 s3, v45, 16
	v_readlane_b32 s10, v45, 32
	v_readlane_b32 s11, v45, 48
	v_mov_b32_e32 v49, s3
	v_max_f32_e32 v49, s2, v49
	v_mov_b32_e32 v40, s11
	v_max_f32_e32 v40, s10, v40
	v_max_f32_e32 v49, v49, v40
	v_readlane_b32 s2, v46, 0
	v_readlane_b32 s3, v46, 16
	v_readlane_b32 s10, v46, 32
	v_readlane_b32 s11, v46, 48
	v_mov_b32_e32 v50, s3
	v_max_f32_e32 v50, s2, v50
	v_mov_b32_e32 v40, s11
	v_max_f32_e32 v40, s10, v40
	v_max_f32_e32 v50, v50, v40
	v_readlane_b32 s2, v47, 0
	v_readlane_b32 s3, v47, 16
	v_readlane_b32 s10, v47, 32
	v_readlane_b32 s11, v47, 48
	v_mov_b32_e32 v51, s3
	v_max_f32_e32 v51, s2, v51
	v_mov_b32_e32 v40, s11
	v_max_f32_e32 v40, s10, v40
	v_max_f32_e32 v51, v51, v40
	v_sub_f32_e32 v76, v76, v48
	v_sub_f32_e32 v77, v77, v49
	v_sub_f32_e32 v78, v78, v50
	v_sub_f32_e32 v79, v79, v51
	v_sub_f32_e32 v80, v80, v48
	v_sub_f32_e32 v81, v81, v49
	v_sub_f32_e32 v82, v82, v50
	v_sub_f32_e32 v83, v83, v51
	v_sub_f32_e32 v84, v84, v48
	v_sub_f32_e32 v85, v85, v49
	v_sub_f32_e32 v86, v86, v50
	v_sub_f32_e32 v87, v87, v51
	v_sub_f32_e32 v88, v88, v48
	v_sub_f32_e32 v89, v89, v49
	v_sub_f32_e32 v90, v90, v50
	v_sub_f32_e32 v91, v91, v51
	v_mul_f32_e32 v76, 0x3fb8aa3b, v76
	v_mul_f32_e32 v77, 0x3fb8aa3b, v77
	v_mul_f32_e32 v78, 0x3fb8aa3b, v78
	v_mul_f32_e32 v79, 0x3fb8aa3b, v79
	v_mul_f32_e32 v80, 0x3fb8aa3b, v80
	v_mul_f32_e32 v81, 0x3fb8aa3b, v81
	v_mul_f32_e32 v82, 0x3fb8aa3b, v82
	v_mul_f32_e32 v83, 0x3fb8aa3b, v83
	v_mul_f32_e32 v84, 0x3fb8aa3b, v84
	v_mul_f32_e32 v85, 0x3fb8aa3b, v85
	v_mul_f32_e32 v86, 0x3fb8aa3b, v86
	v_mul_f32_e32 v87, 0x3fb8aa3b, v87
	v_mul_f32_e32 v88, 0x3fb8aa3b, v88
	v_mul_f32_e32 v89, 0x3fb8aa3b, v89
	v_mul_f32_e32 v90, 0x3fb8aa3b, v90
	v_mul_f32_e32 v91, 0x3fb8aa3b, v91
	v_exp_f32_e32 v76, v76
	v_exp_f32_e32 v77, v77
	v_exp_f32_e32 v78, v78
	v_exp_f32_e32 v79, v79
	v_exp_f32_e32 v80, v80
	v_exp_f32_e32 v81, v81
	v_exp_f32_e32 v82, v82
	v_exp_f32_e32 v83, v83
	v_exp_f32_e32 v84, v84
	v_exp_f32_e32 v85, v85
	v_exp_f32_e32 v86, v86
	v_exp_f32_e32 v87, v87
	v_exp_f32_e32 v88, v88
	v_exp_f32_e32 v89, v89
	v_exp_f32_e32 v90, v90
	v_exp_f32_e32 v91, v91
	s_nop 0
	v_add_f32_e32 v52, 0, v76
	v_add_f32_e32 v53, 0, v77
	v_add_f32_e32 v54, 0, v78
	v_add_f32_e32 v55, 0, v79
	v_add_f32_e32 v52, v52, v80
	v_add_f32_e32 v53, v53, v81
	v_add_f32_e32 v54, v54, v82
	v_add_f32_e32 v55, v55, v83
	v_add_f32_e32 v52, v52, v84
	v_add_f32_e32 v53, v53, v85
	v_add_f32_e32 v54, v54, v86
	v_add_f32_e32 v55, v55, v87
	v_add_f32_e32 v52, v52, v88
	v_add_f32_e32 v53, v53, v89
	v_add_f32_e32 v54, v54, v90
	v_add_f32_e32 v55, v55, v91
	v_add_f32_dpp v52, v52, v52 quad_perm:[1,0,3,2] row_mask:0xf bank_mask:0xf bound_ctrl:1
	v_add_f32_dpp v53, v53, v53 quad_perm:[1,0,3,2] row_mask:0xf bank_mask:0xf bound_ctrl:1
	v_add_f32_dpp v54, v54, v54 quad_perm:[1,0,3,2] row_mask:0xf bank_mask:0xf bound_ctrl:1
	v_add_f32_dpp v55, v55, v55 quad_perm:[1,0,3,2] row_mask:0xf bank_mask:0xf bound_ctrl:1
	v_add_f32_dpp v52, v52, v52 quad_perm:[2,3,0,1] row_mask:0xf bank_mask:0xf bound_ctrl:1
	v_add_f32_dpp v53, v53, v53 quad_perm:[2,3,0,1] row_mask:0xf bank_mask:0xf bound_ctrl:1
	v_add_f32_dpp v54, v54, v54 quad_perm:[2,3,0,1] row_mask:0xf bank_mask:0xf bound_ctrl:1
	v_add_f32_dpp v55, v55, v55 quad_perm:[2,3,0,1] row_mask:0xf bank_mask:0xf bound_ctrl:1
	v_add_f32_dpp v52, v52, v52 row_half_mirror row_mask:0xf bank_mask:0xf bound_ctrl:1
	v_add_f32_dpp v53, v53, v53 row_half_mirror row_mask:0xf bank_mask:0xf bound_ctrl:1
	v_add_f32_dpp v54, v54, v54 row_half_mirror row_mask:0xf bank_mask:0xf bound_ctrl:1
	v_add_f32_dpp v55, v55, v55 row_half_mirror row_mask:0xf bank_mask:0xf bound_ctrl:1
	v_add_f32_dpp v52, v52, v52 row_mirror row_mask:0xf bank_mask:0xf bound_ctrl:1
	v_add_f32_dpp v53, v53, v53 row_mirror row_mask:0xf bank_mask:0xf bound_ctrl:1
	v_add_f32_dpp v54, v54, v54 row_mirror row_mask:0xf bank_mask:0xf bound_ctrl:1
	v_add_f32_dpp v55, v55, v55 row_mirror row_mask:0xf bank_mask:0xf bound_ctrl:1
	s_nop 1
	v_readlane_b32 s2, v52, 0
	v_readlane_b32 s3, v52, 16
	v_readlane_b32 s10, v52, 32
	v_readlane_b32 s11, v52, 48
	v_mov_b32_e32 v56, s3
	v_add_f32_e32 v56, s2, v56
	v_mov_b32_e32 v40, s11
	v_add_f32_e32 v40, s10, v40
	v_add_f32_e32 v56, v56, v40
	v_readlane_b32 s2, v53, 0
	v_readlane_b32 s3, v53, 16
	v_readlane_b32 s10, v53, 32
	v_readlane_b32 s11, v53, 48
	v_mov_b32_e32 v57, s3
	v_add_f32_e32 v57, s2, v57
	v_mov_b32_e32 v40, s11
	v_add_f32_e32 v40, s10, v40
	v_add_f32_e32 v57, v57, v40
	v_readlane_b32 s2, v54, 0
	v_readlane_b32 s3, v54, 16
	v_readlane_b32 s10, v54, 32
	v_readlane_b32 s11, v54, 48
	v_mov_b32_e32 v58, s3
	v_add_f32_e32 v58, s2, v58
	v_mov_b32_e32 v40, s11
	v_add_f32_e32 v40, s10, v40
	v_add_f32_e32 v58, v58, v40
	v_readlane_b32 s2, v55, 0
	v_readlane_b32 s3, v55, 16
	v_readlane_b32 s10, v55, 32
	v_readlane_b32 s11, v55, 48
	v_mov_b32_e32 v59, s3
	v_add_f32_e32 v59, s2, v59
	v_mov_b32_e32 v40, s11
	v_add_f32_e32 v40, s10, v40
	v_add_f32_e32 v59, v59, v40
	v_div_scale_f32 v60, s[2:3], v56, v56, 1.0
	v_rcp_f32_e32 v61, v60
	s_nop 0
	v_fma_f32 v62, -v60, v61, 1.0
	v_fmac_f32_e32 v61, v62, v61
	v_div_scale_f32 v62, vcc, 1.0, v56, 1.0
	v_mul_f32_e32 v63, v62, v61
	v_fma_f32 v64, -v60, v63, v62
	v_fmac_f32_e32 v63, v64, v61
	v_fma_f32 v60, -v60, v63, v62
	s_nop 0
	v_div_fmas_f32 v60, v60, v61, v63
	v_div_fixup_f32 v56, v60, v56, 1.0
	v_div_scale_f32 v60, s[2:3], v57, v57, 1.0
	v_rcp_f32_e32 v61, v60
	s_nop 0
	v_fma_f32 v62, -v60, v61, 1.0
	v_fmac_f32_e32 v61, v62, v61
	v_div_scale_f32 v62, vcc, 1.0, v57, 1.0
	v_mul_f32_e32 v63, v62, v61
	v_fma_f32 v64, -v60, v63, v62
	v_fmac_f32_e32 v63, v64, v61
	v_fma_f32 v60, -v60, v63, v62
	s_nop 0
	v_div_fmas_f32 v60, v60, v61, v63
	v_div_fixup_f32 v57, v60, v57, 1.0
	v_div_scale_f32 v60, s[2:3], v58, v58, 1.0
	v_rcp_f32_e32 v61, v60
	s_nop 0
	v_fma_f32 v62, -v60, v61, 1.0
	v_fmac_f32_e32 v61, v62, v61
	v_div_scale_f32 v62, vcc, 1.0, v58, 1.0
	v_mul_f32_e32 v63, v62, v61
	v_fma_f32 v64, -v60, v63, v62
	v_fmac_f32_e32 v63, v64, v61
	v_fma_f32 v60, -v60, v63, v62
	s_nop 0
	v_div_fmas_f32 v60, v60, v61, v63
	v_div_fixup_f32 v58, v60, v58, 1.0
	v_div_scale_f32 v60, s[2:3], v59, v59, 1.0
	v_rcp_f32_e32 v61, v60
	s_nop 0
	v_fma_f32 v62, -v60, v61, 1.0
	v_fmac_f32_e32 v61, v62, v61
	v_div_scale_f32 v62, vcc, 1.0, v59, 1.0
	v_mul_f32_e32 v63, v62, v61
	v_fma_f32 v64, -v60, v63, v62
	v_fmac_f32_e32 v63, v64, v61
	v_fma_f32 v60, -v60, v63, v62
	s_nop 0
	v_div_fmas_f32 v60, v60, v61, v63
	v_div_fixup_f32 v59, v60, v59, 1.0
	v_mul_f32_e32 v76, v76, v56
	v_mul_f32_e32 v77, v77, v57
	v_mul_f32_e32 v78, v78, v58
	v_mul_f32_e32 v79, v79, v59
	v_mul_f32_e32 v80, v80, v56
	v_mul_f32_e32 v81, v81, v57
	v_mul_f32_e32 v82, v82, v58
	v_mul_f32_e32 v83, v83, v59
	v_mul_f32_e32 v84, v84, v56
	v_mul_f32_e32 v85, v85, v57
	v_mul_f32_e32 v86, v86, v58
	v_mul_f32_e32 v87, v87, v59
	v_mul_f32_e32 v88, v88, v56
	v_mul_f32_e32 v89, v89, v57
	v_mul_f32_e32 v90, v90, v58
	v_mul_f32_e32 v91, v91, v59
	ds_write_b128 v73, v[76:79] offset:0
	ds_write_b128 v73, v[80:83] offset:256
	ds_write_b128 v73, v[84:87] offset:2048
	ds_write_b128 v73, v[88:91] offset:2304
	s_waitcnt vmcnt(20)
	ds_read_b128 v[44:47], v74 offset:0
	ds_read_b128 v[48:51], v74 offset:128
	ds_read_b128 v[52:55], v74 offset:256
	s_waitcnt lgkmcnt(2)
	v_cvt_f32_f16_e32 v56, v124
	v_cvt_f32_f16_sdwa v57, v124 dst_sel:DWORD dst_unused:UNUSED_PAD src0_sel:WORD_1
	v_cvt_f32_f16_e32 v58, v125
	v_cvt_f32_f16_sdwa v59, v125 dst_sel:DWORD dst_unused:UNUSED_PAD src0_sel:WORD_1
	v_cvt_f32_f16_e32 v60, v126
	v_cvt_f32_f16_sdwa v61, v126 dst_sel:DWORD dst_unused:UNUSED_PAD src0_sel:WORD_1
	v_cvt_f32_f16_e32 v62, v127
	v_cvt_f32_f16_sdwa v63, v127 dst_sel:DWORD dst_unused:UNUSED_PAD src0_sel:WORD_1
	v_pk_mul_f32 v[92:93], v[44:45], v[56:57] op_sel_hi:[0,1]
	v_pk_mul_f32 v[94:95], v[44:45], v[58:59] op_sel_hi:[0,1]
	v_pk_mul_f32 v[96:97], v[44:45], v[60:61] op_sel_hi:[0,1]
	v_pk_mul_f32 v[98:99], v[44:45], v[62:63] op_sel_hi:[0,1]
	v_pk_mul_f32 v[100:101], v[44:45], v[56:57] op_sel:[1,0] op_sel_hi:[1,1]
	v_pk_mul_f32 v[102:103], v[44:45], v[58:59] op_sel:[1,0] op_sel_hi:[1,1]
	v_pk_mul_f32 v[104:105], v[44:45], v[60:61] op_sel:[1,0] op_sel_hi:[1,1]
	v_pk_mul_f32 v[106:107], v[44:45], v[62:63] op_sel:[1,0] op_sel_hi:[1,1]
	v_pk_mul_f32 v[108:109], v[46:47], v[56:57] op_sel_hi:[0,1]
	v_pk_mul_f32 v[110:111], v[46:47], v[58:59] op_sel_hi:[0,1]
	v_pk_mul_f32 v[112:113], v[46:47], v[60:61] op_sel_hi:[0,1]
	v_pk_mul_f32 v[114:115], v[46:47], v[62:63] op_sel_hi:[0,1]
	v_pk_mul_f32 v[116:117], v[46:47], v[56:57] op_sel:[1,0] op_sel_hi:[1,1]
	v_pk_mul_f32 v[118:119], v[46:47], v[58:59] op_sel:[1,0] op_sel_hi:[1,1]
	v_pk_mul_f32 v[120:121], v[46:47], v[60:61] op_sel:[1,0] op_sel_hi:[1,1]
	v_pk_mul_f32 v[122:123], v[46:47], v[62:63] op_sel:[1,0] op_sel_hi:[1,1]
	ds_read_b128 v[44:47], v74 offset:384
	s_waitcnt lgkmcnt(2)
	v_cvt_f32_f16_e32 v56, v128
	v_cvt_f32_f16_sdwa v57, v128 dst_sel:DWORD dst_unused:UNUSED_PAD src0_sel:WORD_1
	v_cvt_f32_f16_e32 v58, v129
	v_cvt_f32_f16_sdwa v59, v129 dst_sel:DWORD dst_unused:UNUSED_PAD src0_sel:WORD_1
	v_cvt_f32_f16_e32 v60, v130
	v_cvt_f32_f16_sdwa v61, v130 dst_sel:DWORD dst_unused:UNUSED_PAD src0_sel:WORD_1
	v_cvt_f32_f16_e32 v62, v131
	v_cvt_f32_f16_sdwa v63, v131 dst_sel:DWORD dst_unused:UNUSED_PAD src0_sel:WORD_1
	v_pk_fma_f32 v[92:93], v[48:49], v[56:57], v[92:93] op_sel_hi:[0,1,1]
	v_pk_fma_f32 v[94:95], v[48:49], v[58:59], v[94:95] op_sel_hi:[0,1,1]
	v_pk_fma_f32 v[96:97], v[48:49], v[60:61], v[96:97] op_sel_hi:[0,1,1]
	v_pk_fma_f32 v[98:99], v[48:49], v[62:63], v[98:99] op_sel_hi:[0,1,1]
	v_pk_fma_f32 v[100:101], v[48:49], v[56:57], v[100:101] op_sel:[1,0,0] op_sel_hi:[1,1,1]
	v_pk_fma_f32 v[102:103], v[48:49], v[58:59], v[102:103] op_sel:[1,0,0] op_sel_hi:[1,1,1]
	v_pk_fma_f32 v[104:105], v[48:49], v[60:61], v[104:105] op_sel:[1,0,0] op_sel_hi:[1,1,1]
	v_pk_fma_f32 v[106:107], v[48:49], v[62:63], v[106:107] op_sel:[1,0,0] op_sel_hi:[1,1,1]
	v_pk_fma_f32 v[108:109], v[50:51], v[56:57], v[108:109] op_sel_hi:[0,1,1]
	v_pk_fma_f32 v[110:111], v[50:51], v[58:59], v[110:111] op_sel_hi:[0,1,1]
	v_pk_fma_f32 v[112:113], v[50:51], v[60:61], v[112:113] op_sel_hi:[0,1,1]
	v_pk_fma_f32 v[114:115], v[50:51], v[62:63], v[114:115] op_sel_hi:[0,1,1]
	v_pk_fma_f32 v[116:117], v[50:51], v[56:57], v[116:117] op_sel:[1,0,0] op_sel_hi:[1,1,1]
	v_pk_fma_f32 v[118:119], v[50:51], v[58:59], v[118:119] op_sel:[1,0,0] op_sel_hi:[1,1,1]
	v_pk_fma_f32 v[120:121], v[50:51], v[60:61], v[120:121] op_sel:[1,0,0] op_sel_hi:[1,1,1]
	v_pk_fma_f32 v[122:123], v[50:51], v[62:63], v[122:123] op_sel:[1,0,0] op_sel_hi:[1,1,1]
	ds_read_b128 v[48:51], v74 offset:512
	s_waitcnt lgkmcnt(2)
	v_cvt_f32_f16_e32 v56, v132
	v_cvt_f32_f16_sdwa v57, v132 dst_sel:DWORD dst_unused:UNUSED_PAD src0_sel:WORD_1
	v_cvt_f32_f16_e32 v58, v133
	v_cvt_f32_f16_sdwa v59, v133 dst_sel:DWORD dst_unused:UNUSED_PAD src0_sel:WORD_1
	v_cvt_f32_f16_e32 v60, v134
	v_cvt_f32_f16_sdwa v61, v134 dst_sel:DWORD dst_unused:UNUSED_PAD src0_sel:WORD_1
	v_cvt_f32_f16_e32 v62, v135
	v_cvt_f32_f16_sdwa v63, v135 dst_sel:DWORD dst_unused:UNUSED_PAD src0_sel:WORD_1
	v_pk_fma_f32 v[92:93], v[52:53], v[56:57], v[92:93] op_sel_hi:[0,1,1]
	v_pk_fma_f32 v[94:95], v[52:53], v[58:59], v[94:95] op_sel_hi:[0,1,1]
	v_pk_fma_f32 v[96:97], v[52:53], v[60:61], v[96:97] op_sel_hi:[0,1,1]
	v_pk_fma_f32 v[98:99], v[52:53], v[62:63], v[98:99] op_sel_hi:[0,1,1]
	v_pk_fma_f32 v[100:101], v[52:53], v[56:57], v[100:101] op_sel:[1,0,0] op_sel_hi:[1,1,1]
	v_pk_fma_f32 v[102:103], v[52:53], v[58:59], v[102:103] op_sel:[1,0,0] op_sel_hi:[1,1,1]
	v_pk_fma_f32 v[104:105], v[52:53], v[60:61], v[104:105] op_sel:[1,0,0] op_sel_hi:[1,1,1]
	v_pk_fma_f32 v[106:107], v[52:53], v[62:63], v[106:107] op_sel:[1,0,0] op_sel_hi:[1,1,1]
	v_pk_fma_f32 v[108:109], v[54:55], v[56:57], v[108:109] op_sel_hi:[0,1,1]
	v_pk_fma_f32 v[110:111], v[54:55], v[58:59], v[110:111] op_sel_hi:[0,1,1]
	v_pk_fma_f32 v[112:113], v[54:55], v[60:61], v[112:113] op_sel_hi:[0,1,1]
	v_pk_fma_f32 v[114:115], v[54:55], v[62:63], v[114:115] op_sel_hi:[0,1,1]
	v_pk_fma_f32 v[116:117], v[54:55], v[56:57], v[116:117] op_sel:[1,0,0] op_sel_hi:[1,1,1]
	v_pk_fma_f32 v[118:119], v[54:55], v[58:59], v[118:119] op_sel:[1,0,0] op_sel_hi:[1,1,1]
	v_pk_fma_f32 v[120:121], v[54:55], v[60:61], v[120:121] op_sel:[1,0,0] op_sel_hi:[1,1,1]
	v_pk_fma_f32 v[122:123], v[54:55], v[62:63], v[122:123] op_sel:[1,0,0] op_sel_hi:[1,1,1]
	ds_read_b128 v[52:55], v74 offset:640
	s_waitcnt lgkmcnt(2)
	v_cvt_f32_f16_e32 v56, v136
	v_cvt_f32_f16_sdwa v57, v136 dst_sel:DWORD dst_unused:UNUSED_PAD src0_sel:WORD_1
	v_cvt_f32_f16_e32 v58, v137
	v_cvt_f32_f16_sdwa v59, v137 dst_sel:DWORD dst_unused:UNUSED_PAD src0_sel:WORD_1
	v_cvt_f32_f16_e32 v60, v138
	v_cvt_f32_f16_sdwa v61, v138 dst_sel:DWORD dst_unused:UNUSED_PAD src0_sel:WORD_1
	v_cvt_f32_f16_e32 v62, v139
	v_cvt_f32_f16_sdwa v63, v139 dst_sel:DWORD dst_unused:UNUSED_PAD src0_sel:WORD_1
	v_pk_fma_f32 v[92:93], v[44:45], v[56:57], v[92:93] op_sel_hi:[0,1,1]
	v_pk_fma_f32 v[94:95], v[44:45], v[58:59], v[94:95] op_sel_hi:[0,1,1]
	v_pk_fma_f32 v[96:97], v[44:45], v[60:61], v[96:97] op_sel_hi:[0,1,1]
	v_pk_fma_f32 v[98:99], v[44:45], v[62:63], v[98:99] op_sel_hi:[0,1,1]
	v_pk_fma_f32 v[100:101], v[44:45], v[56:57], v[100:101] op_sel:[1,0,0] op_sel_hi:[1,1,1]
	v_pk_fma_f32 v[102:103], v[44:45], v[58:59], v[102:103] op_sel:[1,0,0] op_sel_hi:[1,1,1]
	v_pk_fma_f32 v[104:105], v[44:45], v[60:61], v[104:105] op_sel:[1,0,0] op_sel_hi:[1,1,1]
	v_pk_fma_f32 v[106:107], v[44:45], v[62:63], v[106:107] op_sel:[1,0,0] op_sel_hi:[1,1,1]
	v_pk_fma_f32 v[108:109], v[46:47], v[56:57], v[108:109] op_sel_hi:[0,1,1]
	v_pk_fma_f32 v[110:111], v[46:47], v[58:59], v[110:111] op_sel_hi:[0,1,1]
	v_pk_fma_f32 v[112:113], v[46:47], v[60:61], v[112:113] op_sel_hi:[0,1,1]
	v_pk_fma_f32 v[114:115], v[46:47], v[62:63], v[114:115] op_sel_hi:[0,1,1]
	v_pk_fma_f32 v[116:117], v[46:47], v[56:57], v[116:117] op_sel:[1,0,0] op_sel_hi:[1,1,1]
	v_pk_fma_f32 v[118:119], v[46:47], v[58:59], v[118:119] op_sel:[1,0,0] op_sel_hi:[1,1,1]
	v_pk_fma_f32 v[120:121], v[46:47], v[60:61], v[120:121] op_sel:[1,0,0] op_sel_hi:[1,1,1]
	v_pk_fma_f32 v[122:123], v[46:47], v[62:63], v[122:123] op_sel:[1,0,0] op_sel_hi:[1,1,1]
	ds_read_b128 v[44:47], v74 offset:768
	s_waitcnt lgkmcnt(2)
	v_cvt_f32_f16_e32 v56, v140
	v_cvt_f32_f16_sdwa v57, v140 dst_sel:DWORD dst_unused:UNUSED_PAD src0_sel:WORD_1
	v_cvt_f32_f16_e32 v58, v141
	v_cvt_f32_f16_sdwa v59, v141 dst_sel:DWORD dst_unused:UNUSED_PAD src0_sel:WORD_1
	v_cvt_f32_f16_e32 v60, v142
	v_cvt_f32_f16_sdwa v61, v142 dst_sel:DWORD dst_unused:UNUSED_PAD src0_sel:WORD_1
	v_cvt_f32_f16_e32 v62, v143
	v_cvt_f32_f16_sdwa v63, v143 dst_sel:DWORD dst_unused:UNUSED_PAD src0_sel:WORD_1
	v_pk_fma_f32 v[92:93], v[48:49], v[56:57], v[92:93] op_sel_hi:[0,1,1]
	v_pk_fma_f32 v[94:95], v[48:49], v[58:59], v[94:95] op_sel_hi:[0,1,1]
	v_pk_fma_f32 v[96:97], v[48:49], v[60:61], v[96:97] op_sel_hi:[0,1,1]
	v_pk_fma_f32 v[98:99], v[48:49], v[62:63], v[98:99] op_sel_hi:[0,1,1]
	v_pk_fma_f32 v[100:101], v[48:49], v[56:57], v[100:101] op_sel:[1,0,0] op_sel_hi:[1,1,1]
	v_pk_fma_f32 v[102:103], v[48:49], v[58:59], v[102:103] op_sel:[1,0,0] op_sel_hi:[1,1,1]
	v_pk_fma_f32 v[104:105], v[48:49], v[60:61], v[104:105] op_sel:[1,0,0] op_sel_hi:[1,1,1]
	v_pk_fma_f32 v[106:107], v[48:49], v[62:63], v[106:107] op_sel:[1,0,0] op_sel_hi:[1,1,1]
	v_pk_fma_f32 v[108:109], v[50:51], v[56:57], v[108:109] op_sel_hi:[0,1,1]
	v_pk_fma_f32 v[110:111], v[50:51], v[58:59], v[110:111] op_sel_hi:[0,1,1]
	v_pk_fma_f32 v[112:113], v[50:51], v[60:61], v[112:113] op_sel_hi:[0,1,1]
	v_pk_fma_f32 v[114:115], v[50:51], v[62:63], v[114:115] op_sel_hi:[0,1,1]
	v_pk_fma_f32 v[116:117], v[50:51], v[56:57], v[116:117] op_sel:[1,0,0] op_sel_hi:[1,1,1]
	v_pk_fma_f32 v[118:119], v[50:51], v[58:59], v[118:119] op_sel:[1,0,0] op_sel_hi:[1,1,1]
	v_pk_fma_f32 v[120:121], v[50:51], v[60:61], v[120:121] op_sel:[1,0,0] op_sel_hi:[1,1,1]
	v_pk_fma_f32 v[122:123], v[50:51], v[62:63], v[122:123] op_sel:[1,0,0] op_sel_hi:[1,1,1]
	ds_read_b128 v[48:51], v74 offset:896
	s_waitcnt lgkmcnt(2)
	v_cvt_f32_f16_e32 v56, v144
	v_cvt_f32_f16_sdwa v57, v144 dst_sel:DWORD dst_unused:UNUSED_PAD src0_sel:WORD_1
	v_cvt_f32_f16_e32 v58, v145
	v_cvt_f32_f16_sdwa v59, v145 dst_sel:DWORD dst_unused:UNUSED_PAD src0_sel:WORD_1
	v_cvt_f32_f16_e32 v60, v146
	v_cvt_f32_f16_sdwa v61, v146 dst_sel:DWORD dst_unused:UNUSED_PAD src0_sel:WORD_1
	v_cvt_f32_f16_e32 v62, v147
	v_cvt_f32_f16_sdwa v63, v147 dst_sel:DWORD dst_unused:UNUSED_PAD src0_sel:WORD_1
	v_pk_fma_f32 v[92:93], v[52:53], v[56:57], v[92:93] op_sel_hi:[0,1,1]
	v_pk_fma_f32 v[94:95], v[52:53], v[58:59], v[94:95] op_sel_hi:[0,1,1]
	v_pk_fma_f32 v[96:97], v[52:53], v[60:61], v[96:97] op_sel_hi:[0,1,1]
	v_pk_fma_f32 v[98:99], v[52:53], v[62:63], v[98:99] op_sel_hi:[0,1,1]
	v_pk_fma_f32 v[100:101], v[52:53], v[56:57], v[100:101] op_sel:[1,0,0] op_sel_hi:[1,1,1]
	v_pk_fma_f32 v[102:103], v[52:53], v[58:59], v[102:103] op_sel:[1,0,0] op_sel_hi:[1,1,1]
	v_pk_fma_f32 v[104:105], v[52:53], v[60:61], v[104:105] op_sel:[1,0,0] op_sel_hi:[1,1,1]
	v_pk_fma_f32 v[106:107], v[52:53], v[62:63], v[106:107] op_sel:[1,0,0] op_sel_hi:[1,1,1]
	v_pk_fma_f32 v[108:109], v[54:55], v[56:57], v[108:109] op_sel_hi:[0,1,1]
	v_pk_fma_f32 v[110:111], v[54:55], v[58:59], v[110:111] op_sel_hi:[0,1,1]
	v_pk_fma_f32 v[112:113], v[54:55], v[60:61], v[112:113] op_sel_hi:[0,1,1]
	v_pk_fma_f32 v[114:115], v[54:55], v[62:63], v[114:115] op_sel_hi:[0,1,1]
	v_pk_fma_f32 v[116:117], v[54:55], v[56:57], v[116:117] op_sel:[1,0,0] op_sel_hi:[1,1,1]
	v_pk_fma_f32 v[118:119], v[54:55], v[58:59], v[118:119] op_sel:[1,0,0] op_sel_hi:[1,1,1]
	v_pk_fma_f32 v[120:121], v[54:55], v[60:61], v[120:121] op_sel:[1,0,0] op_sel_hi:[1,1,1]
	v_pk_fma_f32 v[122:123], v[54:55], v[62:63], v[122:123] op_sel:[1,0,0] op_sel_hi:[1,1,1]
	ds_read_b128 v[52:55], v74 offset:1024
	s_waitcnt lgkmcnt(2)
	v_cvt_f32_f16_e32 v56, v148
	v_cvt_f32_f16_sdwa v57, v148 dst_sel:DWORD dst_unused:UNUSED_PAD src0_sel:WORD_1
	v_cvt_f32_f16_e32 v58, v149
	v_cvt_f32_f16_sdwa v59, v149 dst_sel:DWORD dst_unused:UNUSED_PAD src0_sel:WORD_1
	v_cvt_f32_f16_e32 v60, v150
	v_cvt_f32_f16_sdwa v61, v150 dst_sel:DWORD dst_unused:UNUSED_PAD src0_sel:WORD_1
	v_cvt_f32_f16_e32 v62, v151
	v_cvt_f32_f16_sdwa v63, v151 dst_sel:DWORD dst_unused:UNUSED_PAD src0_sel:WORD_1
	v_pk_fma_f32 v[92:93], v[44:45], v[56:57], v[92:93] op_sel_hi:[0,1,1]
	v_pk_fma_f32 v[94:95], v[44:45], v[58:59], v[94:95] op_sel_hi:[0,1,1]
	v_pk_fma_f32 v[96:97], v[44:45], v[60:61], v[96:97] op_sel_hi:[0,1,1]
	v_pk_fma_f32 v[98:99], v[44:45], v[62:63], v[98:99] op_sel_hi:[0,1,1]
	v_pk_fma_f32 v[100:101], v[44:45], v[56:57], v[100:101] op_sel:[1,0,0] op_sel_hi:[1,1,1]
	v_pk_fma_f32 v[102:103], v[44:45], v[58:59], v[102:103] op_sel:[1,0,0] op_sel_hi:[1,1,1]
	v_pk_fma_f32 v[104:105], v[44:45], v[60:61], v[104:105] op_sel:[1,0,0] op_sel_hi:[1,1,1]
	v_pk_fma_f32 v[106:107], v[44:45], v[62:63], v[106:107] op_sel:[1,0,0] op_sel_hi:[1,1,1]
	v_pk_fma_f32 v[108:109], v[46:47], v[56:57], v[108:109] op_sel_hi:[0,1,1]
	v_pk_fma_f32 v[110:111], v[46:47], v[58:59], v[110:111] op_sel_hi:[0,1,1]
	v_pk_fma_f32 v[112:113], v[46:47], v[60:61], v[112:113] op_sel_hi:[0,1,1]
	v_pk_fma_f32 v[114:115], v[46:47], v[62:63], v[114:115] op_sel_hi:[0,1,1]
	v_pk_fma_f32 v[116:117], v[46:47], v[56:57], v[116:117] op_sel:[1,0,0] op_sel_hi:[1,1,1]
	v_pk_fma_f32 v[118:119], v[46:47], v[58:59], v[118:119] op_sel:[1,0,0] op_sel_hi:[1,1,1]
	v_pk_fma_f32 v[120:121], v[46:47], v[60:61], v[120:121] op_sel:[1,0,0] op_sel_hi:[1,1,1]
	v_pk_fma_f32 v[122:123], v[46:47], v[62:63], v[122:123] op_sel:[1,0,0] op_sel_hi:[1,1,1]
	ds_read_b128 v[44:47], v74 offset:1152
	s_waitcnt lgkmcnt(2)
	v_cvt_f32_f16_e32 v56, v152
	v_cvt_f32_f16_sdwa v57, v152 dst_sel:DWORD dst_unused:UNUSED_PAD src0_sel:WORD_1
	v_cvt_f32_f16_e32 v58, v153
	v_cvt_f32_f16_sdwa v59, v153 dst_sel:DWORD dst_unused:UNUSED_PAD src0_sel:WORD_1
	v_cvt_f32_f16_e32 v60, v154
	v_cvt_f32_f16_sdwa v61, v154 dst_sel:DWORD dst_unused:UNUSED_PAD src0_sel:WORD_1
	v_cvt_f32_f16_e32 v62, v155
	v_cvt_f32_f16_sdwa v63, v155 dst_sel:DWORD dst_unused:UNUSED_PAD src0_sel:WORD_1
	v_pk_fma_f32 v[92:93], v[48:49], v[56:57], v[92:93] op_sel_hi:[0,1,1]
	v_pk_fma_f32 v[94:95], v[48:49], v[58:59], v[94:95] op_sel_hi:[0,1,1]
	v_pk_fma_f32 v[96:97], v[48:49], v[60:61], v[96:97] op_sel_hi:[0,1,1]
	v_pk_fma_f32 v[98:99], v[48:49], v[62:63], v[98:99] op_sel_hi:[0,1,1]
	v_pk_fma_f32 v[100:101], v[48:49], v[56:57], v[100:101] op_sel:[1,0,0] op_sel_hi:[1,1,1]
	v_pk_fma_f32 v[102:103], v[48:49], v[58:59], v[102:103] op_sel:[1,0,0] op_sel_hi:[1,1,1]
	v_pk_fma_f32 v[104:105], v[48:49], v[60:61], v[104:105] op_sel:[1,0,0] op_sel_hi:[1,1,1]
	v_pk_fma_f32 v[106:107], v[48:49], v[62:63], v[106:107] op_sel:[1,0,0] op_sel_hi:[1,1,1]
	v_pk_fma_f32 v[108:109], v[50:51], v[56:57], v[108:109] op_sel_hi:[0,1,1]
	v_pk_fma_f32 v[110:111], v[50:51], v[58:59], v[110:111] op_sel_hi:[0,1,1]
	v_pk_fma_f32 v[112:113], v[50:51], v[60:61], v[112:113] op_sel_hi:[0,1,1]
	v_pk_fma_f32 v[114:115], v[50:51], v[62:63], v[114:115] op_sel_hi:[0,1,1]
	v_pk_fma_f32 v[116:117], v[50:51], v[56:57], v[116:117] op_sel:[1,0,0] op_sel_hi:[1,1,1]
	v_pk_fma_f32 v[118:119], v[50:51], v[58:59], v[118:119] op_sel:[1,0,0] op_sel_hi:[1,1,1]
	v_pk_fma_f32 v[120:121], v[50:51], v[60:61], v[120:121] op_sel:[1,0,0] op_sel_hi:[1,1,1]
	v_pk_fma_f32 v[122:123], v[50:51], v[62:63], v[122:123] op_sel:[1,0,0] op_sel_hi:[1,1,1]
	ds_read_b128 v[48:51], v74 offset:1280
	s_waitcnt lgkmcnt(2)
	v_cvt_f32_f16_e32 v56, v156
	v_cvt_f32_f16_sdwa v57, v156 dst_sel:DWORD dst_unused:UNUSED_PAD src0_sel:WORD_1
	v_cvt_f32_f16_e32 v58, v157
	v_cvt_f32_f16_sdwa v59, v157 dst_sel:DWORD dst_unused:UNUSED_PAD src0_sel:WORD_1
	v_cvt_f32_f16_e32 v60, v158
	v_cvt_f32_f16_sdwa v61, v158 dst_sel:DWORD dst_unused:UNUSED_PAD src0_sel:WORD_1
	v_cvt_f32_f16_e32 v62, v159
	v_cvt_f32_f16_sdwa v63, v159 dst_sel:DWORD dst_unused:UNUSED_PAD src0_sel:WORD_1
	v_pk_fma_f32 v[92:93], v[52:53], v[56:57], v[92:93] op_sel_hi:[0,1,1]
	v_pk_fma_f32 v[94:95], v[52:53], v[58:59], v[94:95] op_sel_hi:[0,1,1]
	v_pk_fma_f32 v[96:97], v[52:53], v[60:61], v[96:97] op_sel_hi:[0,1,1]
	v_pk_fma_f32 v[98:99], v[52:53], v[62:63], v[98:99] op_sel_hi:[0,1,1]
	v_pk_fma_f32 v[100:101], v[52:53], v[56:57], v[100:101] op_sel:[1,0,0] op_sel_hi:[1,1,1]
	v_pk_fma_f32 v[102:103], v[52:53], v[58:59], v[102:103] op_sel:[1,0,0] op_sel_hi:[1,1,1]
	v_pk_fma_f32 v[104:105], v[52:53], v[60:61], v[104:105] op_sel:[1,0,0] op_sel_hi:[1,1,1]
	v_pk_fma_f32 v[106:107], v[52:53], v[62:63], v[106:107] op_sel:[1,0,0] op_sel_hi:[1,1,1]
	v_pk_fma_f32 v[108:109], v[54:55], v[56:57], v[108:109] op_sel_hi:[0,1,1]
	v_pk_fma_f32 v[110:111], v[54:55], v[58:59], v[110:111] op_sel_hi:[0,1,1]
	v_pk_fma_f32 v[112:113], v[54:55], v[60:61], v[112:113] op_sel_hi:[0,1,1]
	v_pk_fma_f32 v[114:115], v[54:55], v[62:63], v[114:115] op_sel_hi:[0,1,1]
	v_pk_fma_f32 v[116:117], v[54:55], v[56:57], v[116:117] op_sel:[1,0,0] op_sel_hi:[1,1,1]
	v_pk_fma_f32 v[118:119], v[54:55], v[58:59], v[118:119] op_sel:[1,0,0] op_sel_hi:[1,1,1]
	v_pk_fma_f32 v[120:121], v[54:55], v[60:61], v[120:121] op_sel:[1,0,0] op_sel_hi:[1,1,1]
	v_pk_fma_f32 v[122:123], v[54:55], v[62:63], v[122:123] op_sel:[1,0,0] op_sel_hi:[1,1,1]
	ds_read_b128 v[52:55], v74 offset:1408
	s_waitcnt lgkmcnt(2)
	v_cvt_f32_f16_e32 v56, v160
	v_cvt_f32_f16_sdwa v57, v160 dst_sel:DWORD dst_unused:UNUSED_PAD src0_sel:WORD_1
	v_cvt_f32_f16_e32 v58, v161
	v_cvt_f32_f16_sdwa v59, v161 dst_sel:DWORD dst_unused:UNUSED_PAD src0_sel:WORD_1
	v_cvt_f32_f16_e32 v60, v162
	v_cvt_f32_f16_sdwa v61, v162 dst_sel:DWORD dst_unused:UNUSED_PAD src0_sel:WORD_1
	v_cvt_f32_f16_e32 v62, v163
	v_cvt_f32_f16_sdwa v63, v163 dst_sel:DWORD dst_unused:UNUSED_PAD src0_sel:WORD_1
	v_pk_fma_f32 v[92:93], v[44:45], v[56:57], v[92:93] op_sel_hi:[0,1,1]
	v_pk_fma_f32 v[94:95], v[44:45], v[58:59], v[94:95] op_sel_hi:[0,1,1]
	v_pk_fma_f32 v[96:97], v[44:45], v[60:61], v[96:97] op_sel_hi:[0,1,1]
	v_pk_fma_f32 v[98:99], v[44:45], v[62:63], v[98:99] op_sel_hi:[0,1,1]
	v_pk_fma_f32 v[100:101], v[44:45], v[56:57], v[100:101] op_sel:[1,0,0] op_sel_hi:[1,1,1]
	v_pk_fma_f32 v[102:103], v[44:45], v[58:59], v[102:103] op_sel:[1,0,0] op_sel_hi:[1,1,1]
	v_pk_fma_f32 v[104:105], v[44:45], v[60:61], v[104:105] op_sel:[1,0,0] op_sel_hi:[1,1,1]
	v_pk_fma_f32 v[106:107], v[44:45], v[62:63], v[106:107] op_sel:[1,0,0] op_sel_hi:[1,1,1]
	v_pk_fma_f32 v[108:109], v[46:47], v[56:57], v[108:109] op_sel_hi:[0,1,1]
	v_pk_fma_f32 v[110:111], v[46:47], v[58:59], v[110:111] op_sel_hi:[0,1,1]
	v_pk_fma_f32 v[112:113], v[46:47], v[60:61], v[112:113] op_sel_hi:[0,1,1]
	v_pk_fma_f32 v[114:115], v[46:47], v[62:63], v[114:115] op_sel_hi:[0,1,1]
	v_pk_fma_f32 v[116:117], v[46:47], v[56:57], v[116:117] op_sel:[1,0,0] op_sel_hi:[1,1,1]
	v_pk_fma_f32 v[118:119], v[46:47], v[58:59], v[118:119] op_sel:[1,0,0] op_sel_hi:[1,1,1]
	v_pk_fma_f32 v[120:121], v[46:47], v[60:61], v[120:121] op_sel:[1,0,0] op_sel_hi:[1,1,1]
	v_pk_fma_f32 v[122:123], v[46:47], v[62:63], v[122:123] op_sel:[1,0,0] op_sel_hi:[1,1,1]
	ds_read_b128 v[44:47], v74 offset:1536
	s_waitcnt lgkmcnt(2)
	v_cvt_f32_f16_e32 v56, v164
	v_cvt_f32_f16_sdwa v57, v164 dst_sel:DWORD dst_unused:UNUSED_PAD src0_sel:WORD_1
	v_cvt_f32_f16_e32 v58, v165
	v_cvt_f32_f16_sdwa v59, v165 dst_sel:DWORD dst_unused:UNUSED_PAD src0_sel:WORD_1
	v_cvt_f32_f16_e32 v60, v166
	v_cvt_f32_f16_sdwa v61, v166 dst_sel:DWORD dst_unused:UNUSED_PAD src0_sel:WORD_1
	v_cvt_f32_f16_e32 v62, v167
	v_cvt_f32_f16_sdwa v63, v167 dst_sel:DWORD dst_unused:UNUSED_PAD src0_sel:WORD_1
	v_pk_fma_f32 v[92:93], v[48:49], v[56:57], v[92:93] op_sel_hi:[0,1,1]
	v_pk_fma_f32 v[94:95], v[48:49], v[58:59], v[94:95] op_sel_hi:[0,1,1]
	v_pk_fma_f32 v[96:97], v[48:49], v[60:61], v[96:97] op_sel_hi:[0,1,1]
	v_pk_fma_f32 v[98:99], v[48:49], v[62:63], v[98:99] op_sel_hi:[0,1,1]
	v_pk_fma_f32 v[100:101], v[48:49], v[56:57], v[100:101] op_sel:[1,0,0] op_sel_hi:[1,1,1]
	v_pk_fma_f32 v[102:103], v[48:49], v[58:59], v[102:103] op_sel:[1,0,0] op_sel_hi:[1,1,1]
	v_pk_fma_f32 v[104:105], v[48:49], v[60:61], v[104:105] op_sel:[1,0,0] op_sel_hi:[1,1,1]
	v_pk_fma_f32 v[106:107], v[48:49], v[62:63], v[106:107] op_sel:[1,0,0] op_sel_hi:[1,1,1]
	v_pk_fma_f32 v[108:109], v[50:51], v[56:57], v[108:109] op_sel_hi:[0,1,1]
	v_pk_fma_f32 v[110:111], v[50:51], v[58:59], v[110:111] op_sel_hi:[0,1,1]
	v_pk_fma_f32 v[112:113], v[50:51], v[60:61], v[112:113] op_sel_hi:[0,1,1]
	v_pk_fma_f32 v[114:115], v[50:51], v[62:63], v[114:115] op_sel_hi:[0,1,1]
	v_pk_fma_f32 v[116:117], v[50:51], v[56:57], v[116:117] op_sel:[1,0,0] op_sel_hi:[1,1,1]
	v_pk_fma_f32 v[118:119], v[50:51], v[58:59], v[118:119] op_sel:[1,0,0] op_sel_hi:[1,1,1]
	v_pk_fma_f32 v[120:121], v[50:51], v[60:61], v[120:121] op_sel:[1,0,0] op_sel_hi:[1,1,1]
	v_pk_fma_f32 v[122:123], v[50:51], v[62:63], v[122:123] op_sel:[1,0,0] op_sel_hi:[1,1,1]
	ds_read_b128 v[48:51], v74 offset:1664
	s_waitcnt lgkmcnt(2)
	v_cvt_f32_f16_e32 v56, v168
	v_cvt_f32_f16_sdwa v57, v168 dst_sel:DWORD dst_unused:UNUSED_PAD src0_sel:WORD_1
	v_cvt_f32_f16_e32 v58, v169
	v_cvt_f32_f16_sdwa v59, v169 dst_sel:DWORD dst_unused:UNUSED_PAD src0_sel:WORD_1
	v_cvt_f32_f16_e32 v60, v170
	v_cvt_f32_f16_sdwa v61, v170 dst_sel:DWORD dst_unused:UNUSED_PAD src0_sel:WORD_1
	v_cvt_f32_f16_e32 v62, v171
	v_cvt_f32_f16_sdwa v63, v171 dst_sel:DWORD dst_unused:UNUSED_PAD src0_sel:WORD_1
	v_pk_fma_f32 v[92:93], v[52:53], v[56:57], v[92:93] op_sel_hi:[0,1,1]
	v_pk_fma_f32 v[94:95], v[52:53], v[58:59], v[94:95] op_sel_hi:[0,1,1]
	v_pk_fma_f32 v[96:97], v[52:53], v[60:61], v[96:97] op_sel_hi:[0,1,1]
	v_pk_fma_f32 v[98:99], v[52:53], v[62:63], v[98:99] op_sel_hi:[0,1,1]
	v_pk_fma_f32 v[100:101], v[52:53], v[56:57], v[100:101] op_sel:[1,0,0] op_sel_hi:[1,1,1]
	v_pk_fma_f32 v[102:103], v[52:53], v[58:59], v[102:103] op_sel:[1,0,0] op_sel_hi:[1,1,1]
	v_pk_fma_f32 v[104:105], v[52:53], v[60:61], v[104:105] op_sel:[1,0,0] op_sel_hi:[1,1,1]
	v_pk_fma_f32 v[106:107], v[52:53], v[62:63], v[106:107] op_sel:[1,0,0] op_sel_hi:[1,1,1]
	v_pk_fma_f32 v[108:109], v[54:55], v[56:57], v[108:109] op_sel_hi:[0,1,1]
	v_pk_fma_f32 v[110:111], v[54:55], v[58:59], v[110:111] op_sel_hi:[0,1,1]
	v_pk_fma_f32 v[112:113], v[54:55], v[60:61], v[112:113] op_sel_hi:[0,1,1]
	v_pk_fma_f32 v[114:115], v[54:55], v[62:63], v[114:115] op_sel_hi:[0,1,1]
	v_pk_fma_f32 v[116:117], v[54:55], v[56:57], v[116:117] op_sel:[1,0,0] op_sel_hi:[1,1,1]
	v_pk_fma_f32 v[118:119], v[54:55], v[58:59], v[118:119] op_sel:[1,0,0] op_sel_hi:[1,1,1]
	v_pk_fma_f32 v[120:121], v[54:55], v[60:61], v[120:121] op_sel:[1,0,0] op_sel_hi:[1,1,1]
	v_pk_fma_f32 v[122:123], v[54:55], v[62:63], v[122:123] op_sel:[1,0,0] op_sel_hi:[1,1,1]
	ds_read_b128 v[52:55], v74 offset:1792
	s_waitcnt lgkmcnt(2)
	v_cvt_f32_f16_e32 v56, v172
	v_cvt_f32_f16_sdwa v57, v172 dst_sel:DWORD dst_unused:UNUSED_PAD src0_sel:WORD_1
	v_cvt_f32_f16_e32 v58, v173
	v_cvt_f32_f16_sdwa v59, v173 dst_sel:DWORD dst_unused:UNUSED_PAD src0_sel:WORD_1
	v_cvt_f32_f16_e32 v60, v174
	v_cvt_f32_f16_sdwa v61, v174 dst_sel:DWORD dst_unused:UNUSED_PAD src0_sel:WORD_1
	v_cvt_f32_f16_e32 v62, v175
	v_cvt_f32_f16_sdwa v63, v175 dst_sel:DWORD dst_unused:UNUSED_PAD src0_sel:WORD_1
	v_pk_fma_f32 v[92:93], v[44:45], v[56:57], v[92:93] op_sel_hi:[0,1,1]
	v_pk_fma_f32 v[94:95], v[44:45], v[58:59], v[94:95] op_sel_hi:[0,1,1]
	v_pk_fma_f32 v[96:97], v[44:45], v[60:61], v[96:97] op_sel_hi:[0,1,1]
	v_pk_fma_f32 v[98:99], v[44:45], v[62:63], v[98:99] op_sel_hi:[0,1,1]
	v_pk_fma_f32 v[100:101], v[44:45], v[56:57], v[100:101] op_sel:[1,0,0] op_sel_hi:[1,1,1]
	v_pk_fma_f32 v[102:103], v[44:45], v[58:59], v[102:103] op_sel:[1,0,0] op_sel_hi:[1,1,1]
	v_pk_fma_f32 v[104:105], v[44:45], v[60:61], v[104:105] op_sel:[1,0,0] op_sel_hi:[1,1,1]
	v_pk_fma_f32 v[106:107], v[44:45], v[62:63], v[106:107] op_sel:[1,0,0] op_sel_hi:[1,1,1]
	v_pk_fma_f32 v[108:109], v[46:47], v[56:57], v[108:109] op_sel_hi:[0,1,1]
	v_pk_fma_f32 v[110:111], v[46:47], v[58:59], v[110:111] op_sel_hi:[0,1,1]
	v_pk_fma_f32 v[112:113], v[46:47], v[60:61], v[112:113] op_sel_hi:[0,1,1]
	v_pk_fma_f32 v[114:115], v[46:47], v[62:63], v[114:115] op_sel_hi:[0,1,1]
	v_pk_fma_f32 v[116:117], v[46:47], v[56:57], v[116:117] op_sel:[1,0,0] op_sel_hi:[1,1,1]
	v_pk_fma_f32 v[118:119], v[46:47], v[58:59], v[118:119] op_sel:[1,0,0] op_sel_hi:[1,1,1]
	v_pk_fma_f32 v[120:121], v[46:47], v[60:61], v[120:121] op_sel:[1,0,0] op_sel_hi:[1,1,1]
	v_pk_fma_f32 v[122:123], v[46:47], v[62:63], v[122:123] op_sel:[1,0,0] op_sel_hi:[1,1,1]
	ds_read_b128 v[44:47], v74 offset:1920
	s_waitcnt lgkmcnt(2)
	v_cvt_f32_f16_e32 v56, v176
	v_cvt_f32_f16_sdwa v57, v176 dst_sel:DWORD dst_unused:UNUSED_PAD src0_sel:WORD_1
	v_cvt_f32_f16_e32 v58, v177
	v_cvt_f32_f16_sdwa v59, v177 dst_sel:DWORD dst_unused:UNUSED_PAD src0_sel:WORD_1
	v_cvt_f32_f16_e32 v60, v178
	v_cvt_f32_f16_sdwa v61, v178 dst_sel:DWORD dst_unused:UNUSED_PAD src0_sel:WORD_1
	v_cvt_f32_f16_e32 v62, v179
	v_cvt_f32_f16_sdwa v63, v179 dst_sel:DWORD dst_unused:UNUSED_PAD src0_sel:WORD_1
	v_pk_fma_f32 v[92:93], v[48:49], v[56:57], v[92:93] op_sel_hi:[0,1,1]
	v_pk_fma_f32 v[94:95], v[48:49], v[58:59], v[94:95] op_sel_hi:[0,1,1]
	v_pk_fma_f32 v[96:97], v[48:49], v[60:61], v[96:97] op_sel_hi:[0,1,1]
	v_pk_fma_f32 v[98:99], v[48:49], v[62:63], v[98:99] op_sel_hi:[0,1,1]
	v_pk_fma_f32 v[100:101], v[48:49], v[56:57], v[100:101] op_sel:[1,0,0] op_sel_hi:[1,1,1]
	v_pk_fma_f32 v[102:103], v[48:49], v[58:59], v[102:103] op_sel:[1,0,0] op_sel_hi:[1,1,1]
	v_pk_fma_f32 v[104:105], v[48:49], v[60:61], v[104:105] op_sel:[1,0,0] op_sel_hi:[1,1,1]
	v_pk_fma_f32 v[106:107], v[48:49], v[62:63], v[106:107] op_sel:[1,0,0] op_sel_hi:[1,1,1]
	v_pk_fma_f32 v[108:109], v[50:51], v[56:57], v[108:109] op_sel_hi:[0,1,1]
	v_pk_fma_f32 v[110:111], v[50:51], v[58:59], v[110:111] op_sel_hi:[0,1,1]
	v_pk_fma_f32 v[112:113], v[50:51], v[60:61], v[112:113] op_sel_hi:[0,1,1]
	v_pk_fma_f32 v[114:115], v[50:51], v[62:63], v[114:115] op_sel_hi:[0,1,1]
	v_pk_fma_f32 v[116:117], v[50:51], v[56:57], v[116:117] op_sel:[1,0,0] op_sel_hi:[1,1,1]
	v_pk_fma_f32 v[118:119], v[50:51], v[58:59], v[118:119] op_sel:[1,0,0] op_sel_hi:[1,1,1]
	v_pk_fma_f32 v[120:121], v[50:51], v[60:61], v[120:121] op_sel:[1,0,0] op_sel_hi:[1,1,1]
	v_pk_fma_f32 v[122:123], v[50:51], v[62:63], v[122:123] op_sel:[1,0,0] op_sel_hi:[1,1,1]
	s_waitcnt lgkmcnt(1)
	v_cvt_f32_f16_e32 v56, v180
	v_cvt_f32_f16_sdwa v57, v180 dst_sel:DWORD dst_unused:UNUSED_PAD src0_sel:WORD_1
	v_cvt_f32_f16_e32 v58, v181
	v_cvt_f32_f16_sdwa v59, v181 dst_sel:DWORD dst_unused:UNUSED_PAD src0_sel:WORD_1
	v_cvt_f32_f16_e32 v60, v182
	v_cvt_f32_f16_sdwa v61, v182 dst_sel:DWORD dst_unused:UNUSED_PAD src0_sel:WORD_1
	v_cvt_f32_f16_e32 v62, v183
	v_cvt_f32_f16_sdwa v63, v183 dst_sel:DWORD dst_unused:UNUSED_PAD src0_sel:WORD_1
	v_pk_fma_f32 v[92:93], v[52:53], v[56:57], v[92:93] op_sel_hi:[0,1,1]
	v_pk_fma_f32 v[94:95], v[52:53], v[58:59], v[94:95] op_sel_hi:[0,1,1]
	v_pk_fma_f32 v[96:97], v[52:53], v[60:61], v[96:97] op_sel_hi:[0,1,1]
	v_pk_fma_f32 v[98:99], v[52:53], v[62:63], v[98:99] op_sel_hi:[0,1,1]
	v_pk_fma_f32 v[100:101], v[52:53], v[56:57], v[100:101] op_sel:[1,0,0] op_sel_hi:[1,1,1]
	v_pk_fma_f32 v[102:103], v[52:53], v[58:59], v[102:103] op_sel:[1,0,0] op_sel_hi:[1,1,1]
	v_pk_fma_f32 v[104:105], v[52:53], v[60:61], v[104:105] op_sel:[1,0,0] op_sel_hi:[1,1,1]
	v_pk_fma_f32 v[106:107], v[52:53], v[62:63], v[106:107] op_sel:[1,0,0] op_sel_hi:[1,1,1]
	v_pk_fma_f32 v[108:109], v[54:55], v[56:57], v[108:109] op_sel_hi:[0,1,1]
	v_pk_fma_f32 v[110:111], v[54:55], v[58:59], v[110:111] op_sel_hi:[0,1,1]
	v_pk_fma_f32 v[112:113], v[54:55], v[60:61], v[112:113] op_sel_hi:[0,1,1]
	v_pk_fma_f32 v[114:115], v[54:55], v[62:63], v[114:115] op_sel_hi:[0,1,1]
	v_pk_fma_f32 v[116:117], v[54:55], v[56:57], v[116:117] op_sel:[1,0,0] op_sel_hi:[1,1,1]
	v_pk_fma_f32 v[118:119], v[54:55], v[58:59], v[118:119] op_sel:[1,0,0] op_sel_hi:[1,1,1]
	v_pk_fma_f32 v[120:121], v[54:55], v[60:61], v[120:121] op_sel:[1,0,0] op_sel_hi:[1,1,1]
	v_pk_fma_f32 v[122:123], v[54:55], v[62:63], v[122:123] op_sel:[1,0,0] op_sel_hi:[1,1,1]
	s_waitcnt lgkmcnt(0)
	v_cvt_f32_f16_e32 v56, v184
	v_cvt_f32_f16_sdwa v57, v184 dst_sel:DWORD dst_unused:UNUSED_PAD src0_sel:WORD_1
	v_cvt_f32_f16_e32 v58, v185
	v_cvt_f32_f16_sdwa v59, v185 dst_sel:DWORD dst_unused:UNUSED_PAD src0_sel:WORD_1
	v_cvt_f32_f16_e32 v60, v186
	v_cvt_f32_f16_sdwa v61, v186 dst_sel:DWORD dst_unused:UNUSED_PAD src0_sel:WORD_1
	v_cvt_f32_f16_e32 v62, v187
	v_cvt_f32_f16_sdwa v63, v187 dst_sel:DWORD dst_unused:UNUSED_PAD src0_sel:WORD_1
	v_pk_fma_f32 v[92:93], v[44:45], v[56:57], v[92:93] op_sel_hi:[0,1,1]
	v_pk_fma_f32 v[94:95], v[44:45], v[58:59], v[94:95] op_sel_hi:[0,1,1]
	v_pk_fma_f32 v[96:97], v[44:45], v[60:61], v[96:97] op_sel_hi:[0,1,1]
	v_pk_fma_f32 v[98:99], v[44:45], v[62:63], v[98:99] op_sel_hi:[0,1,1]
	v_pk_fma_f32 v[100:101], v[44:45], v[56:57], v[100:101] op_sel:[1,0,0] op_sel_hi:[1,1,1]
	v_pk_fma_f32 v[102:103], v[44:45], v[58:59], v[102:103] op_sel:[1,0,0] op_sel_hi:[1,1,1]
	v_pk_fma_f32 v[104:105], v[44:45], v[60:61], v[104:105] op_sel:[1,0,0] op_sel_hi:[1,1,1]
	v_pk_fma_f32 v[106:107], v[44:45], v[62:63], v[106:107] op_sel:[1,0,0] op_sel_hi:[1,1,1]
	v_pk_fma_f32 v[108:109], v[46:47], v[56:57], v[108:109] op_sel_hi:[0,1,1]
	v_pk_fma_f32 v[110:111], v[46:47], v[58:59], v[110:111] op_sel_hi:[0,1,1]
	v_pk_fma_f32 v[112:113], v[46:47], v[60:61], v[112:113] op_sel_hi:[0,1,1]
	v_pk_fma_f32 v[114:115], v[46:47], v[62:63], v[114:115] op_sel_hi:[0,1,1]
	v_pk_fma_f32 v[116:117], v[46:47], v[56:57], v[116:117] op_sel:[1,0,0] op_sel_hi:[1,1,1]
	v_pk_fma_f32 v[118:119], v[46:47], v[58:59], v[118:119] op_sel:[1,0,0] op_sel_hi:[1,1,1]
	v_pk_fma_f32 v[120:121], v[46:47], v[60:61], v[120:121] op_sel:[1,0,0] op_sel_hi:[1,1,1]
	v_pk_fma_f32 v[122:123], v[46:47], v[62:63], v[122:123] op_sel:[1,0,0] op_sel_hi:[1,1,1]
	global_load_dwordx4 a[0:3], v8, s[96:97] offset:128
	global_load_dwordx4 a[4:7], v8, s[96:97] offset:144
	global_load_dwordx4 a[8:11], v9, s[96:97] offset:128
	global_load_dwordx4 a[12:15], v9, s[96:97] offset:144
	global_load_dwordx4 a[16:19], v10, s[96:97] offset:128
	global_load_dwordx4 a[20:23], v10, s[96:97] offset:144
	global_load_dwordx4 a[24:27], v11, s[96:97] offset:128
	global_load_dwordx4 a[28:31], v11, s[96:97] offset:144
	global_load_dwordx4 a[32:35], v12, s[96:97] offset:128
	global_load_dwordx4 a[36:39], v12, s[96:97] offset:144
	global_load_dwordx4 a[40:43], v13, s[96:97] offset:128
	global_load_dwordx4 a[44:47], v13, s[96:97] offset:144
	global_load_dwordx4 a[48:51], v14, s[96:97] offset:128
	global_load_dwordx4 a[52:55], v14, s[96:97] offset:144
	global_load_dwordx4 a[56:59], v15, s[96:97] offset:128
	global_load_dwordx4 a[60:63], v15, s[96:97] offset:144
	global_load_dwordx4 a[64:67], v16, s[96:97] offset:128
	global_load_dwordx4 a[68:71], v16, s[96:97] offset:144
	global_load_dwordx4 a[72:75], v17, s[96:97] offset:128
	global_load_dwordx4 a[76:79], v17, s[96:97] offset:144
	global_load_dwordx4 a[80:83], v18, s[96:97] offset:128
	global_load_dwordx4 a[84:87], v18, s[96:97] offset:144
	global_load_dwordx4 a[88:91], v19, s[96:97] offset:128
	global_load_dwordx4 a[92:95], v19, s[96:97] offset:144
	global_load_dwordx4 a[96:99], v20, s[96:97] offset:128
	global_load_dwordx4 a[100:103], v20, s[96:97] offset:144
	global_load_dwordx4 a[104:107], v21, s[96:97] offset:128
	global_load_dwordx4 a[108:111], v21, s[96:97] offset:144
	global_load_dwordx4 a[112:115], v22, s[96:97] offset:128
	global_load_dwordx4 a[116:119], v22, s[96:97] offset:144
	global_load_dwordx4 a[120:123], v23, s[96:97] offset:128
	global_load_dwordx4 a[124:127], v23, s[96:97] offset:144
	global_load_dwordx4 a[144:147], v3, s[12:13] offset:3584
	global_load_dwordx4 a[148:151], v3, s[12:13] offset:3600
	s_waitcnt vmcnt(34)
	ds_read_b128 v[44:47], v74 offset:2048
	ds_read_b128 v[48:51], v74 offset:2176
	ds_read_b128 v[52:55], v74 offset:2304
	s_waitcnt lgkmcnt(2)
	v_cvt_f32_f16_e32 v56, v188
	v_cvt_f32_f16_sdwa v57, v188 dst_sel:DWORD dst_unused:UNUSED_PAD src0_sel:WORD_1
	v_cvt_f32_f16_e32 v58, v189
	v_cvt_f32_f16_sdwa v59, v189 dst_sel:DWORD dst_unused:UNUSED_PAD src0_sel:WORD_1
	v_cvt_f32_f16_e32 v60, v190
	v_cvt_f32_f16_sdwa v61, v190 dst_sel:DWORD dst_unused:UNUSED_PAD src0_sel:WORD_1
	v_cvt_f32_f16_e32 v62, v191
	v_cvt_f32_f16_sdwa v63, v191 dst_sel:DWORD dst_unused:UNUSED_PAD src0_sel:WORD_1
	v_pk_fma_f32 v[92:93], v[44:45], v[56:57], v[92:93] op_sel_hi:[0,1,1]
	v_pk_fma_f32 v[94:95], v[44:45], v[58:59], v[94:95] op_sel_hi:[0,1,1]
	v_pk_fma_f32 v[96:97], v[44:45], v[60:61], v[96:97] op_sel_hi:[0,1,1]
	v_pk_fma_f32 v[98:99], v[44:45], v[62:63], v[98:99] op_sel_hi:[0,1,1]
	v_pk_fma_f32 v[100:101], v[44:45], v[56:57], v[100:101] op_sel:[1,0,0] op_sel_hi:[1,1,1]
	v_pk_fma_f32 v[102:103], v[44:45], v[58:59], v[102:103] op_sel:[1,0,0] op_sel_hi:[1,1,1]
	v_pk_fma_f32 v[104:105], v[44:45], v[60:61], v[104:105] op_sel:[1,0,0] op_sel_hi:[1,1,1]
	v_pk_fma_f32 v[106:107], v[44:45], v[62:63], v[106:107] op_sel:[1,0,0] op_sel_hi:[1,1,1]
	v_pk_fma_f32 v[108:109], v[46:47], v[56:57], v[108:109] op_sel_hi:[0,1,1]
	v_pk_fma_f32 v[110:111], v[46:47], v[58:59], v[110:111] op_sel_hi:[0,1,1]
	v_pk_fma_f32 v[112:113], v[46:47], v[60:61], v[112:113] op_sel_hi:[0,1,1]
	v_pk_fma_f32 v[114:115], v[46:47], v[62:63], v[114:115] op_sel_hi:[0,1,1]
	v_pk_fma_f32 v[116:117], v[46:47], v[56:57], v[116:117] op_sel:[1,0,0] op_sel_hi:[1,1,1]
	v_pk_fma_f32 v[118:119], v[46:47], v[58:59], v[118:119] op_sel:[1,0,0] op_sel_hi:[1,1,1]
	v_pk_fma_f32 v[120:121], v[46:47], v[60:61], v[120:121] op_sel:[1,0,0] op_sel_hi:[1,1,1]
	v_pk_fma_f32 v[122:123], v[46:47], v[62:63], v[122:123] op_sel:[1,0,0] op_sel_hi:[1,1,1]
	ds_read_b128 v[44:47], v74 offset:2432
	s_waitcnt lgkmcnt(2)
	v_cvt_f32_f16_e32 v56, v192
	v_cvt_f32_f16_sdwa v57, v192 dst_sel:DWORD dst_unused:UNUSED_PAD src0_sel:WORD_1
	v_cvt_f32_f16_e32 v58, v193
	v_cvt_f32_f16_sdwa v59, v193 dst_sel:DWORD dst_unused:UNUSED_PAD src0_sel:WORD_1
	v_cvt_f32_f16_e32 v60, v194
	v_cvt_f32_f16_sdwa v61, v194 dst_sel:DWORD dst_unused:UNUSED_PAD src0_sel:WORD_1
	v_cvt_f32_f16_e32 v62, v195
	v_cvt_f32_f16_sdwa v63, v195 dst_sel:DWORD dst_unused:UNUSED_PAD src0_sel:WORD_1
	v_pk_fma_f32 v[92:93], v[48:49], v[56:57], v[92:93] op_sel_hi:[0,1,1]
	v_pk_fma_f32 v[94:95], v[48:49], v[58:59], v[94:95] op_sel_hi:[0,1,1]
	v_pk_fma_f32 v[96:97], v[48:49], v[60:61], v[96:97] op_sel_hi:[0,1,1]
	v_pk_fma_f32 v[98:99], v[48:49], v[62:63], v[98:99] op_sel_hi:[0,1,1]
	v_pk_fma_f32 v[100:101], v[48:49], v[56:57], v[100:101] op_sel:[1,0,0] op_sel_hi:[1,1,1]
	v_pk_fma_f32 v[102:103], v[48:49], v[58:59], v[102:103] op_sel:[1,0,0] op_sel_hi:[1,1,1]
	v_pk_fma_f32 v[104:105], v[48:49], v[60:61], v[104:105] op_sel:[1,0,0] op_sel_hi:[1,1,1]
	v_pk_fma_f32 v[106:107], v[48:49], v[62:63], v[106:107] op_sel:[1,0,0] op_sel_hi:[1,1,1]
	v_pk_fma_f32 v[108:109], v[50:51], v[56:57], v[108:109] op_sel_hi:[0,1,1]
	v_pk_fma_f32 v[110:111], v[50:51], v[58:59], v[110:111] op_sel_hi:[0,1,1]
	v_pk_fma_f32 v[112:113], v[50:51], v[60:61], v[112:113] op_sel_hi:[0,1,1]
	v_pk_fma_f32 v[114:115], v[50:51], v[62:63], v[114:115] op_sel_hi:[0,1,1]
	v_pk_fma_f32 v[116:117], v[50:51], v[56:57], v[116:117] op_sel:[1,0,0] op_sel_hi:[1,1,1]
	v_pk_fma_f32 v[118:119], v[50:51], v[58:59], v[118:119] op_sel:[1,0,0] op_sel_hi:[1,1,1]
	v_pk_fma_f32 v[120:121], v[50:51], v[60:61], v[120:121] op_sel:[1,0,0] op_sel_hi:[1,1,1]
	v_pk_fma_f32 v[122:123], v[50:51], v[62:63], v[122:123] op_sel:[1,0,0] op_sel_hi:[1,1,1]
	ds_read_b128 v[48:51], v74 offset:2560
	s_waitcnt lgkmcnt(2)
	v_cvt_f32_f16_e32 v56, v196
	v_cvt_f32_f16_sdwa v57, v196 dst_sel:DWORD dst_unused:UNUSED_PAD src0_sel:WORD_1
	v_cvt_f32_f16_e32 v58, v197
	v_cvt_f32_f16_sdwa v59, v197 dst_sel:DWORD dst_unused:UNUSED_PAD src0_sel:WORD_1
	v_cvt_f32_f16_e32 v60, v198
	v_cvt_f32_f16_sdwa v61, v198 dst_sel:DWORD dst_unused:UNUSED_PAD src0_sel:WORD_1
	v_cvt_f32_f16_e32 v62, v199
	v_cvt_f32_f16_sdwa v63, v199 dst_sel:DWORD dst_unused:UNUSED_PAD src0_sel:WORD_1
	v_pk_fma_f32 v[92:93], v[52:53], v[56:57], v[92:93] op_sel_hi:[0,1,1]
	v_pk_fma_f32 v[94:95], v[52:53], v[58:59], v[94:95] op_sel_hi:[0,1,1]
	v_pk_fma_f32 v[96:97], v[52:53], v[60:61], v[96:97] op_sel_hi:[0,1,1]
	v_pk_fma_f32 v[98:99], v[52:53], v[62:63], v[98:99] op_sel_hi:[0,1,1]
	v_pk_fma_f32 v[100:101], v[52:53], v[56:57], v[100:101] op_sel:[1,0,0] op_sel_hi:[1,1,1]
	v_pk_fma_f32 v[102:103], v[52:53], v[58:59], v[102:103] op_sel:[1,0,0] op_sel_hi:[1,1,1]
	v_pk_fma_f32 v[104:105], v[52:53], v[60:61], v[104:105] op_sel:[1,0,0] op_sel_hi:[1,1,1]
	v_pk_fma_f32 v[106:107], v[52:53], v[62:63], v[106:107] op_sel:[1,0,0] op_sel_hi:[1,1,1]
	v_pk_fma_f32 v[108:109], v[54:55], v[56:57], v[108:109] op_sel_hi:[0,1,1]
	v_pk_fma_f32 v[110:111], v[54:55], v[58:59], v[110:111] op_sel_hi:[0,1,1]
	v_pk_fma_f32 v[112:113], v[54:55], v[60:61], v[112:113] op_sel_hi:[0,1,1]
	v_pk_fma_f32 v[114:115], v[54:55], v[62:63], v[114:115] op_sel_hi:[0,1,1]
	v_pk_fma_f32 v[116:117], v[54:55], v[56:57], v[116:117] op_sel:[1,0,0] op_sel_hi:[1,1,1]
	v_pk_fma_f32 v[118:119], v[54:55], v[58:59], v[118:119] op_sel:[1,0,0] op_sel_hi:[1,1,1]
	v_pk_fma_f32 v[120:121], v[54:55], v[60:61], v[120:121] op_sel:[1,0,0] op_sel_hi:[1,1,1]
	v_pk_fma_f32 v[122:123], v[54:55], v[62:63], v[122:123] op_sel:[1,0,0] op_sel_hi:[1,1,1]
	ds_read_b128 v[52:55], v74 offset:2688
	s_waitcnt lgkmcnt(2)
	v_cvt_f32_f16_e32 v56, v200
	v_cvt_f32_f16_sdwa v57, v200 dst_sel:DWORD dst_unused:UNUSED_PAD src0_sel:WORD_1
	v_cvt_f32_f16_e32 v58, v201
	v_cvt_f32_f16_sdwa v59, v201 dst_sel:DWORD dst_unused:UNUSED_PAD src0_sel:WORD_1
	v_cvt_f32_f16_e32 v60, v202
	v_cvt_f32_f16_sdwa v61, v202 dst_sel:DWORD dst_unused:UNUSED_PAD src0_sel:WORD_1
	v_cvt_f32_f16_e32 v62, v203
	v_cvt_f32_f16_sdwa v63, v203 dst_sel:DWORD dst_unused:UNUSED_PAD src0_sel:WORD_1
	v_pk_fma_f32 v[92:93], v[44:45], v[56:57], v[92:93] op_sel_hi:[0,1,1]
	v_pk_fma_f32 v[94:95], v[44:45], v[58:59], v[94:95] op_sel_hi:[0,1,1]
	v_pk_fma_f32 v[96:97], v[44:45], v[60:61], v[96:97] op_sel_hi:[0,1,1]
	v_pk_fma_f32 v[98:99], v[44:45], v[62:63], v[98:99] op_sel_hi:[0,1,1]
	v_pk_fma_f32 v[100:101], v[44:45], v[56:57], v[100:101] op_sel:[1,0,0] op_sel_hi:[1,1,1]
	v_pk_fma_f32 v[102:103], v[44:45], v[58:59], v[102:103] op_sel:[1,0,0] op_sel_hi:[1,1,1]
	v_pk_fma_f32 v[104:105], v[44:45], v[60:61], v[104:105] op_sel:[1,0,0] op_sel_hi:[1,1,1]
	v_pk_fma_f32 v[106:107], v[44:45], v[62:63], v[106:107] op_sel:[1,0,0] op_sel_hi:[1,1,1]
	v_pk_fma_f32 v[108:109], v[46:47], v[56:57], v[108:109] op_sel_hi:[0,1,1]
	v_pk_fma_f32 v[110:111], v[46:47], v[58:59], v[110:111] op_sel_hi:[0,1,1]
	v_pk_fma_f32 v[112:113], v[46:47], v[60:61], v[112:113] op_sel_hi:[0,1,1]
	v_pk_fma_f32 v[114:115], v[46:47], v[62:63], v[114:115] op_sel_hi:[0,1,1]
	v_pk_fma_f32 v[116:117], v[46:47], v[56:57], v[116:117] op_sel:[1,0,0] op_sel_hi:[1,1,1]
	v_pk_fma_f32 v[118:119], v[46:47], v[58:59], v[118:119] op_sel:[1,0,0] op_sel_hi:[1,1,1]
	v_pk_fma_f32 v[120:121], v[46:47], v[60:61], v[120:121] op_sel:[1,0,0] op_sel_hi:[1,1,1]
	v_pk_fma_f32 v[122:123], v[46:47], v[62:63], v[122:123] op_sel:[1,0,0] op_sel_hi:[1,1,1]
	ds_read_b128 v[44:47], v74 offset:2816
	s_waitcnt lgkmcnt(2)
	v_cvt_f32_f16_e32 v56, v204
	v_cvt_f32_f16_sdwa v57, v204 dst_sel:DWORD dst_unused:UNUSED_PAD src0_sel:WORD_1
	v_cvt_f32_f16_e32 v58, v205
	v_cvt_f32_f16_sdwa v59, v205 dst_sel:DWORD dst_unused:UNUSED_PAD src0_sel:WORD_1
	v_cvt_f32_f16_e32 v60, v206
	v_cvt_f32_f16_sdwa v61, v206 dst_sel:DWORD dst_unused:UNUSED_PAD src0_sel:WORD_1
	v_cvt_f32_f16_e32 v62, v207
	v_cvt_f32_f16_sdwa v63, v207 dst_sel:DWORD dst_unused:UNUSED_PAD src0_sel:WORD_1
	v_pk_fma_f32 v[92:93], v[48:49], v[56:57], v[92:93] op_sel_hi:[0,1,1]
	v_pk_fma_f32 v[94:95], v[48:49], v[58:59], v[94:95] op_sel_hi:[0,1,1]
	v_pk_fma_f32 v[96:97], v[48:49], v[60:61], v[96:97] op_sel_hi:[0,1,1]
	v_pk_fma_f32 v[98:99], v[48:49], v[62:63], v[98:99] op_sel_hi:[0,1,1]
	v_pk_fma_f32 v[100:101], v[48:49], v[56:57], v[100:101] op_sel:[1,0,0] op_sel_hi:[1,1,1]
	v_pk_fma_f32 v[102:103], v[48:49], v[58:59], v[102:103] op_sel:[1,0,0] op_sel_hi:[1,1,1]
	v_pk_fma_f32 v[104:105], v[48:49], v[60:61], v[104:105] op_sel:[1,0,0] op_sel_hi:[1,1,1]
	v_pk_fma_f32 v[106:107], v[48:49], v[62:63], v[106:107] op_sel:[1,0,0] op_sel_hi:[1,1,1]
	v_pk_fma_f32 v[108:109], v[50:51], v[56:57], v[108:109] op_sel_hi:[0,1,1]
	v_pk_fma_f32 v[110:111], v[50:51], v[58:59], v[110:111] op_sel_hi:[0,1,1]
	v_pk_fma_f32 v[112:113], v[50:51], v[60:61], v[112:113] op_sel_hi:[0,1,1]
	v_pk_fma_f32 v[114:115], v[50:51], v[62:63], v[114:115] op_sel_hi:[0,1,1]
	v_pk_fma_f32 v[116:117], v[50:51], v[56:57], v[116:117] op_sel:[1,0,0] op_sel_hi:[1,1,1]
	v_pk_fma_f32 v[118:119], v[50:51], v[58:59], v[118:119] op_sel:[1,0,0] op_sel_hi:[1,1,1]
	v_pk_fma_f32 v[120:121], v[50:51], v[60:61], v[120:121] op_sel:[1,0,0] op_sel_hi:[1,1,1]
	v_pk_fma_f32 v[122:123], v[50:51], v[62:63], v[122:123] op_sel:[1,0,0] op_sel_hi:[1,1,1]
	ds_read_b128 v[48:51], v74 offset:2944
	s_waitcnt lgkmcnt(2)
	v_cvt_f32_f16_e32 v56, v208
	v_cvt_f32_f16_sdwa v57, v208 dst_sel:DWORD dst_unused:UNUSED_PAD src0_sel:WORD_1
	v_cvt_f32_f16_e32 v58, v209
	v_cvt_f32_f16_sdwa v59, v209 dst_sel:DWORD dst_unused:UNUSED_PAD src0_sel:WORD_1
	v_cvt_f32_f16_e32 v60, v210
	v_cvt_f32_f16_sdwa v61, v210 dst_sel:DWORD dst_unused:UNUSED_PAD src0_sel:WORD_1
	v_cvt_f32_f16_e32 v62, v211
	v_cvt_f32_f16_sdwa v63, v211 dst_sel:DWORD dst_unused:UNUSED_PAD src0_sel:WORD_1
	v_pk_fma_f32 v[92:93], v[52:53], v[56:57], v[92:93] op_sel_hi:[0,1,1]
	v_pk_fma_f32 v[94:95], v[52:53], v[58:59], v[94:95] op_sel_hi:[0,1,1]
	v_pk_fma_f32 v[96:97], v[52:53], v[60:61], v[96:97] op_sel_hi:[0,1,1]
	v_pk_fma_f32 v[98:99], v[52:53], v[62:63], v[98:99] op_sel_hi:[0,1,1]
	v_pk_fma_f32 v[100:101], v[52:53], v[56:57], v[100:101] op_sel:[1,0,0] op_sel_hi:[1,1,1]
	v_pk_fma_f32 v[102:103], v[52:53], v[58:59], v[102:103] op_sel:[1,0,0] op_sel_hi:[1,1,1]
	v_pk_fma_f32 v[104:105], v[52:53], v[60:61], v[104:105] op_sel:[1,0,0] op_sel_hi:[1,1,1]
	v_pk_fma_f32 v[106:107], v[52:53], v[62:63], v[106:107] op_sel:[1,0,0] op_sel_hi:[1,1,1]
	v_pk_fma_f32 v[108:109], v[54:55], v[56:57], v[108:109] op_sel_hi:[0,1,1]
	v_pk_fma_f32 v[110:111], v[54:55], v[58:59], v[110:111] op_sel_hi:[0,1,1]
	v_pk_fma_f32 v[112:113], v[54:55], v[60:61], v[112:113] op_sel_hi:[0,1,1]
	v_pk_fma_f32 v[114:115], v[54:55], v[62:63], v[114:115] op_sel_hi:[0,1,1]
	v_pk_fma_f32 v[116:117], v[54:55], v[56:57], v[116:117] op_sel:[1,0,0] op_sel_hi:[1,1,1]
	v_pk_fma_f32 v[118:119], v[54:55], v[58:59], v[118:119] op_sel:[1,0,0] op_sel_hi:[1,1,1]
	v_pk_fma_f32 v[120:121], v[54:55], v[60:61], v[120:121] op_sel:[1,0,0] op_sel_hi:[1,1,1]
	v_pk_fma_f32 v[122:123], v[54:55], v[62:63], v[122:123] op_sel:[1,0,0] op_sel_hi:[1,1,1]
	ds_read_b128 v[52:55], v74 offset:3072
	s_waitcnt lgkmcnt(2)
	v_cvt_f32_f16_e32 v56, v212
	v_cvt_f32_f16_sdwa v57, v212 dst_sel:DWORD dst_unused:UNUSED_PAD src0_sel:WORD_1
	v_cvt_f32_f16_e32 v58, v213
	v_cvt_f32_f16_sdwa v59, v213 dst_sel:DWORD dst_unused:UNUSED_PAD src0_sel:WORD_1
	v_cvt_f32_f16_e32 v60, v214
	v_cvt_f32_f16_sdwa v61, v214 dst_sel:DWORD dst_unused:UNUSED_PAD src0_sel:WORD_1
	v_cvt_f32_f16_e32 v62, v215
	v_cvt_f32_f16_sdwa v63, v215 dst_sel:DWORD dst_unused:UNUSED_PAD src0_sel:WORD_1
	v_pk_fma_f32 v[92:93], v[44:45], v[56:57], v[92:93] op_sel_hi:[0,1,1]
	v_pk_fma_f32 v[94:95], v[44:45], v[58:59], v[94:95] op_sel_hi:[0,1,1]
	v_pk_fma_f32 v[96:97], v[44:45], v[60:61], v[96:97] op_sel_hi:[0,1,1]
	v_pk_fma_f32 v[98:99], v[44:45], v[62:63], v[98:99] op_sel_hi:[0,1,1]
	v_pk_fma_f32 v[100:101], v[44:45], v[56:57], v[100:101] op_sel:[1,0,0] op_sel_hi:[1,1,1]
	v_pk_fma_f32 v[102:103], v[44:45], v[58:59], v[102:103] op_sel:[1,0,0] op_sel_hi:[1,1,1]
	v_pk_fma_f32 v[104:105], v[44:45], v[60:61], v[104:105] op_sel:[1,0,0] op_sel_hi:[1,1,1]
	v_pk_fma_f32 v[106:107], v[44:45], v[62:63], v[106:107] op_sel:[1,0,0] op_sel_hi:[1,1,1]
	v_pk_fma_f32 v[108:109], v[46:47], v[56:57], v[108:109] op_sel_hi:[0,1,1]
	v_pk_fma_f32 v[110:111], v[46:47], v[58:59], v[110:111] op_sel_hi:[0,1,1]
	v_pk_fma_f32 v[112:113], v[46:47], v[60:61], v[112:113] op_sel_hi:[0,1,1]
	v_pk_fma_f32 v[114:115], v[46:47], v[62:63], v[114:115] op_sel_hi:[0,1,1]
	v_pk_fma_f32 v[116:117], v[46:47], v[56:57], v[116:117] op_sel:[1,0,0] op_sel_hi:[1,1,1]
	v_pk_fma_f32 v[118:119], v[46:47], v[58:59], v[118:119] op_sel:[1,0,0] op_sel_hi:[1,1,1]
	v_pk_fma_f32 v[120:121], v[46:47], v[60:61], v[120:121] op_sel:[1,0,0] op_sel_hi:[1,1,1]
	v_pk_fma_f32 v[122:123], v[46:47], v[62:63], v[122:123] op_sel:[1,0,0] op_sel_hi:[1,1,1]
	ds_read_b128 v[44:47], v74 offset:3200
	s_waitcnt lgkmcnt(2)
	v_cvt_f32_f16_e32 v56, v216
	v_cvt_f32_f16_sdwa v57, v216 dst_sel:DWORD dst_unused:UNUSED_PAD src0_sel:WORD_1
	v_cvt_f32_f16_e32 v58, v217
	v_cvt_f32_f16_sdwa v59, v217 dst_sel:DWORD dst_unused:UNUSED_PAD src0_sel:WORD_1
	v_cvt_f32_f16_e32 v60, v218
	v_cvt_f32_f16_sdwa v61, v218 dst_sel:DWORD dst_unused:UNUSED_PAD src0_sel:WORD_1
	v_cvt_f32_f16_e32 v62, v219
	v_cvt_f32_f16_sdwa v63, v219 dst_sel:DWORD dst_unused:UNUSED_PAD src0_sel:WORD_1
	v_pk_fma_f32 v[92:93], v[48:49], v[56:57], v[92:93] op_sel_hi:[0,1,1]
	v_pk_fma_f32 v[94:95], v[48:49], v[58:59], v[94:95] op_sel_hi:[0,1,1]
	v_pk_fma_f32 v[96:97], v[48:49], v[60:61], v[96:97] op_sel_hi:[0,1,1]
	v_pk_fma_f32 v[98:99], v[48:49], v[62:63], v[98:99] op_sel_hi:[0,1,1]
	v_pk_fma_f32 v[100:101], v[48:49], v[56:57], v[100:101] op_sel:[1,0,0] op_sel_hi:[1,1,1]
	v_pk_fma_f32 v[102:103], v[48:49], v[58:59], v[102:103] op_sel:[1,0,0] op_sel_hi:[1,1,1]
	v_pk_fma_f32 v[104:105], v[48:49], v[60:61], v[104:105] op_sel:[1,0,0] op_sel_hi:[1,1,1]
	v_pk_fma_f32 v[106:107], v[48:49], v[62:63], v[106:107] op_sel:[1,0,0] op_sel_hi:[1,1,1]
	v_pk_fma_f32 v[108:109], v[50:51], v[56:57], v[108:109] op_sel_hi:[0,1,1]
	v_pk_fma_f32 v[110:111], v[50:51], v[58:59], v[110:111] op_sel_hi:[0,1,1]
	v_pk_fma_f32 v[112:113], v[50:51], v[60:61], v[112:113] op_sel_hi:[0,1,1]
	v_pk_fma_f32 v[114:115], v[50:51], v[62:63], v[114:115] op_sel_hi:[0,1,1]
	v_pk_fma_f32 v[116:117], v[50:51], v[56:57], v[116:117] op_sel:[1,0,0] op_sel_hi:[1,1,1]
	v_pk_fma_f32 v[118:119], v[50:51], v[58:59], v[118:119] op_sel:[1,0,0] op_sel_hi:[1,1,1]
	v_pk_fma_f32 v[120:121], v[50:51], v[60:61], v[120:121] op_sel:[1,0,0] op_sel_hi:[1,1,1]
	v_pk_fma_f32 v[122:123], v[50:51], v[62:63], v[122:123] op_sel:[1,0,0] op_sel_hi:[1,1,1]
	ds_read_b128 v[48:51], v74 offset:3328
	s_waitcnt lgkmcnt(2)
	v_cvt_f32_f16_e32 v56, v220
	v_cvt_f32_f16_sdwa v57, v220 dst_sel:DWORD dst_unused:UNUSED_PAD src0_sel:WORD_1
	v_cvt_f32_f16_e32 v58, v221
	v_cvt_f32_f16_sdwa v59, v221 dst_sel:DWORD dst_unused:UNUSED_PAD src0_sel:WORD_1
	v_cvt_f32_f16_e32 v60, v222
	v_cvt_f32_f16_sdwa v61, v222 dst_sel:DWORD dst_unused:UNUSED_PAD src0_sel:WORD_1
	v_cvt_f32_f16_e32 v62, v223
	v_cvt_f32_f16_sdwa v63, v223 dst_sel:DWORD dst_unused:UNUSED_PAD src0_sel:WORD_1
	v_pk_fma_f32 v[92:93], v[52:53], v[56:57], v[92:93] op_sel_hi:[0,1,1]
	v_pk_fma_f32 v[94:95], v[52:53], v[58:59], v[94:95] op_sel_hi:[0,1,1]
	v_pk_fma_f32 v[96:97], v[52:53], v[60:61], v[96:97] op_sel_hi:[0,1,1]
	v_pk_fma_f32 v[98:99], v[52:53], v[62:63], v[98:99] op_sel_hi:[0,1,1]
	v_pk_fma_f32 v[100:101], v[52:53], v[56:57], v[100:101] op_sel:[1,0,0] op_sel_hi:[1,1,1]
	v_pk_fma_f32 v[102:103], v[52:53], v[58:59], v[102:103] op_sel:[1,0,0] op_sel_hi:[1,1,1]
	v_pk_fma_f32 v[104:105], v[52:53], v[60:61], v[104:105] op_sel:[1,0,0] op_sel_hi:[1,1,1]
	v_pk_fma_f32 v[106:107], v[52:53], v[62:63], v[106:107] op_sel:[1,0,0] op_sel_hi:[1,1,1]
	v_pk_fma_f32 v[108:109], v[54:55], v[56:57], v[108:109] op_sel_hi:[0,1,1]
	v_pk_fma_f32 v[110:111], v[54:55], v[58:59], v[110:111] op_sel_hi:[0,1,1]
	v_pk_fma_f32 v[112:113], v[54:55], v[60:61], v[112:113] op_sel_hi:[0,1,1]
	v_pk_fma_f32 v[114:115], v[54:55], v[62:63], v[114:115] op_sel_hi:[0,1,1]
	v_pk_fma_f32 v[116:117], v[54:55], v[56:57], v[116:117] op_sel:[1,0,0] op_sel_hi:[1,1,1]
	v_pk_fma_f32 v[118:119], v[54:55], v[58:59], v[118:119] op_sel:[1,0,0] op_sel_hi:[1,1,1]
	v_pk_fma_f32 v[120:121], v[54:55], v[60:61], v[120:121] op_sel:[1,0,0] op_sel_hi:[1,1,1]
	v_pk_fma_f32 v[122:123], v[54:55], v[62:63], v[122:123] op_sel:[1,0,0] op_sel_hi:[1,1,1]
	ds_read_b128 v[52:55], v74 offset:3456
	s_waitcnt lgkmcnt(2)
	v_cvt_f32_f16_e32 v56, v224
	v_cvt_f32_f16_sdwa v57, v224 dst_sel:DWORD dst_unused:UNUSED_PAD src0_sel:WORD_1
	v_cvt_f32_f16_e32 v58, v225
	v_cvt_f32_f16_sdwa v59, v225 dst_sel:DWORD dst_unused:UNUSED_PAD src0_sel:WORD_1
	v_cvt_f32_f16_e32 v60, v226
	v_cvt_f32_f16_sdwa v61, v226 dst_sel:DWORD dst_unused:UNUSED_PAD src0_sel:WORD_1
	v_cvt_f32_f16_e32 v62, v227
	v_cvt_f32_f16_sdwa v63, v227 dst_sel:DWORD dst_unused:UNUSED_PAD src0_sel:WORD_1
	v_pk_fma_f32 v[92:93], v[44:45], v[56:57], v[92:93] op_sel_hi:[0,1,1]
	v_pk_fma_f32 v[94:95], v[44:45], v[58:59], v[94:95] op_sel_hi:[0,1,1]
	v_pk_fma_f32 v[96:97], v[44:45], v[60:61], v[96:97] op_sel_hi:[0,1,1]
	v_pk_fma_f32 v[98:99], v[44:45], v[62:63], v[98:99] op_sel_hi:[0,1,1]
	v_pk_fma_f32 v[100:101], v[44:45], v[56:57], v[100:101] op_sel:[1,0,0] op_sel_hi:[1,1,1]
	v_pk_fma_f32 v[102:103], v[44:45], v[58:59], v[102:103] op_sel:[1,0,0] op_sel_hi:[1,1,1]
	v_pk_fma_f32 v[104:105], v[44:45], v[60:61], v[104:105] op_sel:[1,0,0] op_sel_hi:[1,1,1]
	v_pk_fma_f32 v[106:107], v[44:45], v[62:63], v[106:107] op_sel:[1,0,0] op_sel_hi:[1,1,1]
	v_pk_fma_f32 v[108:109], v[46:47], v[56:57], v[108:109] op_sel_hi:[0,1,1]
	v_pk_fma_f32 v[110:111], v[46:47], v[58:59], v[110:111] op_sel_hi:[0,1,1]
	v_pk_fma_f32 v[112:113], v[46:47], v[60:61], v[112:113] op_sel_hi:[0,1,1]
	v_pk_fma_f32 v[114:115], v[46:47], v[62:63], v[114:115] op_sel_hi:[0,1,1]
	v_pk_fma_f32 v[116:117], v[46:47], v[56:57], v[116:117] op_sel:[1,0,0] op_sel_hi:[1,1,1]
	v_pk_fma_f32 v[118:119], v[46:47], v[58:59], v[118:119] op_sel:[1,0,0] op_sel_hi:[1,1,1]
	v_pk_fma_f32 v[120:121], v[46:47], v[60:61], v[120:121] op_sel:[1,0,0] op_sel_hi:[1,1,1]
	v_pk_fma_f32 v[122:123], v[46:47], v[62:63], v[122:123] op_sel:[1,0,0] op_sel_hi:[1,1,1]
	ds_read_b128 v[44:47], v74 offset:3584
	s_waitcnt lgkmcnt(2)
	v_cvt_f32_f16_e32 v56, v228
	v_cvt_f32_f16_sdwa v57, v228 dst_sel:DWORD dst_unused:UNUSED_PAD src0_sel:WORD_1
	v_cvt_f32_f16_e32 v58, v229
	v_cvt_f32_f16_sdwa v59, v229 dst_sel:DWORD dst_unused:UNUSED_PAD src0_sel:WORD_1
	v_cvt_f32_f16_e32 v60, v230
	v_cvt_f32_f16_sdwa v61, v230 dst_sel:DWORD dst_unused:UNUSED_PAD src0_sel:WORD_1
	v_cvt_f32_f16_e32 v62, v231
	v_cvt_f32_f16_sdwa v63, v231 dst_sel:DWORD dst_unused:UNUSED_PAD src0_sel:WORD_1
	v_pk_fma_f32 v[92:93], v[48:49], v[56:57], v[92:93] op_sel_hi:[0,1,1]
	v_pk_fma_f32 v[94:95], v[48:49], v[58:59], v[94:95] op_sel_hi:[0,1,1]
	v_pk_fma_f32 v[96:97], v[48:49], v[60:61], v[96:97] op_sel_hi:[0,1,1]
	v_pk_fma_f32 v[98:99], v[48:49], v[62:63], v[98:99] op_sel_hi:[0,1,1]
	v_pk_fma_f32 v[100:101], v[48:49], v[56:57], v[100:101] op_sel:[1,0,0] op_sel_hi:[1,1,1]
	v_pk_fma_f32 v[102:103], v[48:49], v[58:59], v[102:103] op_sel:[1,0,0] op_sel_hi:[1,1,1]
	v_pk_fma_f32 v[104:105], v[48:49], v[60:61], v[104:105] op_sel:[1,0,0] op_sel_hi:[1,1,1]
	v_pk_fma_f32 v[106:107], v[48:49], v[62:63], v[106:107] op_sel:[1,0,0] op_sel_hi:[1,1,1]
	v_pk_fma_f32 v[108:109], v[50:51], v[56:57], v[108:109] op_sel_hi:[0,1,1]
	v_pk_fma_f32 v[110:111], v[50:51], v[58:59], v[110:111] op_sel_hi:[0,1,1]
	v_pk_fma_f32 v[112:113], v[50:51], v[60:61], v[112:113] op_sel_hi:[0,1,1]
	v_pk_fma_f32 v[114:115], v[50:51], v[62:63], v[114:115] op_sel_hi:[0,1,1]
	v_pk_fma_f32 v[116:117], v[50:51], v[56:57], v[116:117] op_sel:[1,0,0] op_sel_hi:[1,1,1]
	v_pk_fma_f32 v[118:119], v[50:51], v[58:59], v[118:119] op_sel:[1,0,0] op_sel_hi:[1,1,1]
	v_pk_fma_f32 v[120:121], v[50:51], v[60:61], v[120:121] op_sel:[1,0,0] op_sel_hi:[1,1,1]
	v_pk_fma_f32 v[122:123], v[50:51], v[62:63], v[122:123] op_sel:[1,0,0] op_sel_hi:[1,1,1]
	ds_read_b128 v[48:51], v74 offset:3712
	s_waitcnt lgkmcnt(2)
	v_cvt_f32_f16_e32 v56, v232
	v_cvt_f32_f16_sdwa v57, v232 dst_sel:DWORD dst_unused:UNUSED_PAD src0_sel:WORD_1
	v_cvt_f32_f16_e32 v58, v233
	v_cvt_f32_f16_sdwa v59, v233 dst_sel:DWORD dst_unused:UNUSED_PAD src0_sel:WORD_1
	v_cvt_f32_f16_e32 v60, v234
	v_cvt_f32_f16_sdwa v61, v234 dst_sel:DWORD dst_unused:UNUSED_PAD src0_sel:WORD_1
	v_cvt_f32_f16_e32 v62, v235
	v_cvt_f32_f16_sdwa v63, v235 dst_sel:DWORD dst_unused:UNUSED_PAD src0_sel:WORD_1
	v_pk_fma_f32 v[92:93], v[52:53], v[56:57], v[92:93] op_sel_hi:[0,1,1]
	v_pk_fma_f32 v[94:95], v[52:53], v[58:59], v[94:95] op_sel_hi:[0,1,1]
	v_pk_fma_f32 v[96:97], v[52:53], v[60:61], v[96:97] op_sel_hi:[0,1,1]
	v_pk_fma_f32 v[98:99], v[52:53], v[62:63], v[98:99] op_sel_hi:[0,1,1]
	v_pk_fma_f32 v[100:101], v[52:53], v[56:57], v[100:101] op_sel:[1,0,0] op_sel_hi:[1,1,1]
	v_pk_fma_f32 v[102:103], v[52:53], v[58:59], v[102:103] op_sel:[1,0,0] op_sel_hi:[1,1,1]
	v_pk_fma_f32 v[104:105], v[52:53], v[60:61], v[104:105] op_sel:[1,0,0] op_sel_hi:[1,1,1]
	v_pk_fma_f32 v[106:107], v[52:53], v[62:63], v[106:107] op_sel:[1,0,0] op_sel_hi:[1,1,1]
	v_pk_fma_f32 v[108:109], v[54:55], v[56:57], v[108:109] op_sel_hi:[0,1,1]
	v_pk_fma_f32 v[110:111], v[54:55], v[58:59], v[110:111] op_sel_hi:[0,1,1]
	v_pk_fma_f32 v[112:113], v[54:55], v[60:61], v[112:113] op_sel_hi:[0,1,1]
	v_pk_fma_f32 v[114:115], v[54:55], v[62:63], v[114:115] op_sel_hi:[0,1,1]
	v_pk_fma_f32 v[116:117], v[54:55], v[56:57], v[116:117] op_sel:[1,0,0] op_sel_hi:[1,1,1]
	v_pk_fma_f32 v[118:119], v[54:55], v[58:59], v[118:119] op_sel:[1,0,0] op_sel_hi:[1,1,1]
	v_pk_fma_f32 v[120:121], v[54:55], v[60:61], v[120:121] op_sel:[1,0,0] op_sel_hi:[1,1,1]
	v_pk_fma_f32 v[122:123], v[54:55], v[62:63], v[122:123] op_sel:[1,0,0] op_sel_hi:[1,1,1]
	ds_read_b128 v[52:55], v74 offset:3840
	s_waitcnt lgkmcnt(2)
	v_cvt_f32_f16_e32 v56, v236
	v_cvt_f32_f16_sdwa v57, v236 dst_sel:DWORD dst_unused:UNUSED_PAD src0_sel:WORD_1
	v_cvt_f32_f16_e32 v58, v237
	v_cvt_f32_f16_sdwa v59, v237 dst_sel:DWORD dst_unused:UNUSED_PAD src0_sel:WORD_1
	v_cvt_f32_f16_e32 v60, v238
	v_cvt_f32_f16_sdwa v61, v238 dst_sel:DWORD dst_unused:UNUSED_PAD src0_sel:WORD_1
	v_cvt_f32_f16_e32 v62, v239
	v_cvt_f32_f16_sdwa v63, v239 dst_sel:DWORD dst_unused:UNUSED_PAD src0_sel:WORD_1
	v_pk_fma_f32 v[92:93], v[44:45], v[56:57], v[92:93] op_sel_hi:[0,1,1]
	v_pk_fma_f32 v[94:95], v[44:45], v[58:59], v[94:95] op_sel_hi:[0,1,1]
	v_pk_fma_f32 v[96:97], v[44:45], v[60:61], v[96:97] op_sel_hi:[0,1,1]
	v_pk_fma_f32 v[98:99], v[44:45], v[62:63], v[98:99] op_sel_hi:[0,1,1]
	v_pk_fma_f32 v[100:101], v[44:45], v[56:57], v[100:101] op_sel:[1,0,0] op_sel_hi:[1,1,1]
	v_pk_fma_f32 v[102:103], v[44:45], v[58:59], v[102:103] op_sel:[1,0,0] op_sel_hi:[1,1,1]
	v_pk_fma_f32 v[104:105], v[44:45], v[60:61], v[104:105] op_sel:[1,0,0] op_sel_hi:[1,1,1]
	v_pk_fma_f32 v[106:107], v[44:45], v[62:63], v[106:107] op_sel:[1,0,0] op_sel_hi:[1,1,1]
	v_pk_fma_f32 v[108:109], v[46:47], v[56:57], v[108:109] op_sel_hi:[0,1,1]
	v_pk_fma_f32 v[110:111], v[46:47], v[58:59], v[110:111] op_sel_hi:[0,1,1]
	v_pk_fma_f32 v[112:113], v[46:47], v[60:61], v[112:113] op_sel_hi:[0,1,1]
	v_pk_fma_f32 v[114:115], v[46:47], v[62:63], v[114:115] op_sel_hi:[0,1,1]
	v_pk_fma_f32 v[116:117], v[46:47], v[56:57], v[116:117] op_sel:[1,0,0] op_sel_hi:[1,1,1]
	v_pk_fma_f32 v[118:119], v[46:47], v[58:59], v[118:119] op_sel:[1,0,0] op_sel_hi:[1,1,1]
	v_pk_fma_f32 v[120:121], v[46:47], v[60:61], v[120:121] op_sel:[1,0,0] op_sel_hi:[1,1,1]
	v_pk_fma_f32 v[122:123], v[46:47], v[62:63], v[122:123] op_sel:[1,0,0] op_sel_hi:[1,1,1]
	ds_read_b128 v[44:47], v74 offset:3968
	s_waitcnt lgkmcnt(2)
	v_cvt_f32_f16_e32 v56, v240
	v_cvt_f32_f16_sdwa v57, v240 dst_sel:DWORD dst_unused:UNUSED_PAD src0_sel:WORD_1
	v_cvt_f32_f16_e32 v58, v241
	v_cvt_f32_f16_sdwa v59, v241 dst_sel:DWORD dst_unused:UNUSED_PAD src0_sel:WORD_1
	v_cvt_f32_f16_e32 v60, v242
	v_cvt_f32_f16_sdwa v61, v242 dst_sel:DWORD dst_unused:UNUSED_PAD src0_sel:WORD_1
	v_cvt_f32_f16_e32 v62, v243
	v_cvt_f32_f16_sdwa v63, v243 dst_sel:DWORD dst_unused:UNUSED_PAD src0_sel:WORD_1
	v_pk_fma_f32 v[92:93], v[48:49], v[56:57], v[92:93] op_sel_hi:[0,1,1]
	v_pk_fma_f32 v[94:95], v[48:49], v[58:59], v[94:95] op_sel_hi:[0,1,1]
	v_pk_fma_f32 v[96:97], v[48:49], v[60:61], v[96:97] op_sel_hi:[0,1,1]
	v_pk_fma_f32 v[98:99], v[48:49], v[62:63], v[98:99] op_sel_hi:[0,1,1]
	v_pk_fma_f32 v[100:101], v[48:49], v[56:57], v[100:101] op_sel:[1,0,0] op_sel_hi:[1,1,1]
	v_pk_fma_f32 v[102:103], v[48:49], v[58:59], v[102:103] op_sel:[1,0,0] op_sel_hi:[1,1,1]
	v_pk_fma_f32 v[104:105], v[48:49], v[60:61], v[104:105] op_sel:[1,0,0] op_sel_hi:[1,1,1]
	v_pk_fma_f32 v[106:107], v[48:49], v[62:63], v[106:107] op_sel:[1,0,0] op_sel_hi:[1,1,1]
	v_pk_fma_f32 v[108:109], v[50:51], v[56:57], v[108:109] op_sel_hi:[0,1,1]
	v_pk_fma_f32 v[110:111], v[50:51], v[58:59], v[110:111] op_sel_hi:[0,1,1]
	v_pk_fma_f32 v[112:113], v[50:51], v[60:61], v[112:113] op_sel_hi:[0,1,1]
	v_pk_fma_f32 v[114:115], v[50:51], v[62:63], v[114:115] op_sel_hi:[0,1,1]
	v_pk_fma_f32 v[116:117], v[50:51], v[56:57], v[116:117] op_sel:[1,0,0] op_sel_hi:[1,1,1]
	v_pk_fma_f32 v[118:119], v[50:51], v[58:59], v[118:119] op_sel:[1,0,0] op_sel_hi:[1,1,1]
	v_pk_fma_f32 v[120:121], v[50:51], v[60:61], v[120:121] op_sel:[1,0,0] op_sel_hi:[1,1,1]
	v_pk_fma_f32 v[122:123], v[50:51], v[62:63], v[122:123] op_sel:[1,0,0] op_sel_hi:[1,1,1]
	s_waitcnt lgkmcnt(1)
	v_cvt_f32_f16_e32 v56, v244
	v_cvt_f32_f16_sdwa v57, v244 dst_sel:DWORD dst_unused:UNUSED_PAD src0_sel:WORD_1
	v_cvt_f32_f16_e32 v58, v245
	v_cvt_f32_f16_sdwa v59, v245 dst_sel:DWORD dst_unused:UNUSED_PAD src0_sel:WORD_1
	v_cvt_f32_f16_e32 v60, v246
	v_cvt_f32_f16_sdwa v61, v246 dst_sel:DWORD dst_unused:UNUSED_PAD src0_sel:WORD_1
	v_cvt_f32_f16_e32 v62, v247
	v_cvt_f32_f16_sdwa v63, v247 dst_sel:DWORD dst_unused:UNUSED_PAD src0_sel:WORD_1
	v_pk_fma_f32 v[92:93], v[52:53], v[56:57], v[92:93] op_sel_hi:[0,1,1]
	v_pk_fma_f32 v[94:95], v[52:53], v[58:59], v[94:95] op_sel_hi:[0,1,1]
	v_pk_fma_f32 v[96:97], v[52:53], v[60:61], v[96:97] op_sel_hi:[0,1,1]
	v_pk_fma_f32 v[98:99], v[52:53], v[62:63], v[98:99] op_sel_hi:[0,1,1]
	v_pk_fma_f32 v[100:101], v[52:53], v[56:57], v[100:101] op_sel:[1,0,0] op_sel_hi:[1,1,1]
	v_pk_fma_f32 v[102:103], v[52:53], v[58:59], v[102:103] op_sel:[1,0,0] op_sel_hi:[1,1,1]
	v_pk_fma_f32 v[104:105], v[52:53], v[60:61], v[104:105] op_sel:[1,0,0] op_sel_hi:[1,1,1]
	v_pk_fma_f32 v[106:107], v[52:53], v[62:63], v[106:107] op_sel:[1,0,0] op_sel_hi:[1,1,1]
	v_pk_fma_f32 v[108:109], v[54:55], v[56:57], v[108:109] op_sel_hi:[0,1,1]
	v_pk_fma_f32 v[110:111], v[54:55], v[58:59], v[110:111] op_sel_hi:[0,1,1]
	v_pk_fma_f32 v[112:113], v[54:55], v[60:61], v[112:113] op_sel_hi:[0,1,1]
	v_pk_fma_f32 v[114:115], v[54:55], v[62:63], v[114:115] op_sel_hi:[0,1,1]
	v_pk_fma_f32 v[116:117], v[54:55], v[56:57], v[116:117] op_sel:[1,0,0] op_sel_hi:[1,1,1]
	v_pk_fma_f32 v[118:119], v[54:55], v[58:59], v[118:119] op_sel:[1,0,0] op_sel_hi:[1,1,1]
	v_pk_fma_f32 v[120:121], v[54:55], v[60:61], v[120:121] op_sel:[1,0,0] op_sel_hi:[1,1,1]
	v_pk_fma_f32 v[122:123], v[54:55], v[62:63], v[122:123] op_sel:[1,0,0] op_sel_hi:[1,1,1]
	s_waitcnt lgkmcnt(0)
	v_cvt_f32_f16_e32 v56, v248
	v_cvt_f32_f16_sdwa v57, v248 dst_sel:DWORD dst_unused:UNUSED_PAD src0_sel:WORD_1
	v_cvt_f32_f16_e32 v58, v249
	v_cvt_f32_f16_sdwa v59, v249 dst_sel:DWORD dst_unused:UNUSED_PAD src0_sel:WORD_1
	v_cvt_f32_f16_e32 v60, v250
	v_cvt_f32_f16_sdwa v61, v250 dst_sel:DWORD dst_unused:UNUSED_PAD src0_sel:WORD_1
	v_cvt_f32_f16_e32 v62, v251
	v_cvt_f32_f16_sdwa v63, v251 dst_sel:DWORD dst_unused:UNUSED_PAD src0_sel:WORD_1
	v_pk_fma_f32 v[92:93], v[44:45], v[56:57], v[92:93] op_sel_hi:[0,1,1]
	v_pk_fma_f32 v[94:95], v[44:45], v[58:59], v[94:95] op_sel_hi:[0,1,1]
	v_pk_fma_f32 v[96:97], v[44:45], v[60:61], v[96:97] op_sel_hi:[0,1,1]
	v_pk_fma_f32 v[98:99], v[44:45], v[62:63], v[98:99] op_sel_hi:[0,1,1]
	v_pk_fma_f32 v[100:101], v[44:45], v[56:57], v[100:101] op_sel:[1,0,0] op_sel_hi:[1,1,1]
	v_pk_fma_f32 v[102:103], v[44:45], v[58:59], v[102:103] op_sel:[1,0,0] op_sel_hi:[1,1,1]
	v_pk_fma_f32 v[104:105], v[44:45], v[60:61], v[104:105] op_sel:[1,0,0] op_sel_hi:[1,1,1]
	v_pk_fma_f32 v[106:107], v[44:45], v[62:63], v[106:107] op_sel:[1,0,0] op_sel_hi:[1,1,1]
	v_pk_fma_f32 v[108:109], v[46:47], v[56:57], v[108:109] op_sel_hi:[0,1,1]
	v_pk_fma_f32 v[110:111], v[46:47], v[58:59], v[110:111] op_sel_hi:[0,1,1]
	v_pk_fma_f32 v[112:113], v[46:47], v[60:61], v[112:113] op_sel_hi:[0,1,1]
	v_pk_fma_f32 v[114:115], v[46:47], v[62:63], v[114:115] op_sel_hi:[0,1,1]
	v_pk_fma_f32 v[116:117], v[46:47], v[56:57], v[116:117] op_sel:[1,0,0] op_sel_hi:[1,1,1]
	v_pk_fma_f32 v[118:119], v[46:47], v[58:59], v[118:119] op_sel:[1,0,0] op_sel_hi:[1,1,1]
	v_pk_fma_f32 v[120:121], v[46:47], v[60:61], v[120:121] op_sel:[1,0,0] op_sel_hi:[1,1,1]
	v_pk_fma_f32 v[122:123], v[46:47], v[62:63], v[122:123] op_sel:[1,0,0] op_sel_hi:[1,1,1]
	v_add_f32_dpp v92, v92, v92 quad_perm:[1,0,3,2] row_mask:0xf bank_mask:0xf bound_ctrl:1
	v_add_f32_dpp v93, v93, v93 quad_perm:[1,0,3,2] row_mask:0xf bank_mask:0xf bound_ctrl:1
	v_add_f32_dpp v94, v94, v94 quad_perm:[1,0,3,2] row_mask:0xf bank_mask:0xf bound_ctrl:1
	v_add_f32_dpp v95, v95, v95 quad_perm:[1,0,3,2] row_mask:0xf bank_mask:0xf bound_ctrl:1
	v_add_f32_dpp v96, v96, v96 quad_perm:[1,0,3,2] row_mask:0xf bank_mask:0xf bound_ctrl:1
	v_add_f32_dpp v97, v97, v97 quad_perm:[1,0,3,2] row_mask:0xf bank_mask:0xf bound_ctrl:1
	v_add_f32_dpp v98, v98, v98 quad_perm:[1,0,3,2] row_mask:0xf bank_mask:0xf bound_ctrl:1
	v_add_f32_dpp v99, v99, v99 quad_perm:[1,0,3,2] row_mask:0xf bank_mask:0xf bound_ctrl:1
	v_add_f32_dpp v100, v100, v100 quad_perm:[1,0,3,2] row_mask:0xf bank_mask:0xf bound_ctrl:1
	v_add_f32_dpp v101, v101, v101 quad_perm:[1,0,3,2] row_mask:0xf bank_mask:0xf bound_ctrl:1
	v_add_f32_dpp v102, v102, v102 quad_perm:[1,0,3,2] row_mask:0xf bank_mask:0xf bound_ctrl:1
	v_add_f32_dpp v103, v103, v103 quad_perm:[1,0,3,2] row_mask:0xf bank_mask:0xf bound_ctrl:1
	v_add_f32_dpp v104, v104, v104 quad_perm:[1,0,3,2] row_mask:0xf bank_mask:0xf bound_ctrl:1
	v_add_f32_dpp v105, v105, v105 quad_perm:[1,0,3,2] row_mask:0xf bank_mask:0xf bound_ctrl:1
	v_add_f32_dpp v106, v106, v106 quad_perm:[1,0,3,2] row_mask:0xf bank_mask:0xf bound_ctrl:1
	v_add_f32_dpp v107, v107, v107 quad_perm:[1,0,3,2] row_mask:0xf bank_mask:0xf bound_ctrl:1
	v_add_f32_dpp v108, v108, v108 quad_perm:[1,0,3,2] row_mask:0xf bank_mask:0xf bound_ctrl:1
	v_add_f32_dpp v109, v109, v109 quad_perm:[1,0,3,2] row_mask:0xf bank_mask:0xf bound_ctrl:1
	v_add_f32_dpp v110, v110, v110 quad_perm:[1,0,3,2] row_mask:0xf bank_mask:0xf bound_ctrl:1
	v_add_f32_dpp v111, v111, v111 quad_perm:[1,0,3,2] row_mask:0xf bank_mask:0xf bound_ctrl:1
	v_add_f32_dpp v112, v112, v112 quad_perm:[1,0,3,2] row_mask:0xf bank_mask:0xf bound_ctrl:1
	v_add_f32_dpp v113, v113, v113 quad_perm:[1,0,3,2] row_mask:0xf bank_mask:0xf bound_ctrl:1
	v_add_f32_dpp v114, v114, v114 quad_perm:[1,0,3,2] row_mask:0xf bank_mask:0xf bound_ctrl:1
	v_add_f32_dpp v115, v115, v115 quad_perm:[1,0,3,2] row_mask:0xf bank_mask:0xf bound_ctrl:1
	v_add_f32_dpp v116, v116, v116 quad_perm:[1,0,3,2] row_mask:0xf bank_mask:0xf bound_ctrl:1
	v_add_f32_dpp v117, v117, v117 quad_perm:[1,0,3,2] row_mask:0xf bank_mask:0xf bound_ctrl:1
	v_add_f32_dpp v118, v118, v118 quad_perm:[1,0,3,2] row_mask:0xf bank_mask:0xf bound_ctrl:1
	v_add_f32_dpp v119, v119, v119 quad_perm:[1,0,3,2] row_mask:0xf bank_mask:0xf bound_ctrl:1
	v_add_f32_dpp v120, v120, v120 quad_perm:[1,0,3,2] row_mask:0xf bank_mask:0xf bound_ctrl:1
	v_add_f32_dpp v121, v121, v121 quad_perm:[1,0,3,2] row_mask:0xf bank_mask:0xf bound_ctrl:1
	v_add_f32_dpp v122, v122, v122 quad_perm:[1,0,3,2] row_mask:0xf bank_mask:0xf bound_ctrl:1
	v_add_f32_dpp v123, v123, v123 quad_perm:[1,0,3,2] row_mask:0xf bank_mask:0xf bound_ctrl:1
	v_add_f32_dpp v92, v92, v92 quad_perm:[2,3,0,1] row_mask:0xf bank_mask:0xf bound_ctrl:1
	v_add_f32_dpp v93, v93, v93 quad_perm:[2,3,0,1] row_mask:0xf bank_mask:0xf bound_ctrl:1
	v_add_f32_dpp v94, v94, v94 quad_perm:[2,3,0,1] row_mask:0xf bank_mask:0xf bound_ctrl:1
	v_add_f32_dpp v95, v95, v95 quad_perm:[2,3,0,1] row_mask:0xf bank_mask:0xf bound_ctrl:1
	v_add_f32_dpp v96, v96, v96 quad_perm:[2,3,0,1] row_mask:0xf bank_mask:0xf bound_ctrl:1
	v_add_f32_dpp v97, v97, v97 quad_perm:[2,3,0,1] row_mask:0xf bank_mask:0xf bound_ctrl:1
	v_add_f32_dpp v98, v98, v98 quad_perm:[2,3,0,1] row_mask:0xf bank_mask:0xf bound_ctrl:1
	v_add_f32_dpp v99, v99, v99 quad_perm:[2,3,0,1] row_mask:0xf bank_mask:0xf bound_ctrl:1
	v_add_f32_dpp v100, v100, v100 quad_perm:[2,3,0,1] row_mask:0xf bank_mask:0xf bound_ctrl:1
	v_add_f32_dpp v101, v101, v101 quad_perm:[2,3,0,1] row_mask:0xf bank_mask:0xf bound_ctrl:1
	v_add_f32_dpp v102, v102, v102 quad_perm:[2,3,0,1] row_mask:0xf bank_mask:0xf bound_ctrl:1
	v_add_f32_dpp v103, v103, v103 quad_perm:[2,3,0,1] row_mask:0xf bank_mask:0xf bound_ctrl:1
	v_add_f32_dpp v104, v104, v104 quad_perm:[2,3,0,1] row_mask:0xf bank_mask:0xf bound_ctrl:1
	v_add_f32_dpp v105, v105, v105 quad_perm:[2,3,0,1] row_mask:0xf bank_mask:0xf bound_ctrl:1
	v_add_f32_dpp v106, v106, v106 quad_perm:[2,3,0,1] row_mask:0xf bank_mask:0xf bound_ctrl:1
	v_add_f32_dpp v107, v107, v107 quad_perm:[2,3,0,1] row_mask:0xf bank_mask:0xf bound_ctrl:1
	v_add_f32_dpp v108, v108, v108 quad_perm:[2,3,0,1] row_mask:0xf bank_mask:0xf bound_ctrl:1
	v_add_f32_dpp v109, v109, v109 quad_perm:[2,3,0,1] row_mask:0xf bank_mask:0xf bound_ctrl:1
	v_add_f32_dpp v110, v110, v110 quad_perm:[2,3,0,1] row_mask:0xf bank_mask:0xf bound_ctrl:1
	v_add_f32_dpp v111, v111, v111 quad_perm:[2,3,0,1] row_mask:0xf bank_mask:0xf bound_ctrl:1
	v_add_f32_dpp v112, v112, v112 quad_perm:[2,3,0,1] row_mask:0xf bank_mask:0xf bound_ctrl:1
	v_add_f32_dpp v113, v113, v113 quad_perm:[2,3,0,1] row_mask:0xf bank_mask:0xf bound_ctrl:1
	v_add_f32_dpp v114, v114, v114 quad_perm:[2,3,0,1] row_mask:0xf bank_mask:0xf bound_ctrl:1
	v_add_f32_dpp v115, v115, v115 quad_perm:[2,3,0,1] row_mask:0xf bank_mask:0xf bound_ctrl:1
	v_add_f32_dpp v116, v116, v116 quad_perm:[2,3,0,1] row_mask:0xf bank_mask:0xf bound_ctrl:1
	v_add_f32_dpp v117, v117, v117 quad_perm:[2,3,0,1] row_mask:0xf bank_mask:0xf bound_ctrl:1
	v_add_f32_dpp v118, v118, v118 quad_perm:[2,3,0,1] row_mask:0xf bank_mask:0xf bound_ctrl:1
	v_add_f32_dpp v119, v119, v119 quad_perm:[2,3,0,1] row_mask:0xf bank_mask:0xf bound_ctrl:1
	v_add_f32_dpp v120, v120, v120 quad_perm:[2,3,0,1] row_mask:0xf bank_mask:0xf bound_ctrl:1
	v_add_f32_dpp v121, v121, v121 quad_perm:[2,3,0,1] row_mask:0xf bank_mask:0xf bound_ctrl:1
	v_add_f32_dpp v122, v122, v122 quad_perm:[2,3,0,1] row_mask:0xf bank_mask:0xf bound_ctrl:1
	v_add_f32_dpp v123, v123, v123 quad_perm:[2,3,0,1] row_mask:0xf bank_mask:0xf bound_ctrl:1
	v_add_f32_dpp v92, v92, v92 row_half_mirror row_mask:0xf bank_mask:0xf bound_ctrl:1
	v_add_f32_dpp v93, v93, v93 row_half_mirror row_mask:0xf bank_mask:0xf bound_ctrl:1
	v_add_f32_dpp v94, v94, v94 row_half_mirror row_mask:0xf bank_mask:0xf bound_ctrl:1
	v_add_f32_dpp v95, v95, v95 row_half_mirror row_mask:0xf bank_mask:0xf bound_ctrl:1
	v_add_f32_dpp v96, v96, v96 row_half_mirror row_mask:0xf bank_mask:0xf bound_ctrl:1
	v_add_f32_dpp v97, v97, v97 row_half_mirror row_mask:0xf bank_mask:0xf bound_ctrl:1
	v_add_f32_dpp v98, v98, v98 row_half_mirror row_mask:0xf bank_mask:0xf bound_ctrl:1
	v_add_f32_dpp v99, v99, v99 row_half_mirror row_mask:0xf bank_mask:0xf bound_ctrl:1
	v_add_f32_dpp v100, v100, v100 row_half_mirror row_mask:0xf bank_mask:0xf bound_ctrl:1
	v_add_f32_dpp v101, v101, v101 row_half_mirror row_mask:0xf bank_mask:0xf bound_ctrl:1
	v_add_f32_dpp v102, v102, v102 row_half_mirror row_mask:0xf bank_mask:0xf bound_ctrl:1
	v_add_f32_dpp v103, v103, v103 row_half_mirror row_mask:0xf bank_mask:0xf bound_ctrl:1
	v_add_f32_dpp v104, v104, v104 row_half_mirror row_mask:0xf bank_mask:0xf bound_ctrl:1
	v_add_f32_dpp v105, v105, v105 row_half_mirror row_mask:0xf bank_mask:0xf bound_ctrl:1
	v_add_f32_dpp v106, v106, v106 row_half_mirror row_mask:0xf bank_mask:0xf bound_ctrl:1
	v_add_f32_dpp v107, v107, v107 row_half_mirror row_mask:0xf bank_mask:0xf bound_ctrl:1
	v_add_f32_dpp v108, v108, v108 row_half_mirror row_mask:0xf bank_mask:0xf bound_ctrl:1
	v_add_f32_dpp v109, v109, v109 row_half_mirror row_mask:0xf bank_mask:0xf bound_ctrl:1
	v_add_f32_dpp v110, v110, v110 row_half_mirror row_mask:0xf bank_mask:0xf bound_ctrl:1
	v_add_f32_dpp v111, v111, v111 row_half_mirror row_mask:0xf bank_mask:0xf bound_ctrl:1
	v_add_f32_dpp v112, v112, v112 row_half_mirror row_mask:0xf bank_mask:0xf bound_ctrl:1
	v_add_f32_dpp v113, v113, v113 row_half_mirror row_mask:0xf bank_mask:0xf bound_ctrl:1
	v_add_f32_dpp v114, v114, v114 row_half_mirror row_mask:0xf bank_mask:0xf bound_ctrl:1
	v_add_f32_dpp v115, v115, v115 row_half_mirror row_mask:0xf bank_mask:0xf bound_ctrl:1
	v_add_f32_dpp v116, v116, v116 row_half_mirror row_mask:0xf bank_mask:0xf bound_ctrl:1
	v_add_f32_dpp v117, v117, v117 row_half_mirror row_mask:0xf bank_mask:0xf bound_ctrl:1
	v_add_f32_dpp v118, v118, v118 row_half_mirror row_mask:0xf bank_mask:0xf bound_ctrl:1
	v_add_f32_dpp v119, v119, v119 row_half_mirror row_mask:0xf bank_mask:0xf bound_ctrl:1
	v_add_f32_dpp v120, v120, v120 row_half_mirror row_mask:0xf bank_mask:0xf bound_ctrl:1
	v_add_f32_dpp v121, v121, v121 row_half_mirror row_mask:0xf bank_mask:0xf bound_ctrl:1
	v_add_f32_dpp v122, v122, v122 row_half_mirror row_mask:0xf bank_mask:0xf bound_ctrl:1
	v_add_f32_dpp v123, v123, v123 row_half_mirror row_mask:0xf bank_mask:0xf bound_ctrl:1
	s_mov_b64 s[2:3], exec
	s_mov_b64 exec, s[4:5]
	v_accvgpr_read_b32 v44, a128
	v_accvgpr_read_b32 v45, a129
	v_accvgpr_read_b32 v46, a130
	v_accvgpr_read_b32 v47, a131
	v_cvt_f32_f16_e32 v56, v44
	v_cvt_f32_f16_sdwa v57, v44 dst_sel:DWORD dst_unused:UNUSED_PAD src0_sel:WORD_1
	v_cvt_f32_f16_e32 v58, v45
	v_cvt_f32_f16_sdwa v59, v45 dst_sel:DWORD dst_unused:UNUSED_PAD src0_sel:WORD_1
	v_cvt_f32_f16_e32 v60, v46
	v_cvt_f32_f16_sdwa v61, v46 dst_sel:DWORD dst_unused:UNUSED_PAD src0_sel:WORD_1
	v_cvt_f32_f16_e32 v62, v47
	v_cvt_f32_f16_sdwa v63, v47 dst_sel:DWORD dst_unused:UNUSED_PAD src0_sel:WORD_1
	v_pk_mul_f32 v[92:93], v[92:93], v[56:57]
	v_pk_mul_f32 v[94:95], v[94:95], v[58:59]
	v_pk_mul_f32 v[96:97], v[96:97], v[60:61]
	v_pk_mul_f32 v[98:99], v[98:99], v[62:63]
	v_cvt_pk_f16_f32 v64, v92, v93
	v_cvt_pk_f16_f32 v65, v94, v95
	v_cvt_pk_f16_f32 v66, v96, v97
	v_cvt_pk_f16_f32 v67, v98, v99
	global_store_dwordx4 v70, v[64:67], s[96:97] offset:1024
	v_accvgpr_read_b32 v44, a132
	v_accvgpr_read_b32 v45, a133
	v_accvgpr_read_b32 v46, a134
	v_accvgpr_read_b32 v47, a135
	v_cvt_f32_f16_e32 v56, v44
	v_cvt_f32_f16_sdwa v57, v44 dst_sel:DWORD dst_unused:UNUSED_PAD src0_sel:WORD_1
	v_cvt_f32_f16_e32 v58, v45
	v_cvt_f32_f16_sdwa v59, v45 dst_sel:DWORD dst_unused:UNUSED_PAD src0_sel:WORD_1
	v_cvt_f32_f16_e32 v60, v46
	v_cvt_f32_f16_sdwa v61, v46 dst_sel:DWORD dst_unused:UNUSED_PAD src0_sel:WORD_1
	v_cvt_f32_f16_e32 v62, v47
	v_cvt_f32_f16_sdwa v63, v47 dst_sel:DWORD dst_unused:UNUSED_PAD src0_sel:WORD_1
	v_pk_mul_f32 v[100:101], v[100:101], v[56:57]
	v_pk_mul_f32 v[102:103], v[102:103], v[58:59]
	v_pk_mul_f32 v[104:105], v[104:105], v[60:61]
	v_pk_mul_f32 v[106:107], v[106:107], v[62:63]
	v_cvt_pk_f16_f32 v48, v100, v101
	v_cvt_pk_f16_f32 v49, v102, v103
	v_cvt_pk_f16_f32 v50, v104, v105
	v_cvt_pk_f16_f32 v51, v106, v107
	global_store_dwordx4 v70, v[48:51], s[96:97] offset:1152
	v_accvgpr_read_b32 v44, a136
	v_accvgpr_read_b32 v45, a137
	v_accvgpr_read_b32 v46, a138
	v_accvgpr_read_b32 v47, a139
	v_cvt_f32_f16_e32 v56, v44
	v_cvt_f32_f16_sdwa v57, v44 dst_sel:DWORD dst_unused:UNUSED_PAD src0_sel:WORD_1
	v_cvt_f32_f16_e32 v58, v45
	v_cvt_f32_f16_sdwa v59, v45 dst_sel:DWORD dst_unused:UNUSED_PAD src0_sel:WORD_1
	v_cvt_f32_f16_e32 v60, v46
	v_cvt_f32_f16_sdwa v61, v46 dst_sel:DWORD dst_unused:UNUSED_PAD src0_sel:WORD_1
	v_cvt_f32_f16_e32 v62, v47
	v_cvt_f32_f16_sdwa v63, v47 dst_sel:DWORD dst_unused:UNUSED_PAD src0_sel:WORD_1
	v_pk_mul_f32 v[108:109], v[108:109], v[56:57]
	v_pk_mul_f32 v[110:111], v[110:111], v[58:59]
	v_pk_mul_f32 v[112:113], v[112:113], v[60:61]
	v_pk_mul_f32 v[114:115], v[114:115], v[62:63]
	v_cvt_pk_f16_f32 v64, v108, v109
	v_cvt_pk_f16_f32 v65, v110, v111
	v_cvt_pk_f16_f32 v66, v112, v113
	v_cvt_pk_f16_f32 v67, v114, v115
	global_store_dwordx4 v70, v[64:67], s[96:97] offset:1280
	v_accvgpr_read_b32 v44, a140
	v_accvgpr_read_b32 v45, a141
	v_accvgpr_read_b32 v46, a142
	v_accvgpr_read_b32 v47, a143
	v_cvt_f32_f16_e32 v56, v44
	v_cvt_f32_f16_sdwa v57, v44 dst_sel:DWORD dst_unused:UNUSED_PAD src0_sel:WORD_1
	v_cvt_f32_f16_e32 v58, v45
	v_cvt_f32_f16_sdwa v59, v45 dst_sel:DWORD dst_unused:UNUSED_PAD src0_sel:WORD_1
	v_cvt_f32_f16_e32 v60, v46
	v_cvt_f32_f16_sdwa v61, v46 dst_sel:DWORD dst_unused:UNUSED_PAD src0_sel:WORD_1
	v_cvt_f32_f16_e32 v62, v47
	v_cvt_f32_f16_sdwa v63, v47 dst_sel:DWORD dst_unused:UNUSED_PAD src0_sel:WORD_1
	v_pk_mul_f32 v[116:117], v[116:117], v[56:57]
	v_pk_mul_f32 v[118:119], v[118:119], v[58:59]
	v_pk_mul_f32 v[120:121], v[120:121], v[60:61]
	v_pk_mul_f32 v[122:123], v[122:123], v[62:63]
	v_cvt_pk_f16_f32 v48, v116, v117
	v_cvt_pk_f16_f32 v49, v118, v119
	v_cvt_pk_f16_f32 v50, v120, v121
	v_cvt_pk_f16_f32 v51, v122, v123
	global_store_dwordx4 v70, v[48:51], s[96:97] offset:1408
	s_mov_b64 exec, s[2:3]
	s_add_i32 s6, s6, 1
	v_accvgpr_read_b32 v27, a160
	global_load_dwordx4 v[124:127], v27, s[96:97] offset:384
	v_accvgpr_read_b32 v28, a161
	global_load_dwordx4 v[128:131], v28, s[96:97] offset:384
	v_accvgpr_read_b32 v29, a162
	global_load_dwordx4 v[132:135], v29, s[96:97] offset:384
	v_accvgpr_read_b32 v30, a163
	global_load_dwordx4 v[136:139], v30, s[96:97] offset:384
	v_accvgpr_read_b32 v27, a164
	global_load_dwordx4 v[140:143], v27, s[96:97] offset:384
	v_accvgpr_read_b32 v28, a165
	global_load_dwordx4 v[144:147], v28, s[96:97] offset:384
	v_accvgpr_read_b32 v29, a166
	global_load_dwordx4 v[148:151], v29, s[96:97] offset:384
	v_accvgpr_read_b32 v30, a167
	global_load_dwordx4 v[152:155], v30, s[96:97] offset:384
	v_accvgpr_read_b32 v27, a168
	global_load_dwordx4 v[156:159], v27, s[96:97] offset:384
	v_accvgpr_read_b32 v28, a169
	global_load_dwordx4 v[160:163], v28, s[96:97] offset:384
	v_accvgpr_read_b32 v29, a170
	global_load_dwordx4 v[164:167], v29, s[96:97] offset:384
	v_accvgpr_read_b32 v30, a171
	global_load_dwordx4 v[168:171], v30, s[96:97] offset:384
	v_accvgpr_read_b32 v27, a172
	global_load_dwordx4 v[172:175], v27, s[96:97] offset:384
	v_accvgpr_read_b32 v28, a173
	global_load_dwordx4 v[176:179], v28, s[96:97] offset:384
	v_accvgpr_read_b32 v29, a174
	global_load_dwordx4 v[180:183], v29, s[96:97] offset:384
	v_accvgpr_read_b32 v30, a175
	global_load_dwordx4 v[184:187], v30, s[96:97] offset:384
	s_waitcnt vmcnt(16)
	v_mfma_f32_4x4x4_16b_f16 v[92:95], a[144:145], a[0:1], 0
	v_mfma_f32_4x4x4_16b_f16 v[96:99], a[144:145], a[8:9], 0
	v_mfma_f32_4x4x4_16b_f16 v[100:103], a[144:145], a[16:17], 0
	v_mfma_f32_4x4x4_16b_f16 v[104:107], a[144:145], a[24:25], 0
	v_mfma_f32_4x4x4_16b_f16 v[108:111], a[144:145], a[32:33], 0
	v_mfma_f32_4x4x4_16b_f16 v[112:115], a[144:145], a[40:41], 0
	v_mfma_f32_4x4x4_16b_f16 v[116:119], a[144:145], a[48:49], 0
	v_mfma_f32_4x4x4_16b_f16 v[120:123], a[144:145], a[56:57], 0
	v_mfma_f32_4x4x4_16b_f16 v[92:95], a[146:147], a[2:3], v[92:95]
	v_mfma_f32_4x4x4_16b_f16 v[96:99], a[146:147], a[10:11], v[96:99]
	v_mfma_f32_4x4x4_16b_f16 v[100:103], a[146:147], a[18:19], v[100:103]
	v_mfma_f32_4x4x4_16b_f16 v[104:107], a[146:147], a[26:27], v[104:107]
	v_mfma_f32_4x4x4_16b_f16 v[108:111], a[146:147], a[34:35], v[108:111]
	v_mfma_f32_4x4x4_16b_f16 v[112:115], a[146:147], a[42:43], v[112:115]
	v_mfma_f32_4x4x4_16b_f16 v[116:119], a[146:147], a[50:51], v[116:119]
	v_mfma_f32_4x4x4_16b_f16 v[120:123], a[146:147], a[58:59], v[120:123]
	v_mfma_f32_4x4x4_16b_f16 v[92:95], a[148:149], a[4:5], v[92:95]
	v_mfma_f32_4x4x4_16b_f16 v[96:99], a[148:149], a[12:13], v[96:99]
	v_mfma_f32_4x4x4_16b_f16 v[100:103], a[148:149], a[20:21], v[100:103]
	v_mfma_f32_4x4x4_16b_f16 v[104:107], a[148:149], a[28:29], v[104:107]
	v_mfma_f32_4x4x4_16b_f16 v[108:111], a[148:149], a[36:37], v[108:111]
	v_mfma_f32_4x4x4_16b_f16 v[112:115], a[148:149], a[44:45], v[112:115]
	v_mfma_f32_4x4x4_16b_f16 v[116:119], a[148:149], a[52:53], v[116:119]
	v_mfma_f32_4x4x4_16b_f16 v[120:123], a[148:149], a[60:61], v[120:123]
	v_mfma_f32_4x4x4_16b_f16 v[92:95], a[150:151], a[6:7], v[92:95]
	v_mfma_f32_4x4x4_16b_f16 v[96:99], a[150:151], a[14:15], v[96:99]
	v_mfma_f32_4x4x4_16b_f16 v[100:103], a[150:151], a[22:23], v[100:103]
	v_mfma_f32_4x4x4_16b_f16 v[104:107], a[150:151], a[30:31], v[104:107]
	v_mfma_f32_4x4x4_16b_f16 v[108:111], a[150:151], a[38:39], v[108:111]
	v_mfma_f32_4x4x4_16b_f16 v[112:115], a[150:151], a[46:47], v[112:115]
	v_mfma_f32_4x4x4_16b_f16 v[116:119], a[150:151], a[54:55], v[116:119]
	v_mfma_f32_4x4x4_16b_f16 v[120:123], a[150:151], a[62:63], v[120:123]
	s_nop 4
	v_permlane32_swap_b32 v92, v108
	v_permlane32_swap_b32 v93, v109
	v_permlane32_swap_b32 v94, v110
	v_permlane32_swap_b32 v95, v111
	v_permlane32_swap_b32 v96, v112
	v_permlane32_swap_b32 v97, v113
	v_permlane32_swap_b32 v98, v114
	v_permlane32_swap_b32 v99, v115
	v_permlane32_swap_b32 v100, v116
	v_permlane32_swap_b32 v101, v117
	v_permlane32_swap_b32 v102, v118
	v_permlane32_swap_b32 v103, v119
	v_permlane32_swap_b32 v104, v120
	v_permlane32_swap_b32 v105, v121
	v_permlane32_swap_b32 v106, v122
	v_permlane32_swap_b32 v107, v123
	v_add_f32_e32 v92, v92, v108
	v_add_f32_e32 v93, v93, v109
	v_add_f32_e32 v94, v94, v110
	v_add_f32_e32 v95, v95, v111
	v_add_f32_e32 v96, v96, v112
	v_add_f32_e32 v97, v97, v113
	v_add_f32_e32 v98, v98, v114
	v_add_f32_e32 v99, v99, v115
	v_add_f32_e32 v100, v100, v116
	v_add_f32_e32 v101, v101, v117
	v_add_f32_e32 v102, v102, v118
	v_add_f32_e32 v103, v103, v119
	v_add_f32_e32 v104, v104, v120
	v_add_f32_e32 v105, v105, v121
	v_add_f32_e32 v106, v106, v122
	v_add_f32_e32 v107, v107, v123
	v_permlane16_swap_b32 v92, v100
	v_permlane16_swap_b32 v93, v101
	v_permlane16_swap_b32 v94, v102
	v_permlane16_swap_b32 v95, v103
	v_permlane16_swap_b32 v96, v104
	v_permlane16_swap_b32 v97, v105
	v_permlane16_swap_b32 v98, v106
	v_permlane16_swap_b32 v99, v107
	v_add_f32_e32 v76, v92, v100
	v_add_f32_e32 v77, v93, v101
	v_add_f32_e32 v78, v94, v102
	v_add_f32_e32 v79, v95, v103
	v_add_f32_e32 v80, v96, v104
	v_add_f32_e32 v81, v97, v105
	v_add_f32_e32 v82, v98, v106
	v_add_f32_e32 v83, v99, v107
	v_mfma_f32_4x4x4_16b_f16 v[92:95], a[144:145], a[64:65], 0
	v_mfma_f32_4x4x4_16b_f16 v[96:99], a[144:145], a[72:73], 0
	v_mfma_f32_4x4x4_16b_f16 v[100:103], a[144:145], a[80:81], 0
	v_mfma_f32_4x4x4_16b_f16 v[104:107], a[144:145], a[88:89], 0
	v_mfma_f32_4x4x4_16b_f16 v[108:111], a[144:145], a[96:97], 0
	v_mfma_f32_4x4x4_16b_f16 v[112:115], a[144:145], a[104:105], 0
	v_mfma_f32_4x4x4_16b_f16 v[116:119], a[144:145], a[112:113], 0
	v_mfma_f32_4x4x4_16b_f16 v[120:123], a[144:145], a[120:121], 0
	v_mfma_f32_4x4x4_16b_f16 v[92:95], a[146:147], a[66:67], v[92:95]
	v_mfma_f32_4x4x4_16b_f16 v[96:99], a[146:147], a[74:75], v[96:99]
	v_mfma_f32_4x4x4_16b_f16 v[100:103], a[146:147], a[82:83], v[100:103]
	v_mfma_f32_4x4x4_16b_f16 v[104:107], a[146:147], a[90:91], v[104:107]
	v_mfma_f32_4x4x4_16b_f16 v[108:111], a[146:147], a[98:99], v[108:111]
	v_mfma_f32_4x4x4_16b_f16 v[112:115], a[146:147], a[106:107], v[112:115]
	v_mfma_f32_4x4x4_16b_f16 v[116:119], a[146:147], a[114:115], v[116:119]
	v_mfma_f32_4x4x4_16b_f16 v[120:123], a[146:147], a[122:123], v[120:123]
	v_mfma_f32_4x4x4_16b_f16 v[92:95], a[148:149], a[68:69], v[92:95]
	v_mfma_f32_4x4x4_16b_f16 v[96:99], a[148:149], a[76:77], v[96:99]
	v_mfma_f32_4x4x4_16b_f16 v[100:103], a[148:149], a[84:85], v[100:103]
	v_mfma_f32_4x4x4_16b_f16 v[104:107], a[148:149], a[92:93], v[104:107]
	v_mfma_f32_4x4x4_16b_f16 v[108:111], a[148:149], a[100:101], v[108:111]
	v_mfma_f32_4x4x4_16b_f16 v[112:115], a[148:149], a[108:109], v[112:115]
	v_mfma_f32_4x4x4_16b_f16 v[116:119], a[148:149], a[116:117], v[116:119]
	v_mfma_f32_4x4x4_16b_f16 v[120:123], a[148:149], a[124:125], v[120:123]
	v_mfma_f32_4x4x4_16b_f16 v[92:95], a[150:151], a[70:71], v[92:95]
	v_mfma_f32_4x4x4_16b_f16 v[96:99], a[150:151], a[78:79], v[96:99]
	v_mfma_f32_4x4x4_16b_f16 v[100:103], a[150:151], a[86:87], v[100:103]
	v_mfma_f32_4x4x4_16b_f16 v[104:107], a[150:151], a[94:95], v[104:107]
	v_mfma_f32_4x4x4_16b_f16 v[108:111], a[150:151], a[102:103], v[108:111]
	v_mfma_f32_4x4x4_16b_f16 v[112:115], a[150:151], a[110:111], v[112:115]
	v_mfma_f32_4x4x4_16b_f16 v[116:119], a[150:151], a[118:119], v[116:119]
	v_mfma_f32_4x4x4_16b_f16 v[120:123], a[150:151], a[126:127], v[120:123]
	s_nop 4
	v_permlane32_swap_b32 v92, v108
	v_permlane32_swap_b32 v93, v109
	v_permlane32_swap_b32 v94, v110
	v_permlane32_swap_b32 v95, v111
	v_permlane32_swap_b32 v96, v112
	v_permlane32_swap_b32 v97, v113
	v_permlane32_swap_b32 v98, v114
	v_permlane32_swap_b32 v99, v115
	v_permlane32_swap_b32 v100, v116
	v_permlane32_swap_b32 v101, v117
	v_permlane32_swap_b32 v102, v118
	v_permlane32_swap_b32 v103, v119
	v_permlane32_swap_b32 v104, v120
	v_permlane32_swap_b32 v105, v121
	v_permlane32_swap_b32 v106, v122
	v_permlane32_swap_b32 v107, v123
	v_add_f32_e32 v92, v92, v108
	v_add_f32_e32 v93, v93, v109
	v_add_f32_e32 v94, v94, v110
	v_add_f32_e32 v95, v95, v111
	v_add_f32_e32 v96, v96, v112
	v_add_f32_e32 v97, v97, v113
	v_add_f32_e32 v98, v98, v114
	v_add_f32_e32 v99, v99, v115
	v_add_f32_e32 v100, v100, v116
	v_add_f32_e32 v101, v101, v117
	v_add_f32_e32 v102, v102, v118
	v_add_f32_e32 v103, v103, v119
	v_add_f32_e32 v104, v104, v120
	v_add_f32_e32 v105, v105, v121
	v_add_f32_e32 v106, v106, v122
	v_add_f32_e32 v107, v107, v123
	v_permlane16_swap_b32 v92, v100
	v_permlane16_swap_b32 v93, v101
	v_permlane16_swap_b32 v94, v102
	v_permlane16_swap_b32 v95, v103
	v_permlane16_swap_b32 v96, v104
	v_permlane16_swap_b32 v97, v105
	v_permlane16_swap_b32 v98, v106
	v_permlane16_swap_b32 v99, v107
	v_add_f32_e32 v84, v92, v100
	v_add_f32_e32 v85, v93, v101
	v_add_f32_e32 v86, v94, v102
	v_add_f32_e32 v87, v95, v103
	v_add_f32_e32 v88, v96, v104
	v_add_f32_e32 v89, v97, v105
	v_add_f32_e32 v90, v98, v106
	v_add_f32_e32 v91, v99, v107
	v_accvgpr_read_b32 v27, a176
	global_load_dwordx4 v[188:191], v27, s[96:97] offset:384
	v_accvgpr_read_b32 v28, a177
	global_load_dwordx4 v[192:195], v28, s[96:97] offset:384
	v_accvgpr_read_b32 v29, a178
	global_load_dwordx4 v[196:199], v29, s[96:97] offset:384
	v_accvgpr_read_b32 v30, a179
	global_load_dwordx4 v[200:203], v30, s[96:97] offset:384
	v_accvgpr_read_b32 v27, a180
	global_load_dwordx4 v[204:207], v27, s[96:97] offset:384
	v_accvgpr_read_b32 v28, a181
	global_load_dwordx4 v[208:211], v28, s[96:97] offset:384
	v_accvgpr_read_b32 v29, a182
	global_load_dwordx4 v[212:215], v29, s[96:97] offset:384
	v_accvgpr_read_b32 v30, a183
	global_load_dwordx4 v[216:219], v30, s[96:97] offset:384
	v_accvgpr_read_b32 v27, a184
	global_load_dwordx4 v[220:223], v27, s[96:97] offset:384
	v_accvgpr_read_b32 v28, a185
	global_load_dwordx4 v[224:227], v28, s[96:97] offset:384
	v_accvgpr_read_b32 v29, a186
	global_load_dwordx4 v[228:231], v29, s[96:97] offset:384
	v_accvgpr_read_b32 v30, a187
	global_load_dwordx4 v[232:235], v30, s[96:97] offset:384
	v_accvgpr_read_b32 v27, a188
	global_load_dwordx4 v[236:239], v27, s[96:97] offset:384
	v_accvgpr_read_b32 v28, a189
	global_load_dwordx4 v[240:243], v28, s[96:97] offset:384
	v_accvgpr_read_b32 v29, a190
	global_load_dwordx4 v[244:247], v29, s[96:97] offset:384
	v_accvgpr_read_b32 v30, a191
	global_load_dwordx4 v[248:251], v30, s[96:97] offset:384
	global_load_dwordx4 a[128:131], v75, s[12:13] offset:512
	global_load_dwordx4 a[132:135], v75, s[12:13] offset:640
	global_load_dwordx4 a[136:139], v75, s[12:13] offset:768
	global_load_dwordx4 a[140:143], v75, s[12:13] offset:896
	s_nop 3
	v_cmp_le_i32_e32 vcc, s7, v26
	v_add_u32_e32 v40, 16, v26
	v_add_u32_e32 v42, 0x80, v26
	v_add_u32_e32 v43, 0x90, v26
	v_cmp_le_i32_e64 s[2:3], s7, v40
	v_cmp_le_i32_e64 s[10:11], s7, v42
	v_cndmask_b32_e32 v76, v76, v72, vcc
	v_cndmask_b32_e32 v77, v77, v72, vcc
	v_cndmask_b32_e32 v78, v78, v72, vcc
	v_cndmask_b32_e32 v79, v79, v72, vcc
	v_cmp_le_i32_e32 vcc, s7, v43
	v_cndmask_b32_e64 v80, v80, v72, s[2:3]
	v_cndmask_b32_e64 v81, v81, v72, s[2:3]
	v_cndmask_b32_e64 v82, v82, v72, s[2:3]
	v_cndmask_b32_e64 v83, v83, v72, s[2:3]
	v_cndmask_b32_e64 v84, v84, v72, s[10:11]
	v_cndmask_b32_e64 v85, v85, v72, s[10:11]
	v_cndmask_b32_e64 v86, v86, v72, s[10:11]
	v_cndmask_b32_e64 v87, v87, v72, s[10:11]
	v_cndmask_b32_e32 v88, v88, v72, vcc
	v_cndmask_b32_e32 v89, v89, v72, vcc
	v_cndmask_b32_e32 v90, v90, v72, vcc
	v_cndmask_b32_e32 v91, v91, v72, vcc
	v_max_f32_e32 v44, v76, v80
	v_max_f32_e32 v45, v77, v81
	v_max_f32_e32 v46, v78, v82
	v_max_f32_e32 v47, v79, v83
	v_max3_f32 v44, v84, v88, v44
	v_max3_f32 v45, v85, v89, v45
	v_max3_f32 v46, v86, v90, v46
	v_max3_f32 v47, v87, v91, v47
	v_max_f32_dpp v44, v44, v44 quad_perm:[1,0,3,2] row_mask:0xf bank_mask:0xf bound_ctrl:1
	v_max_f32_dpp v45, v45, v45 quad_perm:[1,0,3,2] row_mask:0xf bank_mask:0xf bound_ctrl:1
	v_max_f32_dpp v46, v46, v46 quad_perm:[1,0,3,2] row_mask:0xf bank_mask:0xf bound_ctrl:1
	v_max_f32_dpp v47, v47, v47 quad_perm:[1,0,3,2] row_mask:0xf bank_mask:0xf bound_ctrl:1
	v_max_f32_dpp v44, v44, v44 quad_perm:[2,3,0,1] row_mask:0xf bank_mask:0xf bound_ctrl:1
	v_max_f32_dpp v45, v45, v45 quad_perm:[2,3,0,1] row_mask:0xf bank_mask:0xf bound_ctrl:1
	v_max_f32_dpp v46, v46, v46 quad_perm:[2,3,0,1] row_mask:0xf bank_mask:0xf bound_ctrl:1
	v_max_f32_dpp v47, v47, v47 quad_perm:[2,3,0,1] row_mask:0xf bank_mask:0xf bound_ctrl:1
	v_max_f32_dpp v44, v44, v44 row_half_mirror row_mask:0xf bank_mask:0xf bound_ctrl:1
	v_max_f32_dpp v45, v45, v45 row_half_mirror row_mask:0xf bank_mask:0xf bound_ctrl:1
	v_max_f32_dpp v46, v46, v46 row_half_mirror row_mask:0xf bank_mask:0xf bound_ctrl:1
	v_max_f32_dpp v47, v47, v47 row_half_mirror row_mask:0xf bank_mask:0xf bound_ctrl:1
	v_max_f32_dpp v44, v44, v44 row_mirror row_mask:0xf bank_mask:0xf bound_ctrl:1
	v_max_f32_dpp v45, v45, v45 row_mirror row_mask:0xf bank_mask:0xf bound_ctrl:1
	v_max_f32_dpp v46, v46, v46 row_mirror row_mask:0xf bank_mask:0xf bound_ctrl:1
	v_max_f32_dpp v47, v47, v47 row_mirror row_mask:0xf bank_mask:0xf bound_ctrl:1
	s_nop 1
	v_readlane_b32 s2, v44, 0
	v_readlane_b32 s3, v44, 16
	v_readlane_b32 s10, v44, 32
	v_readlane_b32 s11, v44, 48
	v_mov_b32_e32 v48, s3
	v_max_f32_e32 v48, s2, v48
	v_mov_b32_e32 v40, s11
	v_max_f32_e32 v40, s10, v40
	v_max_f32_e32 v48, v48, v40
	v_readlane_b32 s2, v45, 0
	v_readlane_b32 s3, v45, 16
	v_readlane_b32 s10, v45, 32
	v_readlane_b32 s11, v45, 48
	v_mov_b32_e32 v49, s3
	v_max_f32_e32 v49, s2, v49
	v_mov_b32_e32 v40, s11
	v_max_f32_e32 v40, s10, v40
	v_max_f32_e32 v49, v49, v40
	v_readlane_b32 s2, v46, 0
	v_readlane_b32 s3, v46, 16
	v_readlane_b32 s10, v46, 32
	v_readlane_b32 s11, v46, 48
	v_mov_b32_e32 v50, s3
	v_max_f32_e32 v50, s2, v50
	v_mov_b32_e32 v40, s11
	v_max_f32_e32 v40, s10, v40
	v_max_f32_e32 v50, v50, v40
	v_readlane_b32 s2, v47, 0
	v_readlane_b32 s3, v47, 16
	v_readlane_b32 s10, v47, 32
	v_readlane_b32 s11, v47, 48
	v_mov_b32_e32 v51, s3
	v_max_f32_e32 v51, s2, v51
	v_mov_b32_e32 v40, s11
	v_max_f32_e32 v40, s10, v40
	v_max_f32_e32 v51, v51, v40
	v_sub_f32_e32 v76, v76, v48
	v_sub_f32_e32 v77, v77, v49
	v_sub_f32_e32 v78, v78, v50
	v_sub_f32_e32 v79, v79, v51
	v_sub_f32_e32 v80, v80, v48
	v_sub_f32_e32 v81, v81, v49
	v_sub_f32_e32 v82, v82, v50
	v_sub_f32_e32 v83, v83, v51
	v_sub_f32_e32 v84, v84, v48
	v_sub_f32_e32 v85, v85, v49
	v_sub_f32_e32 v86, v86, v50
	v_sub_f32_e32 v87, v87, v51
	v_sub_f32_e32 v88, v88, v48
	v_sub_f32_e32 v89, v89, v49
	v_sub_f32_e32 v90, v90, v50
	v_sub_f32_e32 v91, v91, v51
	v_mul_f32_e32 v76, 0x3fb8aa3b, v76
	v_mul_f32_e32 v77, 0x3fb8aa3b, v77
	v_mul_f32_e32 v78, 0x3fb8aa3b, v78
	v_mul_f32_e32 v79, 0x3fb8aa3b, v79
	v_mul_f32_e32 v80, 0x3fb8aa3b, v80
	v_mul_f32_e32 v81, 0x3fb8aa3b, v81
	v_mul_f32_e32 v82, 0x3fb8aa3b, v82
	v_mul_f32_e32 v83, 0x3fb8aa3b, v83
	v_mul_f32_e32 v84, 0x3fb8aa3b, v84
	v_mul_f32_e32 v85, 0x3fb8aa3b, v85
	v_mul_f32_e32 v86, 0x3fb8aa3b, v86
	v_mul_f32_e32 v87, 0x3fb8aa3b, v87
	v_mul_f32_e32 v88, 0x3fb8aa3b, v88
	v_mul_f32_e32 v89, 0x3fb8aa3b, v89
	v_mul_f32_e32 v90, 0x3fb8aa3b, v90
	v_mul_f32_e32 v91, 0x3fb8aa3b, v91
	v_exp_f32_e32 v76, v76
	v_exp_f32_e32 v77, v77
	v_exp_f32_e32 v78, v78
	v_exp_f32_e32 v79, v79
	v_exp_f32_e32 v80, v80
	v_exp_f32_e32 v81, v81
	v_exp_f32_e32 v82, v82
	v_exp_f32_e32 v83, v83
	v_exp_f32_e32 v84, v84
	v_exp_f32_e32 v85, v85
	v_exp_f32_e32 v86, v86
	v_exp_f32_e32 v87, v87
	v_exp_f32_e32 v88, v88
	v_exp_f32_e32 v89, v89
	v_exp_f32_e32 v90, v90
	v_exp_f32_e32 v91, v91
	s_nop 0
	v_add_f32_e32 v52, 0, v76
	v_add_f32_e32 v53, 0, v77
	v_add_f32_e32 v54, 0, v78
	v_add_f32_e32 v55, 0, v79
	v_add_f32_e32 v52, v52, v80
	v_add_f32_e32 v53, v53, v81
	v_add_f32_e32 v54, v54, v82
	v_add_f32_e32 v55, v55, v83
	v_add_f32_e32 v52, v52, v84
	v_add_f32_e32 v53, v53, v85
	v_add_f32_e32 v54, v54, v86
	v_add_f32_e32 v55, v55, v87
	v_add_f32_e32 v52, v52, v88
	v_add_f32_e32 v53, v53, v89
	v_add_f32_e32 v54, v54, v90
	v_add_f32_e32 v55, v55, v91
	v_add_f32_dpp v52, v52, v52 quad_perm:[1,0,3,2] row_mask:0xf bank_mask:0xf bound_ctrl:1
	v_add_f32_dpp v53, v53, v53 quad_perm:[1,0,3,2] row_mask:0xf bank_mask:0xf bound_ctrl:1
	v_add_f32_dpp v54, v54, v54 quad_perm:[1,0,3,2] row_mask:0xf bank_mask:0xf bound_ctrl:1
	v_add_f32_dpp v55, v55, v55 quad_perm:[1,0,3,2] row_mask:0xf bank_mask:0xf bound_ctrl:1
	v_add_f32_dpp v52, v52, v52 quad_perm:[2,3,0,1] row_mask:0xf bank_mask:0xf bound_ctrl:1
	v_add_f32_dpp v53, v53, v53 quad_perm:[2,3,0,1] row_mask:0xf bank_mask:0xf bound_ctrl:1
	v_add_f32_dpp v54, v54, v54 quad_perm:[2,3,0,1] row_mask:0xf bank_mask:0xf bound_ctrl:1
	v_add_f32_dpp v55, v55, v55 quad_perm:[2,3,0,1] row_mask:0xf bank_mask:0xf bound_ctrl:1
	v_add_f32_dpp v52, v52, v52 row_half_mirror row_mask:0xf bank_mask:0xf bound_ctrl:1
	v_add_f32_dpp v53, v53, v53 row_half_mirror row_mask:0xf bank_mask:0xf bound_ctrl:1
	v_add_f32_dpp v54, v54, v54 row_half_mirror row_mask:0xf bank_mask:0xf bound_ctrl:1
	v_add_f32_dpp v55, v55, v55 row_half_mirror row_mask:0xf bank_mask:0xf bound_ctrl:1
	v_add_f32_dpp v52, v52, v52 row_mirror row_mask:0xf bank_mask:0xf bound_ctrl:1
	v_add_f32_dpp v53, v53, v53 row_mirror row_mask:0xf bank_mask:0xf bound_ctrl:1
	v_add_f32_dpp v54, v54, v54 row_mirror row_mask:0xf bank_mask:0xf bound_ctrl:1
	v_add_f32_dpp v55, v55, v55 row_mirror row_mask:0xf bank_mask:0xf bound_ctrl:1
	s_nop 1
	v_readlane_b32 s2, v52, 0
	v_readlane_b32 s3, v52, 16
	v_readlane_b32 s10, v52, 32
	v_readlane_b32 s11, v52, 48
	v_mov_b32_e32 v56, s3
	v_add_f32_e32 v56, s2, v56
	v_mov_b32_e32 v40, s11
	v_add_f32_e32 v40, s10, v40
	v_add_f32_e32 v56, v56, v40
	v_readlane_b32 s2, v53, 0
	v_readlane_b32 s3, v53, 16
	v_readlane_b32 s10, v53, 32
	v_readlane_b32 s11, v53, 48
	v_mov_b32_e32 v57, s3
	v_add_f32_e32 v57, s2, v57
	v_mov_b32_e32 v40, s11
	v_add_f32_e32 v40, s10, v40
	v_add_f32_e32 v57, v57, v40
	v_readlane_b32 s2, v54, 0
	v_readlane_b32 s3, v54, 16
	v_readlane_b32 s10, v54, 32
	v_readlane_b32 s11, v54, 48
	v_mov_b32_e32 v58, s3
	v_add_f32_e32 v58, s2, v58
	v_mov_b32_e32 v40, s11
	v_add_f32_e32 v40, s10, v40
	v_add_f32_e32 v58, v58, v40
	v_readlane_b32 s2, v55, 0
	v_readlane_b32 s3, v55, 16
	v_readlane_b32 s10, v55, 32
	v_readlane_b32 s11, v55, 48
	v_mov_b32_e32 v59, s3
	v_add_f32_e32 v59, s2, v59
	v_mov_b32_e32 v40, s11
	v_add_f32_e32 v40, s10, v40
	v_add_f32_e32 v59, v59, v40
	v_div_scale_f32 v60, s[2:3], v56, v56, 1.0
	v_rcp_f32_e32 v61, v60
	s_nop 0
	v_fma_f32 v62, -v60, v61, 1.0
	v_fmac_f32_e32 v61, v62, v61
	v_div_scale_f32 v62, vcc, 1.0, v56, 1.0
	v_mul_f32_e32 v63, v62, v61
	v_fma_f32 v64, -v60, v63, v62
	v_fmac_f32_e32 v63, v64, v61
	v_fma_f32 v60, -v60, v63, v62
	s_nop 0
	v_div_fmas_f32 v60, v60, v61, v63
	v_div_fixup_f32 v56, v60, v56, 1.0
	v_div_scale_f32 v60, s[2:3], v57, v57, 1.0
	v_rcp_f32_e32 v61, v60
	s_nop 0
	v_fma_f32 v62, -v60, v61, 1.0
	v_fmac_f32_e32 v61, v62, v61
	v_div_scale_f32 v62, vcc, 1.0, v57, 1.0
	v_mul_f32_e32 v63, v62, v61
	v_fma_f32 v64, -v60, v63, v62
	v_fmac_f32_e32 v63, v64, v61
	v_fma_f32 v60, -v60, v63, v62
	s_nop 0
	v_div_fmas_f32 v60, v60, v61, v63
	v_div_fixup_f32 v57, v60, v57, 1.0
	v_div_scale_f32 v60, s[2:3], v58, v58, 1.0
	v_rcp_f32_e32 v61, v60
	s_nop 0
	v_fma_f32 v62, -v60, v61, 1.0
	v_fmac_f32_e32 v61, v62, v61
	v_div_scale_f32 v62, vcc, 1.0, v58, 1.0
	v_mul_f32_e32 v63, v62, v61
	v_fma_f32 v64, -v60, v63, v62
	v_fmac_f32_e32 v63, v64, v61
	v_fma_f32 v60, -v60, v63, v62
	s_nop 0
	v_div_fmas_f32 v60, v60, v61, v63
	v_div_fixup_f32 v58, v60, v58, 1.0
	v_div_scale_f32 v60, s[2:3], v59, v59, 1.0
	v_rcp_f32_e32 v61, v60
	s_nop 0
	v_fma_f32 v62, -v60, v61, 1.0
	v_fmac_f32_e32 v61, v62, v61
	v_div_scale_f32 v62, vcc, 1.0, v59, 1.0
	v_mul_f32_e32 v63, v62, v61
	v_fma_f32 v64, -v60, v63, v62
	v_fmac_f32_e32 v63, v64, v61
	v_fma_f32 v60, -v60, v63, v62
	s_nop 0
	v_div_fmas_f32 v60, v60, v61, v63
	v_div_fixup_f32 v59, v60, v59, 1.0
	v_mul_f32_e32 v76, v76, v56
	v_mul_f32_e32 v77, v77, v57
	v_mul_f32_e32 v78, v78, v58
	v_mul_f32_e32 v79, v79, v59
	v_mul_f32_e32 v80, v80, v56
	v_mul_f32_e32 v81, v81, v57
	v_mul_f32_e32 v82, v82, v58
	v_mul_f32_e32 v83, v83, v59
	v_mul_f32_e32 v84, v84, v56
	v_mul_f32_e32 v85, v85, v57
	v_mul_f32_e32 v86, v86, v58
	v_mul_f32_e32 v87, v87, v59
	v_mul_f32_e32 v88, v88, v56
	v_mul_f32_e32 v89, v89, v57
	v_mul_f32_e32 v90, v90, v58
	v_mul_f32_e32 v91, v91, v59
	ds_write_b128 v73, v[76:79] offset:0
	ds_write_b128 v73, v[80:83] offset:256
	ds_write_b128 v73, v[84:87] offset:2048
	ds_write_b128 v73, v[88:91] offset:2304
	s_waitcnt vmcnt(20)
	ds_read_b128 v[44:47], v74 offset:0
	ds_read_b128 v[48:51], v74 offset:128
	ds_read_b128 v[52:55], v74 offset:256
	s_waitcnt lgkmcnt(2)
	v_cvt_f32_f16_e32 v56, v124
	v_cvt_f32_f16_sdwa v57, v124 dst_sel:DWORD dst_unused:UNUSED_PAD src0_sel:WORD_1
	v_cvt_f32_f16_e32 v58, v125
	v_cvt_f32_f16_sdwa v59, v125 dst_sel:DWORD dst_unused:UNUSED_PAD src0_sel:WORD_1
	v_cvt_f32_f16_e32 v60, v126
	v_cvt_f32_f16_sdwa v61, v126 dst_sel:DWORD dst_unused:UNUSED_PAD src0_sel:WORD_1
	v_cvt_f32_f16_e32 v62, v127
	v_cvt_f32_f16_sdwa v63, v127 dst_sel:DWORD dst_unused:UNUSED_PAD src0_sel:WORD_1
	v_pk_mul_f32 v[92:93], v[44:45], v[56:57] op_sel_hi:[0,1]
	v_pk_mul_f32 v[94:95], v[44:45], v[58:59] op_sel_hi:[0,1]
	v_pk_mul_f32 v[96:97], v[44:45], v[60:61] op_sel_hi:[0,1]
	v_pk_mul_f32 v[98:99], v[44:45], v[62:63] op_sel_hi:[0,1]
	v_pk_mul_f32 v[100:101], v[44:45], v[56:57] op_sel:[1,0] op_sel_hi:[1,1]
	v_pk_mul_f32 v[102:103], v[44:45], v[58:59] op_sel:[1,0] op_sel_hi:[1,1]
	v_pk_mul_f32 v[104:105], v[44:45], v[60:61] op_sel:[1,0] op_sel_hi:[1,1]
	v_pk_mul_f32 v[106:107], v[44:45], v[62:63] op_sel:[1,0] op_sel_hi:[1,1]
	v_pk_mul_f32 v[108:109], v[46:47], v[56:57] op_sel_hi:[0,1]
	v_pk_mul_f32 v[110:111], v[46:47], v[58:59] op_sel_hi:[0,1]
	v_pk_mul_f32 v[112:113], v[46:47], v[60:61] op_sel_hi:[0,1]
	v_pk_mul_f32 v[114:115], v[46:47], v[62:63] op_sel_hi:[0,1]
	v_pk_mul_f32 v[116:117], v[46:47], v[56:57] op_sel:[1,0] op_sel_hi:[1,1]
	v_pk_mul_f32 v[118:119], v[46:47], v[58:59] op_sel:[1,0] op_sel_hi:[1,1]
	v_pk_mul_f32 v[120:121], v[46:47], v[60:61] op_sel:[1,0] op_sel_hi:[1,1]
	v_pk_mul_f32 v[122:123], v[46:47], v[62:63] op_sel:[1,0] op_sel_hi:[1,1]
	ds_read_b128 v[44:47], v74 offset:384
	s_waitcnt lgkmcnt(2)
	v_cvt_f32_f16_e32 v56, v128
	v_cvt_f32_f16_sdwa v57, v128 dst_sel:DWORD dst_unused:UNUSED_PAD src0_sel:WORD_1
	v_cvt_f32_f16_e32 v58, v129
	v_cvt_f32_f16_sdwa v59, v129 dst_sel:DWORD dst_unused:UNUSED_PAD src0_sel:WORD_1
	v_cvt_f32_f16_e32 v60, v130
	v_cvt_f32_f16_sdwa v61, v130 dst_sel:DWORD dst_unused:UNUSED_PAD src0_sel:WORD_1
	v_cvt_f32_f16_e32 v62, v131
	v_cvt_f32_f16_sdwa v63, v131 dst_sel:DWORD dst_unused:UNUSED_PAD src0_sel:WORD_1
	v_pk_fma_f32 v[92:93], v[48:49], v[56:57], v[92:93] op_sel_hi:[0,1,1]
	v_pk_fma_f32 v[94:95], v[48:49], v[58:59], v[94:95] op_sel_hi:[0,1,1]
	v_pk_fma_f32 v[96:97], v[48:49], v[60:61], v[96:97] op_sel_hi:[0,1,1]
	v_pk_fma_f32 v[98:99], v[48:49], v[62:63], v[98:99] op_sel_hi:[0,1,1]
	v_pk_fma_f32 v[100:101], v[48:49], v[56:57], v[100:101] op_sel:[1,0,0] op_sel_hi:[1,1,1]
	v_pk_fma_f32 v[102:103], v[48:49], v[58:59], v[102:103] op_sel:[1,0,0] op_sel_hi:[1,1,1]
	v_pk_fma_f32 v[104:105], v[48:49], v[60:61], v[104:105] op_sel:[1,0,0] op_sel_hi:[1,1,1]
	v_pk_fma_f32 v[106:107], v[48:49], v[62:63], v[106:107] op_sel:[1,0,0] op_sel_hi:[1,1,1]
	v_pk_fma_f32 v[108:109], v[50:51], v[56:57], v[108:109] op_sel_hi:[0,1,1]
	v_pk_fma_f32 v[110:111], v[50:51], v[58:59], v[110:111] op_sel_hi:[0,1,1]
	v_pk_fma_f32 v[112:113], v[50:51], v[60:61], v[112:113] op_sel_hi:[0,1,1]
	v_pk_fma_f32 v[114:115], v[50:51], v[62:63], v[114:115] op_sel_hi:[0,1,1]
	v_pk_fma_f32 v[116:117], v[50:51], v[56:57], v[116:117] op_sel:[1,0,0] op_sel_hi:[1,1,1]
	v_pk_fma_f32 v[118:119], v[50:51], v[58:59], v[118:119] op_sel:[1,0,0] op_sel_hi:[1,1,1]
	v_pk_fma_f32 v[120:121], v[50:51], v[60:61], v[120:121] op_sel:[1,0,0] op_sel_hi:[1,1,1]
	v_pk_fma_f32 v[122:123], v[50:51], v[62:63], v[122:123] op_sel:[1,0,0] op_sel_hi:[1,1,1]
	ds_read_b128 v[48:51], v74 offset:512
	s_waitcnt lgkmcnt(2)
	v_cvt_f32_f16_e32 v56, v132
	v_cvt_f32_f16_sdwa v57, v132 dst_sel:DWORD dst_unused:UNUSED_PAD src0_sel:WORD_1
	v_cvt_f32_f16_e32 v58, v133
	v_cvt_f32_f16_sdwa v59, v133 dst_sel:DWORD dst_unused:UNUSED_PAD src0_sel:WORD_1
	v_cvt_f32_f16_e32 v60, v134
	v_cvt_f32_f16_sdwa v61, v134 dst_sel:DWORD dst_unused:UNUSED_PAD src0_sel:WORD_1
	v_cvt_f32_f16_e32 v62, v135
	v_cvt_f32_f16_sdwa v63, v135 dst_sel:DWORD dst_unused:UNUSED_PAD src0_sel:WORD_1
	v_pk_fma_f32 v[92:93], v[52:53], v[56:57], v[92:93] op_sel_hi:[0,1,1]
	v_pk_fma_f32 v[94:95], v[52:53], v[58:59], v[94:95] op_sel_hi:[0,1,1]
	v_pk_fma_f32 v[96:97], v[52:53], v[60:61], v[96:97] op_sel_hi:[0,1,1]
	v_pk_fma_f32 v[98:99], v[52:53], v[62:63], v[98:99] op_sel_hi:[0,1,1]
	v_pk_fma_f32 v[100:101], v[52:53], v[56:57], v[100:101] op_sel:[1,0,0] op_sel_hi:[1,1,1]
	v_pk_fma_f32 v[102:103], v[52:53], v[58:59], v[102:103] op_sel:[1,0,0] op_sel_hi:[1,1,1]
	v_pk_fma_f32 v[104:105], v[52:53], v[60:61], v[104:105] op_sel:[1,0,0] op_sel_hi:[1,1,1]
	v_pk_fma_f32 v[106:107], v[52:53], v[62:63], v[106:107] op_sel:[1,0,0] op_sel_hi:[1,1,1]
	v_pk_fma_f32 v[108:109], v[54:55], v[56:57], v[108:109] op_sel_hi:[0,1,1]
	v_pk_fma_f32 v[110:111], v[54:55], v[58:59], v[110:111] op_sel_hi:[0,1,1]
	v_pk_fma_f32 v[112:113], v[54:55], v[60:61], v[112:113] op_sel_hi:[0,1,1]
	v_pk_fma_f32 v[114:115], v[54:55], v[62:63], v[114:115] op_sel_hi:[0,1,1]
	v_pk_fma_f32 v[116:117], v[54:55], v[56:57], v[116:117] op_sel:[1,0,0] op_sel_hi:[1,1,1]
	v_pk_fma_f32 v[118:119], v[54:55], v[58:59], v[118:119] op_sel:[1,0,0] op_sel_hi:[1,1,1]
	v_pk_fma_f32 v[120:121], v[54:55], v[60:61], v[120:121] op_sel:[1,0,0] op_sel_hi:[1,1,1]
	v_pk_fma_f32 v[122:123], v[54:55], v[62:63], v[122:123] op_sel:[1,0,0] op_sel_hi:[1,1,1]
	ds_read_b128 v[52:55], v74 offset:640
	s_waitcnt lgkmcnt(2)
	v_cvt_f32_f16_e32 v56, v136
	v_cvt_f32_f16_sdwa v57, v136 dst_sel:DWORD dst_unused:UNUSED_PAD src0_sel:WORD_1
	v_cvt_f32_f16_e32 v58, v137
	v_cvt_f32_f16_sdwa v59, v137 dst_sel:DWORD dst_unused:UNUSED_PAD src0_sel:WORD_1
	v_cvt_f32_f16_e32 v60, v138
	v_cvt_f32_f16_sdwa v61, v138 dst_sel:DWORD dst_unused:UNUSED_PAD src0_sel:WORD_1
	v_cvt_f32_f16_e32 v62, v139
	v_cvt_f32_f16_sdwa v63, v139 dst_sel:DWORD dst_unused:UNUSED_PAD src0_sel:WORD_1
	v_pk_fma_f32 v[92:93], v[44:45], v[56:57], v[92:93] op_sel_hi:[0,1,1]
	v_pk_fma_f32 v[94:95], v[44:45], v[58:59], v[94:95] op_sel_hi:[0,1,1]
	v_pk_fma_f32 v[96:97], v[44:45], v[60:61], v[96:97] op_sel_hi:[0,1,1]
	v_pk_fma_f32 v[98:99], v[44:45], v[62:63], v[98:99] op_sel_hi:[0,1,1]
	v_pk_fma_f32 v[100:101], v[44:45], v[56:57], v[100:101] op_sel:[1,0,0] op_sel_hi:[1,1,1]
	v_pk_fma_f32 v[102:103], v[44:45], v[58:59], v[102:103] op_sel:[1,0,0] op_sel_hi:[1,1,1]
	v_pk_fma_f32 v[104:105], v[44:45], v[60:61], v[104:105] op_sel:[1,0,0] op_sel_hi:[1,1,1]
	v_pk_fma_f32 v[106:107], v[44:45], v[62:63], v[106:107] op_sel:[1,0,0] op_sel_hi:[1,1,1]
	v_pk_fma_f32 v[108:109], v[46:47], v[56:57], v[108:109] op_sel_hi:[0,1,1]
	v_pk_fma_f32 v[110:111], v[46:47], v[58:59], v[110:111] op_sel_hi:[0,1,1]
	v_pk_fma_f32 v[112:113], v[46:47], v[60:61], v[112:113] op_sel_hi:[0,1,1]
	v_pk_fma_f32 v[114:115], v[46:47], v[62:63], v[114:115] op_sel_hi:[0,1,1]
	v_pk_fma_f32 v[116:117], v[46:47], v[56:57], v[116:117] op_sel:[1,0,0] op_sel_hi:[1,1,1]
	v_pk_fma_f32 v[118:119], v[46:47], v[58:59], v[118:119] op_sel:[1,0,0] op_sel_hi:[1,1,1]
	v_pk_fma_f32 v[120:121], v[46:47], v[60:61], v[120:121] op_sel:[1,0,0] op_sel_hi:[1,1,1]
	v_pk_fma_f32 v[122:123], v[46:47], v[62:63], v[122:123] op_sel:[1,0,0] op_sel_hi:[1,1,1]
	ds_read_b128 v[44:47], v74 offset:768
	s_waitcnt lgkmcnt(2)
	v_cvt_f32_f16_e32 v56, v140
	v_cvt_f32_f16_sdwa v57, v140 dst_sel:DWORD dst_unused:UNUSED_PAD src0_sel:WORD_1
	v_cvt_f32_f16_e32 v58, v141
	v_cvt_f32_f16_sdwa v59, v141 dst_sel:DWORD dst_unused:UNUSED_PAD src0_sel:WORD_1
	v_cvt_f32_f16_e32 v60, v142
	v_cvt_f32_f16_sdwa v61, v142 dst_sel:DWORD dst_unused:UNUSED_PAD src0_sel:WORD_1
	v_cvt_f32_f16_e32 v62, v143
	v_cvt_f32_f16_sdwa v63, v143 dst_sel:DWORD dst_unused:UNUSED_PAD src0_sel:WORD_1
	v_pk_fma_f32 v[92:93], v[48:49], v[56:57], v[92:93] op_sel_hi:[0,1,1]
	v_pk_fma_f32 v[94:95], v[48:49], v[58:59], v[94:95] op_sel_hi:[0,1,1]
	v_pk_fma_f32 v[96:97], v[48:49], v[60:61], v[96:97] op_sel_hi:[0,1,1]
	v_pk_fma_f32 v[98:99], v[48:49], v[62:63], v[98:99] op_sel_hi:[0,1,1]
	v_pk_fma_f32 v[100:101], v[48:49], v[56:57], v[100:101] op_sel:[1,0,0] op_sel_hi:[1,1,1]
	v_pk_fma_f32 v[102:103], v[48:49], v[58:59], v[102:103] op_sel:[1,0,0] op_sel_hi:[1,1,1]
	v_pk_fma_f32 v[104:105], v[48:49], v[60:61], v[104:105] op_sel:[1,0,0] op_sel_hi:[1,1,1]
	v_pk_fma_f32 v[106:107], v[48:49], v[62:63], v[106:107] op_sel:[1,0,0] op_sel_hi:[1,1,1]
	v_pk_fma_f32 v[108:109], v[50:51], v[56:57], v[108:109] op_sel_hi:[0,1,1]
	v_pk_fma_f32 v[110:111], v[50:51], v[58:59], v[110:111] op_sel_hi:[0,1,1]
	v_pk_fma_f32 v[112:113], v[50:51], v[60:61], v[112:113] op_sel_hi:[0,1,1]
	v_pk_fma_f32 v[114:115], v[50:51], v[62:63], v[114:115] op_sel_hi:[0,1,1]
	v_pk_fma_f32 v[116:117], v[50:51], v[56:57], v[116:117] op_sel:[1,0,0] op_sel_hi:[1,1,1]
	v_pk_fma_f32 v[118:119], v[50:51], v[58:59], v[118:119] op_sel:[1,0,0] op_sel_hi:[1,1,1]
	v_pk_fma_f32 v[120:121], v[50:51], v[60:61], v[120:121] op_sel:[1,0,0] op_sel_hi:[1,1,1]
	v_pk_fma_f32 v[122:123], v[50:51], v[62:63], v[122:123] op_sel:[1,0,0] op_sel_hi:[1,1,1]
	ds_read_b128 v[48:51], v74 offset:896
	s_waitcnt lgkmcnt(2)
	v_cvt_f32_f16_e32 v56, v144
	v_cvt_f32_f16_sdwa v57, v144 dst_sel:DWORD dst_unused:UNUSED_PAD src0_sel:WORD_1
	v_cvt_f32_f16_e32 v58, v145
	v_cvt_f32_f16_sdwa v59, v145 dst_sel:DWORD dst_unused:UNUSED_PAD src0_sel:WORD_1
	v_cvt_f32_f16_e32 v60, v146
	v_cvt_f32_f16_sdwa v61, v146 dst_sel:DWORD dst_unused:UNUSED_PAD src0_sel:WORD_1
	v_cvt_f32_f16_e32 v62, v147
	v_cvt_f32_f16_sdwa v63, v147 dst_sel:DWORD dst_unused:UNUSED_PAD src0_sel:WORD_1
	v_pk_fma_f32 v[92:93], v[52:53], v[56:57], v[92:93] op_sel_hi:[0,1,1]
	v_pk_fma_f32 v[94:95], v[52:53], v[58:59], v[94:95] op_sel_hi:[0,1,1]
	v_pk_fma_f32 v[96:97], v[52:53], v[60:61], v[96:97] op_sel_hi:[0,1,1]
	v_pk_fma_f32 v[98:99], v[52:53], v[62:63], v[98:99] op_sel_hi:[0,1,1]
	v_pk_fma_f32 v[100:101], v[52:53], v[56:57], v[100:101] op_sel:[1,0,0] op_sel_hi:[1,1,1]
	v_pk_fma_f32 v[102:103], v[52:53], v[58:59], v[102:103] op_sel:[1,0,0] op_sel_hi:[1,1,1]
	v_pk_fma_f32 v[104:105], v[52:53], v[60:61], v[104:105] op_sel:[1,0,0] op_sel_hi:[1,1,1]
	v_pk_fma_f32 v[106:107], v[52:53], v[62:63], v[106:107] op_sel:[1,0,0] op_sel_hi:[1,1,1]
	v_pk_fma_f32 v[108:109], v[54:55], v[56:57], v[108:109] op_sel_hi:[0,1,1]
	v_pk_fma_f32 v[110:111], v[54:55], v[58:59], v[110:111] op_sel_hi:[0,1,1]
	v_pk_fma_f32 v[112:113], v[54:55], v[60:61], v[112:113] op_sel_hi:[0,1,1]
	v_pk_fma_f32 v[114:115], v[54:55], v[62:63], v[114:115] op_sel_hi:[0,1,1]
	v_pk_fma_f32 v[116:117], v[54:55], v[56:57], v[116:117] op_sel:[1,0,0] op_sel_hi:[1,1,1]
	v_pk_fma_f32 v[118:119], v[54:55], v[58:59], v[118:119] op_sel:[1,0,0] op_sel_hi:[1,1,1]
	v_pk_fma_f32 v[120:121], v[54:55], v[60:61], v[120:121] op_sel:[1,0,0] op_sel_hi:[1,1,1]
	v_pk_fma_f32 v[122:123], v[54:55], v[62:63], v[122:123] op_sel:[1,0,0] op_sel_hi:[1,1,1]
	ds_read_b128 v[52:55], v74 offset:1024
	s_waitcnt lgkmcnt(2)
	v_cvt_f32_f16_e32 v56, v148
	v_cvt_f32_f16_sdwa v57, v148 dst_sel:DWORD dst_unused:UNUSED_PAD src0_sel:WORD_1
	v_cvt_f32_f16_e32 v58, v149
	v_cvt_f32_f16_sdwa v59, v149 dst_sel:DWORD dst_unused:UNUSED_PAD src0_sel:WORD_1
	v_cvt_f32_f16_e32 v60, v150
	v_cvt_f32_f16_sdwa v61, v150 dst_sel:DWORD dst_unused:UNUSED_PAD src0_sel:WORD_1
	v_cvt_f32_f16_e32 v62, v151
	v_cvt_f32_f16_sdwa v63, v151 dst_sel:DWORD dst_unused:UNUSED_PAD src0_sel:WORD_1
	v_pk_fma_f32 v[92:93], v[44:45], v[56:57], v[92:93] op_sel_hi:[0,1,1]
	v_pk_fma_f32 v[94:95], v[44:45], v[58:59], v[94:95] op_sel_hi:[0,1,1]
	v_pk_fma_f32 v[96:97], v[44:45], v[60:61], v[96:97] op_sel_hi:[0,1,1]
	v_pk_fma_f32 v[98:99], v[44:45], v[62:63], v[98:99] op_sel_hi:[0,1,1]
	v_pk_fma_f32 v[100:101], v[44:45], v[56:57], v[100:101] op_sel:[1,0,0] op_sel_hi:[1,1,1]
	v_pk_fma_f32 v[102:103], v[44:45], v[58:59], v[102:103] op_sel:[1,0,0] op_sel_hi:[1,1,1]
	v_pk_fma_f32 v[104:105], v[44:45], v[60:61], v[104:105] op_sel:[1,0,0] op_sel_hi:[1,1,1]
	v_pk_fma_f32 v[106:107], v[44:45], v[62:63], v[106:107] op_sel:[1,0,0] op_sel_hi:[1,1,1]
	v_pk_fma_f32 v[108:109], v[46:47], v[56:57], v[108:109] op_sel_hi:[0,1,1]
	v_pk_fma_f32 v[110:111], v[46:47], v[58:59], v[110:111] op_sel_hi:[0,1,1]
	v_pk_fma_f32 v[112:113], v[46:47], v[60:61], v[112:113] op_sel_hi:[0,1,1]
	v_pk_fma_f32 v[114:115], v[46:47], v[62:63], v[114:115] op_sel_hi:[0,1,1]
	v_pk_fma_f32 v[116:117], v[46:47], v[56:57], v[116:117] op_sel:[1,0,0] op_sel_hi:[1,1,1]
	v_pk_fma_f32 v[118:119], v[46:47], v[58:59], v[118:119] op_sel:[1,0,0] op_sel_hi:[1,1,1]
	v_pk_fma_f32 v[120:121], v[46:47], v[60:61], v[120:121] op_sel:[1,0,0] op_sel_hi:[1,1,1]
	v_pk_fma_f32 v[122:123], v[46:47], v[62:63], v[122:123] op_sel:[1,0,0] op_sel_hi:[1,1,1]
	ds_read_b128 v[44:47], v74 offset:1152
	s_waitcnt lgkmcnt(2)
	v_cvt_f32_f16_e32 v56, v152
	v_cvt_f32_f16_sdwa v57, v152 dst_sel:DWORD dst_unused:UNUSED_PAD src0_sel:WORD_1
	v_cvt_f32_f16_e32 v58, v153
	v_cvt_f32_f16_sdwa v59, v153 dst_sel:DWORD dst_unused:UNUSED_PAD src0_sel:WORD_1
	v_cvt_f32_f16_e32 v60, v154
	v_cvt_f32_f16_sdwa v61, v154 dst_sel:DWORD dst_unused:UNUSED_PAD src0_sel:WORD_1
	v_cvt_f32_f16_e32 v62, v155
	v_cvt_f32_f16_sdwa v63, v155 dst_sel:DWORD dst_unused:UNUSED_PAD src0_sel:WORD_1
	v_pk_fma_f32 v[92:93], v[48:49], v[56:57], v[92:93] op_sel_hi:[0,1,1]
	v_pk_fma_f32 v[94:95], v[48:49], v[58:59], v[94:95] op_sel_hi:[0,1,1]
	v_pk_fma_f32 v[96:97], v[48:49], v[60:61], v[96:97] op_sel_hi:[0,1,1]
	v_pk_fma_f32 v[98:99], v[48:49], v[62:63], v[98:99] op_sel_hi:[0,1,1]
	v_pk_fma_f32 v[100:101], v[48:49], v[56:57], v[100:101] op_sel:[1,0,0] op_sel_hi:[1,1,1]
	v_pk_fma_f32 v[102:103], v[48:49], v[58:59], v[102:103] op_sel:[1,0,0] op_sel_hi:[1,1,1]
	v_pk_fma_f32 v[104:105], v[48:49], v[60:61], v[104:105] op_sel:[1,0,0] op_sel_hi:[1,1,1]
	v_pk_fma_f32 v[106:107], v[48:49], v[62:63], v[106:107] op_sel:[1,0,0] op_sel_hi:[1,1,1]
	v_pk_fma_f32 v[108:109], v[50:51], v[56:57], v[108:109] op_sel_hi:[0,1,1]
	v_pk_fma_f32 v[110:111], v[50:51], v[58:59], v[110:111] op_sel_hi:[0,1,1]
	v_pk_fma_f32 v[112:113], v[50:51], v[60:61], v[112:113] op_sel_hi:[0,1,1]
	v_pk_fma_f32 v[114:115], v[50:51], v[62:63], v[114:115] op_sel_hi:[0,1,1]
	v_pk_fma_f32 v[116:117], v[50:51], v[56:57], v[116:117] op_sel:[1,0,0] op_sel_hi:[1,1,1]
	v_pk_fma_f32 v[118:119], v[50:51], v[58:59], v[118:119] op_sel:[1,0,0] op_sel_hi:[1,1,1]
	v_pk_fma_f32 v[120:121], v[50:51], v[60:61], v[120:121] op_sel:[1,0,0] op_sel_hi:[1,1,1]
	v_pk_fma_f32 v[122:123], v[50:51], v[62:63], v[122:123] op_sel:[1,0,0] op_sel_hi:[1,1,1]
	ds_read_b128 v[48:51], v74 offset:1280
	s_waitcnt lgkmcnt(2)
	v_cvt_f32_f16_e32 v56, v156
	v_cvt_f32_f16_sdwa v57, v156 dst_sel:DWORD dst_unused:UNUSED_PAD src0_sel:WORD_1
	v_cvt_f32_f16_e32 v58, v157
	v_cvt_f32_f16_sdwa v59, v157 dst_sel:DWORD dst_unused:UNUSED_PAD src0_sel:WORD_1
	v_cvt_f32_f16_e32 v60, v158
	v_cvt_f32_f16_sdwa v61, v158 dst_sel:DWORD dst_unused:UNUSED_PAD src0_sel:WORD_1
	v_cvt_f32_f16_e32 v62, v159
	v_cvt_f32_f16_sdwa v63, v159 dst_sel:DWORD dst_unused:UNUSED_PAD src0_sel:WORD_1
	v_pk_fma_f32 v[92:93], v[52:53], v[56:57], v[92:93] op_sel_hi:[0,1,1]
	v_pk_fma_f32 v[94:95], v[52:53], v[58:59], v[94:95] op_sel_hi:[0,1,1]
	v_pk_fma_f32 v[96:97], v[52:53], v[60:61], v[96:97] op_sel_hi:[0,1,1]
	v_pk_fma_f32 v[98:99], v[52:53], v[62:63], v[98:99] op_sel_hi:[0,1,1]
	v_pk_fma_f32 v[100:101], v[52:53], v[56:57], v[100:101] op_sel:[1,0,0] op_sel_hi:[1,1,1]
	v_pk_fma_f32 v[102:103], v[52:53], v[58:59], v[102:103] op_sel:[1,0,0] op_sel_hi:[1,1,1]
	v_pk_fma_f32 v[104:105], v[52:53], v[60:61], v[104:105] op_sel:[1,0,0] op_sel_hi:[1,1,1]
	v_pk_fma_f32 v[106:107], v[52:53], v[62:63], v[106:107] op_sel:[1,0,0] op_sel_hi:[1,1,1]
	v_pk_fma_f32 v[108:109], v[54:55], v[56:57], v[108:109] op_sel_hi:[0,1,1]
	v_pk_fma_f32 v[110:111], v[54:55], v[58:59], v[110:111] op_sel_hi:[0,1,1]
	v_pk_fma_f32 v[112:113], v[54:55], v[60:61], v[112:113] op_sel_hi:[0,1,1]
	v_pk_fma_f32 v[114:115], v[54:55], v[62:63], v[114:115] op_sel_hi:[0,1,1]
	v_pk_fma_f32 v[116:117], v[54:55], v[56:57], v[116:117] op_sel:[1,0,0] op_sel_hi:[1,1,1]
	v_pk_fma_f32 v[118:119], v[54:55], v[58:59], v[118:119] op_sel:[1,0,0] op_sel_hi:[1,1,1]
	v_pk_fma_f32 v[120:121], v[54:55], v[60:61], v[120:121] op_sel:[1,0,0] op_sel_hi:[1,1,1]
	v_pk_fma_f32 v[122:123], v[54:55], v[62:63], v[122:123] op_sel:[1,0,0] op_sel_hi:[1,1,1]
	ds_read_b128 v[52:55], v74 offset:1408
	s_waitcnt lgkmcnt(2)
	v_cvt_f32_f16_e32 v56, v160
	v_cvt_f32_f16_sdwa v57, v160 dst_sel:DWORD dst_unused:UNUSED_PAD src0_sel:WORD_1
	v_cvt_f32_f16_e32 v58, v161
	v_cvt_f32_f16_sdwa v59, v161 dst_sel:DWORD dst_unused:UNUSED_PAD src0_sel:WORD_1
	v_cvt_f32_f16_e32 v60, v162
	v_cvt_f32_f16_sdwa v61, v162 dst_sel:DWORD dst_unused:UNUSED_PAD src0_sel:WORD_1
	v_cvt_f32_f16_e32 v62, v163
	v_cvt_f32_f16_sdwa v63, v163 dst_sel:DWORD dst_unused:UNUSED_PAD src0_sel:WORD_1
	v_pk_fma_f32 v[92:93], v[44:45], v[56:57], v[92:93] op_sel_hi:[0,1,1]
	v_pk_fma_f32 v[94:95], v[44:45], v[58:59], v[94:95] op_sel_hi:[0,1,1]
	v_pk_fma_f32 v[96:97], v[44:45], v[60:61], v[96:97] op_sel_hi:[0,1,1]
	v_pk_fma_f32 v[98:99], v[44:45], v[62:63], v[98:99] op_sel_hi:[0,1,1]
	v_pk_fma_f32 v[100:101], v[44:45], v[56:57], v[100:101] op_sel:[1,0,0] op_sel_hi:[1,1,1]
	v_pk_fma_f32 v[102:103], v[44:45], v[58:59], v[102:103] op_sel:[1,0,0] op_sel_hi:[1,1,1]
	v_pk_fma_f32 v[104:105], v[44:45], v[60:61], v[104:105] op_sel:[1,0,0] op_sel_hi:[1,1,1]
	v_pk_fma_f32 v[106:107], v[44:45], v[62:63], v[106:107] op_sel:[1,0,0] op_sel_hi:[1,1,1]
	v_pk_fma_f32 v[108:109], v[46:47], v[56:57], v[108:109] op_sel_hi:[0,1,1]
	v_pk_fma_f32 v[110:111], v[46:47], v[58:59], v[110:111] op_sel_hi:[0,1,1]
	v_pk_fma_f32 v[112:113], v[46:47], v[60:61], v[112:113] op_sel_hi:[0,1,1]
	v_pk_fma_f32 v[114:115], v[46:47], v[62:63], v[114:115] op_sel_hi:[0,1,1]
	v_pk_fma_f32 v[116:117], v[46:47], v[56:57], v[116:117] op_sel:[1,0,0] op_sel_hi:[1,1,1]
	v_pk_fma_f32 v[118:119], v[46:47], v[58:59], v[118:119] op_sel:[1,0,0] op_sel_hi:[1,1,1]
	v_pk_fma_f32 v[120:121], v[46:47], v[60:61], v[120:121] op_sel:[1,0,0] op_sel_hi:[1,1,1]
	v_pk_fma_f32 v[122:123], v[46:47], v[62:63], v[122:123] op_sel:[1,0,0] op_sel_hi:[1,1,1]
	ds_read_b128 v[44:47], v74 offset:1536
	s_waitcnt lgkmcnt(2)
	v_cvt_f32_f16_e32 v56, v164
	v_cvt_f32_f16_sdwa v57, v164 dst_sel:DWORD dst_unused:UNUSED_PAD src0_sel:WORD_1
	v_cvt_f32_f16_e32 v58, v165
	v_cvt_f32_f16_sdwa v59, v165 dst_sel:DWORD dst_unused:UNUSED_PAD src0_sel:WORD_1
	v_cvt_f32_f16_e32 v60, v166
	v_cvt_f32_f16_sdwa v61, v166 dst_sel:DWORD dst_unused:UNUSED_PAD src0_sel:WORD_1
	v_cvt_f32_f16_e32 v62, v167
	v_cvt_f32_f16_sdwa v63, v167 dst_sel:DWORD dst_unused:UNUSED_PAD src0_sel:WORD_1
	v_pk_fma_f32 v[92:93], v[48:49], v[56:57], v[92:93] op_sel_hi:[0,1,1]
	v_pk_fma_f32 v[94:95], v[48:49], v[58:59], v[94:95] op_sel_hi:[0,1,1]
	v_pk_fma_f32 v[96:97], v[48:49], v[60:61], v[96:97] op_sel_hi:[0,1,1]
	v_pk_fma_f32 v[98:99], v[48:49], v[62:63], v[98:99] op_sel_hi:[0,1,1]
	v_pk_fma_f32 v[100:101], v[48:49], v[56:57], v[100:101] op_sel:[1,0,0] op_sel_hi:[1,1,1]
	v_pk_fma_f32 v[102:103], v[48:49], v[58:59], v[102:103] op_sel:[1,0,0] op_sel_hi:[1,1,1]
	v_pk_fma_f32 v[104:105], v[48:49], v[60:61], v[104:105] op_sel:[1,0,0] op_sel_hi:[1,1,1]
	v_pk_fma_f32 v[106:107], v[48:49], v[62:63], v[106:107] op_sel:[1,0,0] op_sel_hi:[1,1,1]
	v_pk_fma_f32 v[108:109], v[50:51], v[56:57], v[108:109] op_sel_hi:[0,1,1]
	v_pk_fma_f32 v[110:111], v[50:51], v[58:59], v[110:111] op_sel_hi:[0,1,1]
	v_pk_fma_f32 v[112:113], v[50:51], v[60:61], v[112:113] op_sel_hi:[0,1,1]
	v_pk_fma_f32 v[114:115], v[50:51], v[62:63], v[114:115] op_sel_hi:[0,1,1]
	v_pk_fma_f32 v[116:117], v[50:51], v[56:57], v[116:117] op_sel:[1,0,0] op_sel_hi:[1,1,1]
	v_pk_fma_f32 v[118:119], v[50:51], v[58:59], v[118:119] op_sel:[1,0,0] op_sel_hi:[1,1,1]
	v_pk_fma_f32 v[120:121], v[50:51], v[60:61], v[120:121] op_sel:[1,0,0] op_sel_hi:[1,1,1]
	v_pk_fma_f32 v[122:123], v[50:51], v[62:63], v[122:123] op_sel:[1,0,0] op_sel_hi:[1,1,1]
	ds_read_b128 v[48:51], v74 offset:1664
	s_waitcnt lgkmcnt(2)
	v_cvt_f32_f16_e32 v56, v168
	v_cvt_f32_f16_sdwa v57, v168 dst_sel:DWORD dst_unused:UNUSED_PAD src0_sel:WORD_1
	v_cvt_f32_f16_e32 v58, v169
	v_cvt_f32_f16_sdwa v59, v169 dst_sel:DWORD dst_unused:UNUSED_PAD src0_sel:WORD_1
	v_cvt_f32_f16_e32 v60, v170
	v_cvt_f32_f16_sdwa v61, v170 dst_sel:DWORD dst_unused:UNUSED_PAD src0_sel:WORD_1
	v_cvt_f32_f16_e32 v62, v171
	v_cvt_f32_f16_sdwa v63, v171 dst_sel:DWORD dst_unused:UNUSED_PAD src0_sel:WORD_1
	v_pk_fma_f32 v[92:93], v[52:53], v[56:57], v[92:93] op_sel_hi:[0,1,1]
	v_pk_fma_f32 v[94:95], v[52:53], v[58:59], v[94:95] op_sel_hi:[0,1,1]
	v_pk_fma_f32 v[96:97], v[52:53], v[60:61], v[96:97] op_sel_hi:[0,1,1]
	v_pk_fma_f32 v[98:99], v[52:53], v[62:63], v[98:99] op_sel_hi:[0,1,1]
	v_pk_fma_f32 v[100:101], v[52:53], v[56:57], v[100:101] op_sel:[1,0,0] op_sel_hi:[1,1,1]
	v_pk_fma_f32 v[102:103], v[52:53], v[58:59], v[102:103] op_sel:[1,0,0] op_sel_hi:[1,1,1]
	v_pk_fma_f32 v[104:105], v[52:53], v[60:61], v[104:105] op_sel:[1,0,0] op_sel_hi:[1,1,1]
	v_pk_fma_f32 v[106:107], v[52:53], v[62:63], v[106:107] op_sel:[1,0,0] op_sel_hi:[1,1,1]
	v_pk_fma_f32 v[108:109], v[54:55], v[56:57], v[108:109] op_sel_hi:[0,1,1]
	v_pk_fma_f32 v[110:111], v[54:55], v[58:59], v[110:111] op_sel_hi:[0,1,1]
	v_pk_fma_f32 v[112:113], v[54:55], v[60:61], v[112:113] op_sel_hi:[0,1,1]
	v_pk_fma_f32 v[114:115], v[54:55], v[62:63], v[114:115] op_sel_hi:[0,1,1]
	v_pk_fma_f32 v[116:117], v[54:55], v[56:57], v[116:117] op_sel:[1,0,0] op_sel_hi:[1,1,1]
	v_pk_fma_f32 v[118:119], v[54:55], v[58:59], v[118:119] op_sel:[1,0,0] op_sel_hi:[1,1,1]
	v_pk_fma_f32 v[120:121], v[54:55], v[60:61], v[120:121] op_sel:[1,0,0] op_sel_hi:[1,1,1]
	v_pk_fma_f32 v[122:123], v[54:55], v[62:63], v[122:123] op_sel:[1,0,0] op_sel_hi:[1,1,1]
	ds_read_b128 v[52:55], v74 offset:1792
	s_waitcnt lgkmcnt(2)
	v_cvt_f32_f16_e32 v56, v172
	v_cvt_f32_f16_sdwa v57, v172 dst_sel:DWORD dst_unused:UNUSED_PAD src0_sel:WORD_1
	v_cvt_f32_f16_e32 v58, v173
	v_cvt_f32_f16_sdwa v59, v173 dst_sel:DWORD dst_unused:UNUSED_PAD src0_sel:WORD_1
	v_cvt_f32_f16_e32 v60, v174
	v_cvt_f32_f16_sdwa v61, v174 dst_sel:DWORD dst_unused:UNUSED_PAD src0_sel:WORD_1
	v_cvt_f32_f16_e32 v62, v175
	v_cvt_f32_f16_sdwa v63, v175 dst_sel:DWORD dst_unused:UNUSED_PAD src0_sel:WORD_1
	v_pk_fma_f32 v[92:93], v[44:45], v[56:57], v[92:93] op_sel_hi:[0,1,1]
	v_pk_fma_f32 v[94:95], v[44:45], v[58:59], v[94:95] op_sel_hi:[0,1,1]
	v_pk_fma_f32 v[96:97], v[44:45], v[60:61], v[96:97] op_sel_hi:[0,1,1]
	v_pk_fma_f32 v[98:99], v[44:45], v[62:63], v[98:99] op_sel_hi:[0,1,1]
	v_pk_fma_f32 v[100:101], v[44:45], v[56:57], v[100:101] op_sel:[1,0,0] op_sel_hi:[1,1,1]
	v_pk_fma_f32 v[102:103], v[44:45], v[58:59], v[102:103] op_sel:[1,0,0] op_sel_hi:[1,1,1]
	v_pk_fma_f32 v[104:105], v[44:45], v[60:61], v[104:105] op_sel:[1,0,0] op_sel_hi:[1,1,1]
	v_pk_fma_f32 v[106:107], v[44:45], v[62:63], v[106:107] op_sel:[1,0,0] op_sel_hi:[1,1,1]
	v_pk_fma_f32 v[108:109], v[46:47], v[56:57], v[108:109] op_sel_hi:[0,1,1]
	v_pk_fma_f32 v[110:111], v[46:47], v[58:59], v[110:111] op_sel_hi:[0,1,1]
	v_pk_fma_f32 v[112:113], v[46:47], v[60:61], v[112:113] op_sel_hi:[0,1,1]
	v_pk_fma_f32 v[114:115], v[46:47], v[62:63], v[114:115] op_sel_hi:[0,1,1]
	v_pk_fma_f32 v[116:117], v[46:47], v[56:57], v[116:117] op_sel:[1,0,0] op_sel_hi:[1,1,1]
	v_pk_fma_f32 v[118:119], v[46:47], v[58:59], v[118:119] op_sel:[1,0,0] op_sel_hi:[1,1,1]
	v_pk_fma_f32 v[120:121], v[46:47], v[60:61], v[120:121] op_sel:[1,0,0] op_sel_hi:[1,1,1]
	v_pk_fma_f32 v[122:123], v[46:47], v[62:63], v[122:123] op_sel:[1,0,0] op_sel_hi:[1,1,1]
	ds_read_b128 v[44:47], v74 offset:1920
	s_waitcnt lgkmcnt(2)
	v_cvt_f32_f16_e32 v56, v176
	v_cvt_f32_f16_sdwa v57, v176 dst_sel:DWORD dst_unused:UNUSED_PAD src0_sel:WORD_1
	v_cvt_f32_f16_e32 v58, v177
	v_cvt_f32_f16_sdwa v59, v177 dst_sel:DWORD dst_unused:UNUSED_PAD src0_sel:WORD_1
	v_cvt_f32_f16_e32 v60, v178
	v_cvt_f32_f16_sdwa v61, v178 dst_sel:DWORD dst_unused:UNUSED_PAD src0_sel:WORD_1
	v_cvt_f32_f16_e32 v62, v179
	v_cvt_f32_f16_sdwa v63, v179 dst_sel:DWORD dst_unused:UNUSED_PAD src0_sel:WORD_1
	v_pk_fma_f32 v[92:93], v[48:49], v[56:57], v[92:93] op_sel_hi:[0,1,1]
	v_pk_fma_f32 v[94:95], v[48:49], v[58:59], v[94:95] op_sel_hi:[0,1,1]
	v_pk_fma_f32 v[96:97], v[48:49], v[60:61], v[96:97] op_sel_hi:[0,1,1]
	v_pk_fma_f32 v[98:99], v[48:49], v[62:63], v[98:99] op_sel_hi:[0,1,1]
	v_pk_fma_f32 v[100:101], v[48:49], v[56:57], v[100:101] op_sel:[1,0,0] op_sel_hi:[1,1,1]
	v_pk_fma_f32 v[102:103], v[48:49], v[58:59], v[102:103] op_sel:[1,0,0] op_sel_hi:[1,1,1]
	v_pk_fma_f32 v[104:105], v[48:49], v[60:61], v[104:105] op_sel:[1,0,0] op_sel_hi:[1,1,1]
	v_pk_fma_f32 v[106:107], v[48:49], v[62:63], v[106:107] op_sel:[1,0,0] op_sel_hi:[1,1,1]
	v_pk_fma_f32 v[108:109], v[50:51], v[56:57], v[108:109] op_sel_hi:[0,1,1]
	v_pk_fma_f32 v[110:111], v[50:51], v[58:59], v[110:111] op_sel_hi:[0,1,1]
	v_pk_fma_f32 v[112:113], v[50:51], v[60:61], v[112:113] op_sel_hi:[0,1,1]
	v_pk_fma_f32 v[114:115], v[50:51], v[62:63], v[114:115] op_sel_hi:[0,1,1]
	v_pk_fma_f32 v[116:117], v[50:51], v[56:57], v[116:117] op_sel:[1,0,0] op_sel_hi:[1,1,1]
	v_pk_fma_f32 v[118:119], v[50:51], v[58:59], v[118:119] op_sel:[1,0,0] op_sel_hi:[1,1,1]
	v_pk_fma_f32 v[120:121], v[50:51], v[60:61], v[120:121] op_sel:[1,0,0] op_sel_hi:[1,1,1]
	v_pk_fma_f32 v[122:123], v[50:51], v[62:63], v[122:123] op_sel:[1,0,0] op_sel_hi:[1,1,1]
	s_waitcnt lgkmcnt(1)
	v_cvt_f32_f16_e32 v56, v180
	v_cvt_f32_f16_sdwa v57, v180 dst_sel:DWORD dst_unused:UNUSED_PAD src0_sel:WORD_1
	v_cvt_f32_f16_e32 v58, v181
	v_cvt_f32_f16_sdwa v59, v181 dst_sel:DWORD dst_unused:UNUSED_PAD src0_sel:WORD_1
	v_cvt_f32_f16_e32 v60, v182
	v_cvt_f32_f16_sdwa v61, v182 dst_sel:DWORD dst_unused:UNUSED_PAD src0_sel:WORD_1
	v_cvt_f32_f16_e32 v62, v183
	v_cvt_f32_f16_sdwa v63, v183 dst_sel:DWORD dst_unused:UNUSED_PAD src0_sel:WORD_1
	v_pk_fma_f32 v[92:93], v[52:53], v[56:57], v[92:93] op_sel_hi:[0,1,1]
	v_pk_fma_f32 v[94:95], v[52:53], v[58:59], v[94:95] op_sel_hi:[0,1,1]
	v_pk_fma_f32 v[96:97], v[52:53], v[60:61], v[96:97] op_sel_hi:[0,1,1]
	v_pk_fma_f32 v[98:99], v[52:53], v[62:63], v[98:99] op_sel_hi:[0,1,1]
	v_pk_fma_f32 v[100:101], v[52:53], v[56:57], v[100:101] op_sel:[1,0,0] op_sel_hi:[1,1,1]
	v_pk_fma_f32 v[102:103], v[52:53], v[58:59], v[102:103] op_sel:[1,0,0] op_sel_hi:[1,1,1]
	v_pk_fma_f32 v[104:105], v[52:53], v[60:61], v[104:105] op_sel:[1,0,0] op_sel_hi:[1,1,1]
	v_pk_fma_f32 v[106:107], v[52:53], v[62:63], v[106:107] op_sel:[1,0,0] op_sel_hi:[1,1,1]
	v_pk_fma_f32 v[108:109], v[54:55], v[56:57], v[108:109] op_sel_hi:[0,1,1]
	v_pk_fma_f32 v[110:111], v[54:55], v[58:59], v[110:111] op_sel_hi:[0,1,1]
	v_pk_fma_f32 v[112:113], v[54:55], v[60:61], v[112:113] op_sel_hi:[0,1,1]
	v_pk_fma_f32 v[114:115], v[54:55], v[62:63], v[114:115] op_sel_hi:[0,1,1]
	v_pk_fma_f32 v[116:117], v[54:55], v[56:57], v[116:117] op_sel:[1,0,0] op_sel_hi:[1,1,1]
	v_pk_fma_f32 v[118:119], v[54:55], v[58:59], v[118:119] op_sel:[1,0,0] op_sel_hi:[1,1,1]
	v_pk_fma_f32 v[120:121], v[54:55], v[60:61], v[120:121] op_sel:[1,0,0] op_sel_hi:[1,1,1]
	v_pk_fma_f32 v[122:123], v[54:55], v[62:63], v[122:123] op_sel:[1,0,0] op_sel_hi:[1,1,1]
	s_waitcnt lgkmcnt(0)
	v_cvt_f32_f16_e32 v56, v184
	v_cvt_f32_f16_sdwa v57, v184 dst_sel:DWORD dst_unused:UNUSED_PAD src0_sel:WORD_1
	v_cvt_f32_f16_e32 v58, v185
	v_cvt_f32_f16_sdwa v59, v185 dst_sel:DWORD dst_unused:UNUSED_PAD src0_sel:WORD_1
	v_cvt_f32_f16_e32 v60, v186
	v_cvt_f32_f16_sdwa v61, v186 dst_sel:DWORD dst_unused:UNUSED_PAD src0_sel:WORD_1
	v_cvt_f32_f16_e32 v62, v187
	v_cvt_f32_f16_sdwa v63, v187 dst_sel:DWORD dst_unused:UNUSED_PAD src0_sel:WORD_1
	v_pk_fma_f32 v[92:93], v[44:45], v[56:57], v[92:93] op_sel_hi:[0,1,1]
	v_pk_fma_f32 v[94:95], v[44:45], v[58:59], v[94:95] op_sel_hi:[0,1,1]
	v_pk_fma_f32 v[96:97], v[44:45], v[60:61], v[96:97] op_sel_hi:[0,1,1]
	v_pk_fma_f32 v[98:99], v[44:45], v[62:63], v[98:99] op_sel_hi:[0,1,1]
	v_pk_fma_f32 v[100:101], v[44:45], v[56:57], v[100:101] op_sel:[1,0,0] op_sel_hi:[1,1,1]
	v_pk_fma_f32 v[102:103], v[44:45], v[58:59], v[102:103] op_sel:[1,0,0] op_sel_hi:[1,1,1]
	v_pk_fma_f32 v[104:105], v[44:45], v[60:61], v[104:105] op_sel:[1,0,0] op_sel_hi:[1,1,1]
	v_pk_fma_f32 v[106:107], v[44:45], v[62:63], v[106:107] op_sel:[1,0,0] op_sel_hi:[1,1,1]
	v_pk_fma_f32 v[108:109], v[46:47], v[56:57], v[108:109] op_sel_hi:[0,1,1]
	v_pk_fma_f32 v[110:111], v[46:47], v[58:59], v[110:111] op_sel_hi:[0,1,1]
	v_pk_fma_f32 v[112:113], v[46:47], v[60:61], v[112:113] op_sel_hi:[0,1,1]
	v_pk_fma_f32 v[114:115], v[46:47], v[62:63], v[114:115] op_sel_hi:[0,1,1]
	v_pk_fma_f32 v[116:117], v[46:47], v[56:57], v[116:117] op_sel:[1,0,0] op_sel_hi:[1,1,1]
	v_pk_fma_f32 v[118:119], v[46:47], v[58:59], v[118:119] op_sel:[1,0,0] op_sel_hi:[1,1,1]
	v_pk_fma_f32 v[120:121], v[46:47], v[60:61], v[120:121] op_sel:[1,0,0] op_sel_hi:[1,1,1]
	v_pk_fma_f32 v[122:123], v[46:47], v[62:63], v[122:123] op_sel:[1,0,0] op_sel_hi:[1,1,1]
	s_cmp_eq_u32 s6, 15
	s_cbranch_scc1 .Latt_last
	s_add_i32 s2, s6, 1
	s_lshr_b32 s2, s2, 1
	s_add_i32 s2, s2, s15
	s_add_i32 s14, s62, s2
	s_mul_i32 s8, s2, 0x600
	s_add_i32 s8, s8, 0x18000
	s_lshl_b32 s3, s2, 2
	s_add_i32 s3, s3, 0x24000
	v_mov_b32_e32 v40, s3
	ds_read_b32 v40, v40
	s_mul_i32 s2, s14, s68
	s_mul_hi_u32 s3, s14, s68
	s_add_u32 s12, s56, s2
	s_addc_u32 s13, s57, s3
	s_mul_i32 s2, s14, s64
	v_add_u32_e32 v71, s2, v2
	s_waitcnt lgkmcnt(0)
	v_readfirstlane_b32 s7, v40
	s_min_i32 s7, s7, 0x100
	s_add_i32 s9, s7, -1
	v_min_u32_e32 v40, s9, v24
	v_lshl_add_u32 v40, v40, 1, s8
	ds_read_u16 v8, v40
	v_add_u32_e32 v42, 16, v24
	v_min_u32_e32 v42, s9, v42
	v_lshl_add_u32 v42, v42, 1, s8
	ds_read_u16 v9, v42
	v_add_u32_e32 v43, 32, v24
	v_min_u32_e32 v43, s9, v43
	v_lshl_add_u32 v43, v43, 1, s8
	ds_read_u16 v10, v43
	v_add_u32_e32 v40, 48, v24
	v_min_u32_e32 v40, s9, v40
	v_lshl_add_u32 v40, v40, 1, s8
	ds_read_u16 v11, v40
	v_add_u32_e32 v42, 64, v24
	v_min_u32_e32 v42, s9, v42
	v_lshl_add_u32 v42, v42, 1, s8
	ds_read_u16 v12, v42
	v_add_u32_e32 v43, 80, v24
	v_min_u32_e32 v43, s9, v43
	v_lshl_add_u32 v43, v43, 1, s8
	ds_read_u16 v13, v43
	v_add_u32_e32 v40, 96, v24
	v_min_u32_e32 v40, s9, v40
	v_lshl_add_u32 v40, v40, 1, s8
	ds_read_u16 v14, v40
	v_add_u32_e32 v42, 112, v24
	v_min_u32_e32 v42, s9, v42
	v_lshl_add_u32 v42, v42, 1, s8
	ds_read_u16 v15, v42
	v_add_u32_e32 v43, 128, v24
	v_min_u32_e32 v43, s9, v43
	v_lshl_add_u32 v43, v43, 1, s8
	ds_read_u16 v16, v43
	v_add_u32_e32 v40, 144, v24
	v_min_u32_e32 v40, s9, v40
	v_lshl_add_u32 v40, v40, 1, s8
	ds_read_u16 v17, v40
	v_add_u32_e32 v42, 160, v24
	v_min_u32_e32 v42, s9, v42
	v_lshl_add_u32 v42, v42, 1, s8
	ds_read_u16 v18, v42
	v_add_u32_e32 v43, 176, v24
	v_min_u32_e32 v43, s9, v43
	v_lshl_add_u32 v43, v43, 1, s8
	ds_read_u16 v19, v43
	v_add_u32_e32 v40, 192, v24
	v_min_u32_e32 v40, s9, v40
	v_lshl_add_u32 v40, v40, 1, s8
	ds_read_u16 v20, v40
	v_add_u32_e32 v42, 208, v24
	v_min_u32_e32 v42, s9, v42
	v_lshl_add_u32 v42, v42, 1, s8
	ds_read_u16 v21, v42
	v_add_u32_e32 v43, 224, v24
	v_min_u32_e32 v43, s9, v43
	v_lshl_add_u32 v43, v43, 1, s8
	ds_read_u16 v22, v43
	v_add_u32_e32 v40, 240, v24
	v_min_u32_e32 v40, s9, v40
	v_lshl_add_u32 v40, v40, 1, s8
	ds_read_u16 v23, v40
	v_min_u32_e32 v42, s9, v1
	v_lshl_add_u32 v42, v42, 1, s8
	ds_read_u16 v44, v42
	v_add_u32_e32 v43, 8, v1
	v_min_u32_e32 v43, s9, v43
	v_lshl_add_u32 v43, v43, 1, s8
	ds_read_u16 v45, v43
	v_add_u32_e32 v40, 16, v1
	v_min_u32_e32 v40, s9, v40
	v_lshl_add_u32 v40, v40, 1, s8
	ds_read_u16 v46, v40
	v_add_u32_e32 v42, 24, v1
	v_min_u32_e32 v42, s9, v42
	v_lshl_add_u32 v42, v42, 1, s8
	ds_read_u16 v47, v42
	v_add_u32_e32 v43, 32, v1
	v_min_u32_e32 v43, s9, v43
	v_lshl_add_u32 v43, v43, 1, s8
	ds_read_u16 v48, v43
	v_add_u32_e32 v40, 40, v1
	v_min_u32_e32 v40, s9, v40
	v_lshl_add_u32 v40, v40, 1, s8
	ds_read_u16 v49, v40
	v_add_u32_e32 v42, 48, v1
	v_min_u32_e32 v42, s9, v42
	v_lshl_add_u32 v42, v42, 1, s8
	ds_read_u16 v50, v42
	v_add_u32_e32 v43, 56, v1
	v_min_u32_e32 v43, s9, v43
	v_lshl_add_u32 v43, v43, 1, s8
	ds_read_u16 v51, v43
	v_add_u32_e32 v40, 64, v1
	v_min_u32_e32 v40, s9, v40
	v_lshl_add_u32 v40, v40, 1, s8
	ds_read_u16 v52, v40
	v_add_u32_e32 v42, 72, v1
	v_min_u32_e32 v42, s9, v42
	v_lshl_add_u32 v42, v42, 1, s8
	ds_read_u16 v53, v42
	v_add_u32_e32 v43, 80, v1
	v_min_u32_e32 v43, s9, v43
	v_lshl_add_u32 v43, v43, 1, s8
	ds_read_u16 v54, v43
	v_add_u32_e32 v40, 88, v1
	v_min_u32_e32 v40, s9, v40
	v_lshl_add_u32 v40, v40, 1, s8
	ds_read_u16 v55, v40
	v_add_u32_e32 v42, 96, v1
	v_min_u32_e32 v42, s9, v42
	v_lshl_add_u32 v42, v42, 1, s8
	ds_read_u16 v56, v42
	v_add_u32_e32 v43, 104, v1
	v_min_u32_e32 v43, s9, v43
	v_lshl_add_u32 v43, v43, 1, s8
	ds_read_u16 v57, v43
	v_add_u32_e32 v40, 112, v1
	v_min_u32_e32 v40, s9, v40
	v_lshl_add_u32 v40, v40, 1, s8
	ds_read_u16 v58, v40
	v_add_u32_e32 v42, 120, v1
	v_min_u32_e32 v42, s9, v42
	v_lshl_add_u32 v42, v42, 1, s8
	ds_read_u16 v59, v42
	s_waitcnt lgkmcnt(0)
	v_mad_u32_u24 v8, v8, s64, v25
	v_mad_u32_u24 v9, v9, s64, v25
	v_mad_u32_u24 v10, v10, s64, v25
	v_mad_u32_u24 v11, v11, s64, v25
	v_mad_u32_u24 v12, v12, s64, v25
	v_mad_u32_u24 v13, v13, s64, v25
	v_mad_u32_u24 v14, v14, s64, v25
	v_mad_u32_u24 v15, v15, s64, v25
	v_mad_u32_u24 v16, v16, s64, v25
	v_mad_u32_u24 v17, v17, s64, v25
	v_mad_u32_u24 v18, v18, s64, v25
	v_mad_u32_u24 v19, v19, s64, v25
	v_mad_u32_u24 v20, v20, s64, v25
	v_mad_u32_u24 v21, v21, s64, v25
	v_mad_u32_u24 v22, v22, s64, v25
	v_mad_u32_u24 v23, v23, s64, v25
	v_mad_u32_u24 v44, v44, s64, v2
	v_mad_u32_u24 v45, v45, s64, v2
	v_mad_u32_u24 v46, v46, s64, v2
	v_mad_u32_u24 v47, v47, s64, v2
	v_mad_u32_u24 v48, v48, s64, v2
	v_mad_u32_u24 v49, v49, s64, v2
	v_mad_u32_u24 v50, v50, s64, v2
	v_mad_u32_u24 v51, v51, s64, v2
	v_mad_u32_u24 v52, v52, s64, v2
	v_mad_u32_u24 v53, v53, s64, v2
	v_mad_u32_u24 v54, v54, s64, v2
	v_mad_u32_u24 v55, v55, s64, v2
	v_mad_u32_u24 v56, v56, s64, v2
	v_mad_u32_u24 v57, v57, s64, v2
	v_mad_u32_u24 v58, v58, s64, v2
	v_mad_u32_u24 v59, v59, s64, v2
	v_accvgpr_write_b32 a160, v44
	v_accvgpr_write_b32 a161, v45
	v_accvgpr_write_b32 a162, v46
	v_accvgpr_write_b32 a163, v47
	v_accvgpr_write_b32 a164, v48
	v_accvgpr_write_b32 a165, v49
	v_accvgpr_write_b32 a166, v50
	v_accvgpr_write_b32 a167, v51
	v_accvgpr_write_b32 a168, v52
	v_accvgpr_write_b32 a169, v53
	v_accvgpr_write_b32 a170, v54
	v_accvgpr_write_b32 a171, v55
	v_accvgpr_write_b32 a172, v56
	v_accvgpr_write_b32 a173, v57
	v_accvgpr_write_b32 a174, v58
	v_accvgpr_write_b32 a175, v59
	v_add_u32_e32 v43, 128, v1
	v_min_u32_e32 v43, s9, v43
	v_lshl_add_u32 v43, v43, 1, s8
	ds_read_u16 v44, v43
	v_add_u32_e32 v40, 136, v1
	v_min_u32_e32 v40, s9, v40
	v_lshl_add_u32 v40, v40, 1, s8
	ds_read_u16 v45, v40
	v_add_u32_e32 v42, 144, v1
	v_min_u32_e32 v42, s9, v42
	v_lshl_add_u32 v42, v42, 1, s8
	ds_read_u16 v46, v42
	v_add_u32_e32 v43, 152, v1
	v_min_u32_e32 v43, s9, v43
	v_lshl_add_u32 v43, v43, 1, s8
	ds_read_u16 v47, v43
	v_add_u32_e32 v40, 160, v1
	v_min_u32_e32 v40, s9, v40
	v_lshl_add_u32 v40, v40, 1, s8
	ds_read_u16 v48, v40
	v_add_u32_e32 v42, 168, v1
	v_min_u32_e32 v42, s9, v42
	v_lshl_add_u32 v42, v42, 1, s8
	ds_read_u16 v49, v42
	v_add_u32_e32 v43, 176, v1
	v_min_u32_e32 v43, s9, v43
	v_lshl_add_u32 v43, v43, 1, s8
	ds_read_u16 v50, v43
	v_add_u32_e32 v40, 184, v1
	v_min_u32_e32 v40, s9, v40
	v_lshl_add_u32 v40, v40, 1, s8
	ds_read_u16 v51, v40
	v_add_u32_e32 v42, 192, v1
	v_min_u32_e32 v42, s9, v42
	v_lshl_add_u32 v42, v42, 1, s8
	ds_read_u16 v52, v42
	v_add_u32_e32 v43, 200, v1
	v_min_u32_e32 v43, s9, v43
	v_lshl_add_u32 v43, v43, 1, s8
	ds_read_u16 v53, v43
	v_add_u32_e32 v40, 208, v1
	v_min_u32_e32 v40, s9, v40
	v_lshl_add_u32 v40, v40, 1, s8
	ds_read_u16 v54, v40
	v_add_u32_e32 v42, 216, v1
	v_min_u32_e32 v42, s9, v42
	v_lshl_add_u32 v42, v42, 1, s8
	ds_read_u16 v55, v42
	v_add_u32_e32 v43, 224, v1
	v_min_u32_e32 v43, s9, v43
	v_lshl_add_u32 v43, v43, 1, s8
	ds_read_u16 v56, v43
	v_add_u32_e32 v40, 232, v1
	v_min_u32_e32 v40, s9, v40
	v_lshl_add_u32 v40, v40, 1, s8
	ds_read_u16 v57, v40
	v_add_u32_e32 v42, 240, v1
	v_min_u32_e32 v42, s9, v42
	v_lshl_add_u32 v42, v42, 1, s8
	ds_read_u16 v58, v42
	v_add_u32_e32 v43, 248, v1
	v_min_u32_e32 v43, s9, v43
	v_lshl_add_u32 v43, v43, 1, s8
	ds_read_u16 v59, v43
	s_waitcnt lgkmcnt(0)
	v_mad_u32_u24 v44, v44, s64, v2
	v_mad_u32_u24 v45, v45, s64, v2
	v_mad_u32_u24 v46, v46, s64, v2
	v_mad_u32_u24 v47, v47, s64, v2
	v_mad_u32_u24 v48, v48, s64, v2
	v_mad_u32_u24 v49, v49, s64, v2
	v_mad_u32_u24 v50, v50, s64, v2
	v_mad_u32_u24 v51, v51, s64, v2
	v_mad_u32_u24 v52, v52, s64, v2
	v_mad_u32_u24 v53, v53, s64, v2
	v_mad_u32_u24 v54, v54, s64, v2
	v_mad_u32_u24 v55, v55, s64, v2
	v_mad_u32_u24 v56, v56, s64, v2
	v_mad_u32_u24 v57, v57, s64, v2
	v_mad_u32_u24 v58, v58, s64, v2
	v_mad_u32_u24 v59, v59, s64, v2
	v_accvgpr_write_b32 a176, v44
	v_accvgpr_write_b32 a177, v45
	v_accvgpr_write_b32 a178, v46
	v_accvgpr_write_b32 a179, v47
	v_accvgpr_write_b32 a180, v48
	v_accvgpr_write_b32 a181, v49
	v_accvgpr_write_b32 a182, v50
	v_accvgpr_write_b32 a183, v51
	v_accvgpr_write_b32 a184, v52
	v_accvgpr_write_b32 a185, v53
	v_accvgpr_write_b32 a186, v54
	v_accvgpr_write_b32 a187, v55
	v_accvgpr_write_b32 a188, v56
	v_accvgpr_write_b32 a189, v57
	v_accvgpr_write_b32 a190, v58
	v_accvgpr_write_b32 a191, v59
	global_load_dwordx4 a[0:3], v8, s[96:97] offset:0
	global_load_dwordx4 a[4:7], v8, s[96:97] offset:16
	global_load_dwordx4 a[8:11], v9, s[96:97] offset:0
	global_load_dwordx4 a[12:15], v9, s[96:97] offset:16
	global_load_dwordx4 a[16:19], v10, s[96:97] offset:0
	global_load_dwordx4 a[20:23], v10, s[96:97] offset:16
	global_load_dwordx4 a[24:27], v11, s[96:97] offset:0
	global_load_dwordx4 a[28:31], v11, s[96:97] offset:16
	global_load_dwordx4 a[32:35], v12, s[96:97] offset:0
	global_load_dwordx4 a[36:39], v12, s[96:97] offset:16
	global_load_dwordx4 a[40:43], v13, s[96:97] offset:0
	global_load_dwordx4 a[44:47], v13, s[96:97] offset:16
	global_load_dwordx4 a[48:51], v14, s[96:97] offset:0
	global_load_dwordx4 a[52:55], v14, s[96:97] offset:16
	global_load_dwordx4 a[56:59], v15, s[96:97] offset:0
	global_load_dwordx4 a[60:63], v15, s[96:97] offset:16
	global_load_dwordx4 a[64:67], v16, s[96:97] offset:0
	global_load_dwordx4 a[68:71], v16, s[96:97] offset:16
	global_load_dwordx4 a[72:75], v17, s[96:97] offset:0
	global_load_dwordx4 a[76:79], v17, s[96:97] offset:16
	global_load_dwordx4 a[80:83], v18, s[96:97] offset:0
	global_load_dwordx4 a[84:87], v18, s[96:97] offset:16
	global_load_dwordx4 a[88:91], v19, s[96:97] offset:0
	global_load_dwordx4 a[92:95], v19, s[96:97] offset:16
	global_load_dwordx4 a[96:99], v20, s[96:97] offset:0
	global_load_dwordx4 a[100:103], v20, s[96:97] offset:16
	global_load_dwordx4 a[104:107], v21, s[96:97] offset:0
	global_load_dwordx4 a[108:111], v21, s[96:97] offset:16
	global_load_dwordx4 a[112:115], v22, s[96:97] offset:0
	global_load_dwordx4 a[116:119], v22, s[96:97] offset:16
	global_load_dwordx4 a[120:123], v23, s[96:97] offset:0
	global_load_dwordx4 a[124:127], v23, s[96:97] offset:16
	global_load_dwordx4 a[144:147], v3, s[12:13] offset:3072
	global_load_dwordx4 a[148:151], v3, s[12:13] offset:3088
	s_waitcnt vmcnt(34)
	s_branch .Latt_pv2
.Latt_last:
	s_waitcnt vmcnt(0)
.Latt_pv2:
	ds_read_b128 v[44:47], v74 offset:2048
	ds_read_b128 v[48:51], v74 offset:2176
	ds_read_b128 v[52:55], v74 offset:2304
	s_waitcnt lgkmcnt(2)
	v_cvt_f32_f16_e32 v56, v188
	v_cvt_f32_f16_sdwa v57, v188 dst_sel:DWORD dst_unused:UNUSED_PAD src0_sel:WORD_1
	v_cvt_f32_f16_e32 v58, v189
	v_cvt_f32_f16_sdwa v59, v189 dst_sel:DWORD dst_unused:UNUSED_PAD src0_sel:WORD_1
	v_cvt_f32_f16_e32 v60, v190
	v_cvt_f32_f16_sdwa v61, v190 dst_sel:DWORD dst_unused:UNUSED_PAD src0_sel:WORD_1
	v_cvt_f32_f16_e32 v62, v191
	v_cvt_f32_f16_sdwa v63, v191 dst_sel:DWORD dst_unused:UNUSED_PAD src0_sel:WORD_1
	v_pk_fma_f32 v[92:93], v[44:45], v[56:57], v[92:93] op_sel_hi:[0,1,1]
	v_pk_fma_f32 v[94:95], v[44:45], v[58:59], v[94:95] op_sel_hi:[0,1,1]
	v_pk_fma_f32 v[96:97], v[44:45], v[60:61], v[96:97] op_sel_hi:[0,1,1]
	v_pk_fma_f32 v[98:99], v[44:45], v[62:63], v[98:99] op_sel_hi:[0,1,1]
	v_pk_fma_f32 v[100:101], v[44:45], v[56:57], v[100:101] op_sel:[1,0,0] op_sel_hi:[1,1,1]
	v_pk_fma_f32 v[102:103], v[44:45], v[58:59], v[102:103] op_sel:[1,0,0] op_sel_hi:[1,1,1]
	v_pk_fma_f32 v[104:105], v[44:45], v[60:61], v[104:105] op_sel:[1,0,0] op_sel_hi:[1,1,1]
	v_pk_fma_f32 v[106:107], v[44:45], v[62:63], v[106:107] op_sel:[1,0,0] op_sel_hi:[1,1,1]
	v_pk_fma_f32 v[108:109], v[46:47], v[56:57], v[108:109] op_sel_hi:[0,1,1]
	v_pk_fma_f32 v[110:111], v[46:47], v[58:59], v[110:111] op_sel_hi:[0,1,1]
	v_pk_fma_f32 v[112:113], v[46:47], v[60:61], v[112:113] op_sel_hi:[0,1,1]
	v_pk_fma_f32 v[114:115], v[46:47], v[62:63], v[114:115] op_sel_hi:[0,1,1]
	v_pk_fma_f32 v[116:117], v[46:47], v[56:57], v[116:117] op_sel:[1,0,0] op_sel_hi:[1,1,1]
	v_pk_fma_f32 v[118:119], v[46:47], v[58:59], v[118:119] op_sel:[1,0,0] op_sel_hi:[1,1,1]
	v_pk_fma_f32 v[120:121], v[46:47], v[60:61], v[120:121] op_sel:[1,0,0] op_sel_hi:[1,1,1]
	v_pk_fma_f32 v[122:123], v[46:47], v[62:63], v[122:123] op_sel:[1,0,0] op_sel_hi:[1,1,1]
	ds_read_b128 v[44:47], v74 offset:2432
	s_waitcnt lgkmcnt(2)
	v_cvt_f32_f16_e32 v56, v192
	v_cvt_f32_f16_sdwa v57, v192 dst_sel:DWORD dst_unused:UNUSED_PAD src0_sel:WORD_1
	v_cvt_f32_f16_e32 v58, v193
	v_cvt_f32_f16_sdwa v59, v193 dst_sel:DWORD dst_unused:UNUSED_PAD src0_sel:WORD_1
	v_cvt_f32_f16_e32 v60, v194
	v_cvt_f32_f16_sdwa v61, v194 dst_sel:DWORD dst_unused:UNUSED_PAD src0_sel:WORD_1
	v_cvt_f32_f16_e32 v62, v195
	v_cvt_f32_f16_sdwa v63, v195 dst_sel:DWORD dst_unused:UNUSED_PAD src0_sel:WORD_1
	v_pk_fma_f32 v[92:93], v[48:49], v[56:57], v[92:93] op_sel_hi:[0,1,1]
	v_pk_fma_f32 v[94:95], v[48:49], v[58:59], v[94:95] op_sel_hi:[0,1,1]
	v_pk_fma_f32 v[96:97], v[48:49], v[60:61], v[96:97] op_sel_hi:[0,1,1]
	v_pk_fma_f32 v[98:99], v[48:49], v[62:63], v[98:99] op_sel_hi:[0,1,1]
	v_pk_fma_f32 v[100:101], v[48:49], v[56:57], v[100:101] op_sel:[1,0,0] op_sel_hi:[1,1,1]
	v_pk_fma_f32 v[102:103], v[48:49], v[58:59], v[102:103] op_sel:[1,0,0] op_sel_hi:[1,1,1]
	v_pk_fma_f32 v[104:105], v[48:49], v[60:61], v[104:105] op_sel:[1,0,0] op_sel_hi:[1,1,1]
	v_pk_fma_f32 v[106:107], v[48:49], v[62:63], v[106:107] op_sel:[1,0,0] op_sel_hi:[1,1,1]
	v_pk_fma_f32 v[108:109], v[50:51], v[56:57], v[108:109] op_sel_hi:[0,1,1]
	v_pk_fma_f32 v[110:111], v[50:51], v[58:59], v[110:111] op_sel_hi:[0,1,1]
	v_pk_fma_f32 v[112:113], v[50:51], v[60:61], v[112:113] op_sel_hi:[0,1,1]
	v_pk_fma_f32 v[114:115], v[50:51], v[62:63], v[114:115] op_sel_hi:[0,1,1]
	v_pk_fma_f32 v[116:117], v[50:51], v[56:57], v[116:117] op_sel:[1,0,0] op_sel_hi:[1,1,1]
	v_pk_fma_f32 v[118:119], v[50:51], v[58:59], v[118:119] op_sel:[1,0,0] op_sel_hi:[1,1,1]
	v_pk_fma_f32 v[120:121], v[50:51], v[60:61], v[120:121] op_sel:[1,0,0] op_sel_hi:[1,1,1]
	v_pk_fma_f32 v[122:123], v[50:51], v[62:63], v[122:123] op_sel:[1,0,0] op_sel_hi:[1,1,1]
	ds_read_b128 v[48:51], v74 offset:2560
	s_waitcnt lgkmcnt(2)
	v_cvt_f32_f16_e32 v56, v196
	v_cvt_f32_f16_sdwa v57, v196 dst_sel:DWORD dst_unused:UNUSED_PAD src0_sel:WORD_1
	v_cvt_f32_f16_e32 v58, v197
	v_cvt_f32_f16_sdwa v59, v197 dst_sel:DWORD dst_unused:UNUSED_PAD src0_sel:WORD_1
	v_cvt_f32_f16_e32 v60, v198
	v_cvt_f32_f16_sdwa v61, v198 dst_sel:DWORD dst_unused:UNUSED_PAD src0_sel:WORD_1
	v_cvt_f32_f16_e32 v62, v199
	v_cvt_f32_f16_sdwa v63, v199 dst_sel:DWORD dst_unused:UNUSED_PAD src0_sel:WORD_1
	v_pk_fma_f32 v[92:93], v[52:53], v[56:57], v[92:93] op_sel_hi:[0,1,1]
	v_pk_fma_f32 v[94:95], v[52:53], v[58:59], v[94:95] op_sel_hi:[0,1,1]
	v_pk_fma_f32 v[96:97], v[52:53], v[60:61], v[96:97] op_sel_hi:[0,1,1]
	v_pk_fma_f32 v[98:99], v[52:53], v[62:63], v[98:99] op_sel_hi:[0,1,1]
	v_pk_fma_f32 v[100:101], v[52:53], v[56:57], v[100:101] op_sel:[1,0,0] op_sel_hi:[1,1,1]
	v_pk_fma_f32 v[102:103], v[52:53], v[58:59], v[102:103] op_sel:[1,0,0] op_sel_hi:[1,1,1]
	v_pk_fma_f32 v[104:105], v[52:53], v[60:61], v[104:105] op_sel:[1,0,0] op_sel_hi:[1,1,1]
	v_pk_fma_f32 v[106:107], v[52:53], v[62:63], v[106:107] op_sel:[1,0,0] op_sel_hi:[1,1,1]
	v_pk_fma_f32 v[108:109], v[54:55], v[56:57], v[108:109] op_sel_hi:[0,1,1]
	v_pk_fma_f32 v[110:111], v[54:55], v[58:59], v[110:111] op_sel_hi:[0,1,1]
	v_pk_fma_f32 v[112:113], v[54:55], v[60:61], v[112:113] op_sel_hi:[0,1,1]
	v_pk_fma_f32 v[114:115], v[54:55], v[62:63], v[114:115] op_sel_hi:[0,1,1]
	v_pk_fma_f32 v[116:117], v[54:55], v[56:57], v[116:117] op_sel:[1,0,0] op_sel_hi:[1,1,1]
	v_pk_fma_f32 v[118:119], v[54:55], v[58:59], v[118:119] op_sel:[1,0,0] op_sel_hi:[1,1,1]
	v_pk_fma_f32 v[120:121], v[54:55], v[60:61], v[120:121] op_sel:[1,0,0] op_sel_hi:[1,1,1]
	v_pk_fma_f32 v[122:123], v[54:55], v[62:63], v[122:123] op_sel:[1,0,0] op_sel_hi:[1,1,1]
	ds_read_b128 v[52:55], v74 offset:2688
	s_waitcnt lgkmcnt(2)
	v_cvt_f32_f16_e32 v56, v200
	v_cvt_f32_f16_sdwa v57, v200 dst_sel:DWORD dst_unused:UNUSED_PAD src0_sel:WORD_1
	v_cvt_f32_f16_e32 v58, v201
	v_cvt_f32_f16_sdwa v59, v201 dst_sel:DWORD dst_unused:UNUSED_PAD src0_sel:WORD_1
	v_cvt_f32_f16_e32 v60, v202
	v_cvt_f32_f16_sdwa v61, v202 dst_sel:DWORD dst_unused:UNUSED_PAD src0_sel:WORD_1
	v_cvt_f32_f16_e32 v62, v203
	v_cvt_f32_f16_sdwa v63, v203 dst_sel:DWORD dst_unused:UNUSED_PAD src0_sel:WORD_1
	v_pk_fma_f32 v[92:93], v[44:45], v[56:57], v[92:93] op_sel_hi:[0,1,1]
	v_pk_fma_f32 v[94:95], v[44:45], v[58:59], v[94:95] op_sel_hi:[0,1,1]
	v_pk_fma_f32 v[96:97], v[44:45], v[60:61], v[96:97] op_sel_hi:[0,1,1]
	v_pk_fma_f32 v[98:99], v[44:45], v[62:63], v[98:99] op_sel_hi:[0,1,1]
	v_pk_fma_f32 v[100:101], v[44:45], v[56:57], v[100:101] op_sel:[1,0,0] op_sel_hi:[1,1,1]
	v_pk_fma_f32 v[102:103], v[44:45], v[58:59], v[102:103] op_sel:[1,0,0] op_sel_hi:[1,1,1]
	v_pk_fma_f32 v[104:105], v[44:45], v[60:61], v[104:105] op_sel:[1,0,0] op_sel_hi:[1,1,1]
	v_pk_fma_f32 v[106:107], v[44:45], v[62:63], v[106:107] op_sel:[1,0,0] op_sel_hi:[1,1,1]
	v_pk_fma_f32 v[108:109], v[46:47], v[56:57], v[108:109] op_sel_hi:[0,1,1]
	v_pk_fma_f32 v[110:111], v[46:47], v[58:59], v[110:111] op_sel_hi:[0,1,1]
	v_pk_fma_f32 v[112:113], v[46:47], v[60:61], v[112:113] op_sel_hi:[0,1,1]
	v_pk_fma_f32 v[114:115], v[46:47], v[62:63], v[114:115] op_sel_hi:[0,1,1]
	v_pk_fma_f32 v[116:117], v[46:47], v[56:57], v[116:117] op_sel:[1,0,0] op_sel_hi:[1,1,1]
	v_pk_fma_f32 v[118:119], v[46:47], v[58:59], v[118:119] op_sel:[1,0,0] op_sel_hi:[1,1,1]
	v_pk_fma_f32 v[120:121], v[46:47], v[60:61], v[120:121] op_sel:[1,0,0] op_sel_hi:[1,1,1]
	v_pk_fma_f32 v[122:123], v[46:47], v[62:63], v[122:123] op_sel:[1,0,0] op_sel_hi:[1,1,1]
	ds_read_b128 v[44:47], v74 offset:2816
	s_waitcnt lgkmcnt(2)
	v_cvt_f32_f16_e32 v56, v204
	v_cvt_f32_f16_sdwa v57, v204 dst_sel:DWORD dst_unused:UNUSED_PAD src0_sel:WORD_1
	v_cvt_f32_f16_e32 v58, v205
	v_cvt_f32_f16_sdwa v59, v205 dst_sel:DWORD dst_unused:UNUSED_PAD src0_sel:WORD_1
	v_cvt_f32_f16_e32 v60, v206
	v_cvt_f32_f16_sdwa v61, v206 dst_sel:DWORD dst_unused:UNUSED_PAD src0_sel:WORD_1
	v_cvt_f32_f16_e32 v62, v207
	v_cvt_f32_f16_sdwa v63, v207 dst_sel:DWORD dst_unused:UNUSED_PAD src0_sel:WORD_1
	v_pk_fma_f32 v[92:93], v[48:49], v[56:57], v[92:93] op_sel_hi:[0,1,1]
	v_pk_fma_f32 v[94:95], v[48:49], v[58:59], v[94:95] op_sel_hi:[0,1,1]
	v_pk_fma_f32 v[96:97], v[48:49], v[60:61], v[96:97] op_sel_hi:[0,1,1]
	v_pk_fma_f32 v[98:99], v[48:49], v[62:63], v[98:99] op_sel_hi:[0,1,1]
	v_pk_fma_f32 v[100:101], v[48:49], v[56:57], v[100:101] op_sel:[1,0,0] op_sel_hi:[1,1,1]
	v_pk_fma_f32 v[102:103], v[48:49], v[58:59], v[102:103] op_sel:[1,0,0] op_sel_hi:[1,1,1]
	v_pk_fma_f32 v[104:105], v[48:49], v[60:61], v[104:105] op_sel:[1,0,0] op_sel_hi:[1,1,1]
	v_pk_fma_f32 v[106:107], v[48:49], v[62:63], v[106:107] op_sel:[1,0,0] op_sel_hi:[1,1,1]
	v_pk_fma_f32 v[108:109], v[50:51], v[56:57], v[108:109] op_sel_hi:[0,1,1]
	v_pk_fma_f32 v[110:111], v[50:51], v[58:59], v[110:111] op_sel_hi:[0,1,1]
	v_pk_fma_f32 v[112:113], v[50:51], v[60:61], v[112:113] op_sel_hi:[0,1,1]
	v_pk_fma_f32 v[114:115], v[50:51], v[62:63], v[114:115] op_sel_hi:[0,1,1]
	v_pk_fma_f32 v[116:117], v[50:51], v[56:57], v[116:117] op_sel:[1,0,0] op_sel_hi:[1,1,1]
	v_pk_fma_f32 v[118:119], v[50:51], v[58:59], v[118:119] op_sel:[1,0,0] op_sel_hi:[1,1,1]
	v_pk_fma_f32 v[120:121], v[50:51], v[60:61], v[120:121] op_sel:[1,0,0] op_sel_hi:[1,1,1]
	v_pk_fma_f32 v[122:123], v[50:51], v[62:63], v[122:123] op_sel:[1,0,0] op_sel_hi:[1,1,1]
	ds_read_b128 v[48:51], v74 offset:2944
	s_waitcnt lgkmcnt(2)
	v_cvt_f32_f16_e32 v56, v208
	v_cvt_f32_f16_sdwa v57, v208 dst_sel:DWORD dst_unused:UNUSED_PAD src0_sel:WORD_1
	v_cvt_f32_f16_e32 v58, v209
	v_cvt_f32_f16_sdwa v59, v209 dst_sel:DWORD dst_unused:UNUSED_PAD src0_sel:WORD_1
	v_cvt_f32_f16_e32 v60, v210
	v_cvt_f32_f16_sdwa v61, v210 dst_sel:DWORD dst_unused:UNUSED_PAD src0_sel:WORD_1
	v_cvt_f32_f16_e32 v62, v211
	v_cvt_f32_f16_sdwa v63, v211 dst_sel:DWORD dst_unused:UNUSED_PAD src0_sel:WORD_1
	v_pk_fma_f32 v[92:93], v[52:53], v[56:57], v[92:93] op_sel_hi:[0,1,1]
	v_pk_fma_f32 v[94:95], v[52:53], v[58:59], v[94:95] op_sel_hi:[0,1,1]
	v_pk_fma_f32 v[96:97], v[52:53], v[60:61], v[96:97] op_sel_hi:[0,1,1]
	v_pk_fma_f32 v[98:99], v[52:53], v[62:63], v[98:99] op_sel_hi:[0,1,1]
	v_pk_fma_f32 v[100:101], v[52:53], v[56:57], v[100:101] op_sel:[1,0,0] op_sel_hi:[1,1,1]
	v_pk_fma_f32 v[102:103], v[52:53], v[58:59], v[102:103] op_sel:[1,0,0] op_sel_hi:[1,1,1]
	v_pk_fma_f32 v[104:105], v[52:53], v[60:61], v[104:105] op_sel:[1,0,0] op_sel_hi:[1,1,1]
	v_pk_fma_f32 v[106:107], v[52:53], v[62:63], v[106:107] op_sel:[1,0,0] op_sel_hi:[1,1,1]
	v_pk_fma_f32 v[108:109], v[54:55], v[56:57], v[108:109] op_sel_hi:[0,1,1]
	v_pk_fma_f32 v[110:111], v[54:55], v[58:59], v[110:111] op_sel_hi:[0,1,1]
	v_pk_fma_f32 v[112:113], v[54:55], v[60:61], v[112:113] op_sel_hi:[0,1,1]
	v_pk_fma_f32 v[114:115], v[54:55], v[62:63], v[114:115] op_sel_hi:[0,1,1]
	v_pk_fma_f32 v[116:117], v[54:55], v[56:57], v[116:117] op_sel:[1,0,0] op_sel_hi:[1,1,1]
	v_pk_fma_f32 v[118:119], v[54:55], v[58:59], v[118:119] op_sel:[1,0,0] op_sel_hi:[1,1,1]
	v_pk_fma_f32 v[120:121], v[54:55], v[60:61], v[120:121] op_sel:[1,0,0] op_sel_hi:[1,1,1]
	v_pk_fma_f32 v[122:123], v[54:55], v[62:63], v[122:123] op_sel:[1,0,0] op_sel_hi:[1,1,1]
	ds_read_b128 v[52:55], v74 offset:3072
	s_waitcnt lgkmcnt(2)
	v_cvt_f32_f16_e32 v56, v212
	v_cvt_f32_f16_sdwa v57, v212 dst_sel:DWORD dst_unused:UNUSED_PAD src0_sel:WORD_1
	v_cvt_f32_f16_e32 v58, v213
	v_cvt_f32_f16_sdwa v59, v213 dst_sel:DWORD dst_unused:UNUSED_PAD src0_sel:WORD_1
	v_cvt_f32_f16_e32 v60, v214
	v_cvt_f32_f16_sdwa v61, v214 dst_sel:DWORD dst_unused:UNUSED_PAD src0_sel:WORD_1
	v_cvt_f32_f16_e32 v62, v215
	v_cvt_f32_f16_sdwa v63, v215 dst_sel:DWORD dst_unused:UNUSED_PAD src0_sel:WORD_1
	v_pk_fma_f32 v[92:93], v[44:45], v[56:57], v[92:93] op_sel_hi:[0,1,1]
	v_pk_fma_f32 v[94:95], v[44:45], v[58:59], v[94:95] op_sel_hi:[0,1,1]
	v_pk_fma_f32 v[96:97], v[44:45], v[60:61], v[96:97] op_sel_hi:[0,1,1]
	v_pk_fma_f32 v[98:99], v[44:45], v[62:63], v[98:99] op_sel_hi:[0,1,1]
	v_pk_fma_f32 v[100:101], v[44:45], v[56:57], v[100:101] op_sel:[1,0,0] op_sel_hi:[1,1,1]
	v_pk_fma_f32 v[102:103], v[44:45], v[58:59], v[102:103] op_sel:[1,0,0] op_sel_hi:[1,1,1]
	v_pk_fma_f32 v[104:105], v[44:45], v[60:61], v[104:105] op_sel:[1,0,0] op_sel_hi:[1,1,1]
	v_pk_fma_f32 v[106:107], v[44:45], v[62:63], v[106:107] op_sel:[1,0,0] op_sel_hi:[1,1,1]
	v_pk_fma_f32 v[108:109], v[46:47], v[56:57], v[108:109] op_sel_hi:[0,1,1]
	v_pk_fma_f32 v[110:111], v[46:47], v[58:59], v[110:111] op_sel_hi:[0,1,1]
	v_pk_fma_f32 v[112:113], v[46:47], v[60:61], v[112:113] op_sel_hi:[0,1,1]
	v_pk_fma_f32 v[114:115], v[46:47], v[62:63], v[114:115] op_sel_hi:[0,1,1]
	v_pk_fma_f32 v[116:117], v[46:47], v[56:57], v[116:117] op_sel:[1,0,0] op_sel_hi:[1,1,1]
	v_pk_fma_f32 v[118:119], v[46:47], v[58:59], v[118:119] op_sel:[1,0,0] op_sel_hi:[1,1,1]
	v_pk_fma_f32 v[120:121], v[46:47], v[60:61], v[120:121] op_sel:[1,0,0] op_sel_hi:[1,1,1]
	v_pk_fma_f32 v[122:123], v[46:47], v[62:63], v[122:123] op_sel:[1,0,0] op_sel_hi:[1,1,1]
	ds_read_b128 v[44:47], v74 offset:3200
	s_waitcnt lgkmcnt(2)
	v_cvt_f32_f16_e32 v56, v216
	v_cvt_f32_f16_sdwa v57, v216 dst_sel:DWORD dst_unused:UNUSED_PAD src0_sel:WORD_1
	v_cvt_f32_f16_e32 v58, v217
	v_cvt_f32_f16_sdwa v59, v217 dst_sel:DWORD dst_unused:UNUSED_PAD src0_sel:WORD_1
	v_cvt_f32_f16_e32 v60, v218
	v_cvt_f32_f16_sdwa v61, v218 dst_sel:DWORD dst_unused:UNUSED_PAD src0_sel:WORD_1
	v_cvt_f32_f16_e32 v62, v219
	v_cvt_f32_f16_sdwa v63, v219 dst_sel:DWORD dst_unused:UNUSED_PAD src0_sel:WORD_1
	v_pk_fma_f32 v[92:93], v[48:49], v[56:57], v[92:93] op_sel_hi:[0,1,1]
	v_pk_fma_f32 v[94:95], v[48:49], v[58:59], v[94:95] op_sel_hi:[0,1,1]
	v_pk_fma_f32 v[96:97], v[48:49], v[60:61], v[96:97] op_sel_hi:[0,1,1]
	v_pk_fma_f32 v[98:99], v[48:49], v[62:63], v[98:99] op_sel_hi:[0,1,1]
	v_pk_fma_f32 v[100:101], v[48:49], v[56:57], v[100:101] op_sel:[1,0,0] op_sel_hi:[1,1,1]
	v_pk_fma_f32 v[102:103], v[48:49], v[58:59], v[102:103] op_sel:[1,0,0] op_sel_hi:[1,1,1]
	v_pk_fma_f32 v[104:105], v[48:49], v[60:61], v[104:105] op_sel:[1,0,0] op_sel_hi:[1,1,1]
	v_pk_fma_f32 v[106:107], v[48:49], v[62:63], v[106:107] op_sel:[1,0,0] op_sel_hi:[1,1,1]
	v_pk_fma_f32 v[108:109], v[50:51], v[56:57], v[108:109] op_sel_hi:[0,1,1]
	v_pk_fma_f32 v[110:111], v[50:51], v[58:59], v[110:111] op_sel_hi:[0,1,1]
	v_pk_fma_f32 v[112:113], v[50:51], v[60:61], v[112:113] op_sel_hi:[0,1,1]
	v_pk_fma_f32 v[114:115], v[50:51], v[62:63], v[114:115] op_sel_hi:[0,1,1]
	v_pk_fma_f32 v[116:117], v[50:51], v[56:57], v[116:117] op_sel:[1,0,0] op_sel_hi:[1,1,1]
	v_pk_fma_f32 v[118:119], v[50:51], v[58:59], v[118:119] op_sel:[1,0,0] op_sel_hi:[1,1,1]
	v_pk_fma_f32 v[120:121], v[50:51], v[60:61], v[120:121] op_sel:[1,0,0] op_sel_hi:[1,1,1]
	v_pk_fma_f32 v[122:123], v[50:51], v[62:63], v[122:123] op_sel:[1,0,0] op_sel_hi:[1,1,1]
	ds_read_b128 v[48:51], v74 offset:3328
	s_waitcnt lgkmcnt(2)
	v_cvt_f32_f16_e32 v56, v220
	v_cvt_f32_f16_sdwa v57, v220 dst_sel:DWORD dst_unused:UNUSED_PAD src0_sel:WORD_1
	v_cvt_f32_f16_e32 v58, v221
	v_cvt_f32_f16_sdwa v59, v221 dst_sel:DWORD dst_unused:UNUSED_PAD src0_sel:WORD_1
	v_cvt_f32_f16_e32 v60, v222
	v_cvt_f32_f16_sdwa v61, v222 dst_sel:DWORD dst_unused:UNUSED_PAD src0_sel:WORD_1
	v_cvt_f32_f16_e32 v62, v223
	v_cvt_f32_f16_sdwa v63, v223 dst_sel:DWORD dst_unused:UNUSED_PAD src0_sel:WORD_1
	v_pk_fma_f32 v[92:93], v[52:53], v[56:57], v[92:93] op_sel_hi:[0,1,1]
	v_pk_fma_f32 v[94:95], v[52:53], v[58:59], v[94:95] op_sel_hi:[0,1,1]
	v_pk_fma_f32 v[96:97], v[52:53], v[60:61], v[96:97] op_sel_hi:[0,1,1]
	v_pk_fma_f32 v[98:99], v[52:53], v[62:63], v[98:99] op_sel_hi:[0,1,1]
	v_pk_fma_f32 v[100:101], v[52:53], v[56:57], v[100:101] op_sel:[1,0,0] op_sel_hi:[1,1,1]
	v_pk_fma_f32 v[102:103], v[52:53], v[58:59], v[102:103] op_sel:[1,0,0] op_sel_hi:[1,1,1]
	v_pk_fma_f32 v[104:105], v[52:53], v[60:61], v[104:105] op_sel:[1,0,0] op_sel_hi:[1,1,1]
	v_pk_fma_f32 v[106:107], v[52:53], v[62:63], v[106:107] op_sel:[1,0,0] op_sel_hi:[1,1,1]
	v_pk_fma_f32 v[108:109], v[54:55], v[56:57], v[108:109] op_sel_hi:[0,1,1]
	v_pk_fma_f32 v[110:111], v[54:55], v[58:59], v[110:111] op_sel_hi:[0,1,1]
	v_pk_fma_f32 v[112:113], v[54:55], v[60:61], v[112:113] op_sel_hi:[0,1,1]
	v_pk_fma_f32 v[114:115], v[54:55], v[62:63], v[114:115] op_sel_hi:[0,1,1]
	v_pk_fma_f32 v[116:117], v[54:55], v[56:57], v[116:117] op_sel:[1,0,0] op_sel_hi:[1,1,1]
	v_pk_fma_f32 v[118:119], v[54:55], v[58:59], v[118:119] op_sel:[1,0,0] op_sel_hi:[1,1,1]
	v_pk_fma_f32 v[120:121], v[54:55], v[60:61], v[120:121] op_sel:[1,0,0] op_sel_hi:[1,1,1]
	v_pk_fma_f32 v[122:123], v[54:55], v[62:63], v[122:123] op_sel:[1,0,0] op_sel_hi:[1,1,1]
	ds_read_b128 v[52:55], v74 offset:3456
	s_waitcnt lgkmcnt(2)
	v_cvt_f32_f16_e32 v56, v224
	v_cvt_f32_f16_sdwa v57, v224 dst_sel:DWORD dst_unused:UNUSED_PAD src0_sel:WORD_1
	v_cvt_f32_f16_e32 v58, v225
	v_cvt_f32_f16_sdwa v59, v225 dst_sel:DWORD dst_unused:UNUSED_PAD src0_sel:WORD_1
	v_cvt_f32_f16_e32 v60, v226
	v_cvt_f32_f16_sdwa v61, v226 dst_sel:DWORD dst_unused:UNUSED_PAD src0_sel:WORD_1
	v_cvt_f32_f16_e32 v62, v227
	v_cvt_f32_f16_sdwa v63, v227 dst_sel:DWORD dst_unused:UNUSED_PAD src0_sel:WORD_1
	v_pk_fma_f32 v[92:93], v[44:45], v[56:57], v[92:93] op_sel_hi:[0,1,1]
	v_pk_fma_f32 v[94:95], v[44:45], v[58:59], v[94:95] op_sel_hi:[0,1,1]
	v_pk_fma_f32 v[96:97], v[44:45], v[60:61], v[96:97] op_sel_hi:[0,1,1]
	v_pk_fma_f32 v[98:99], v[44:45], v[62:63], v[98:99] op_sel_hi:[0,1,1]
	v_pk_fma_f32 v[100:101], v[44:45], v[56:57], v[100:101] op_sel:[1,0,0] op_sel_hi:[1,1,1]
	v_pk_fma_f32 v[102:103], v[44:45], v[58:59], v[102:103] op_sel:[1,0,0] op_sel_hi:[1,1,1]
	v_pk_fma_f32 v[104:105], v[44:45], v[60:61], v[104:105] op_sel:[1,0,0] op_sel_hi:[1,1,1]
	v_pk_fma_f32 v[106:107], v[44:45], v[62:63], v[106:107] op_sel:[1,0,0] op_sel_hi:[1,1,1]
	v_pk_fma_f32 v[108:109], v[46:47], v[56:57], v[108:109] op_sel_hi:[0,1,1]
	v_pk_fma_f32 v[110:111], v[46:47], v[58:59], v[110:111] op_sel_hi:[0,1,1]
	v_pk_fma_f32 v[112:113], v[46:47], v[60:61], v[112:113] op_sel_hi:[0,1,1]
	v_pk_fma_f32 v[114:115], v[46:47], v[62:63], v[114:115] op_sel_hi:[0,1,1]
	v_pk_fma_f32 v[116:117], v[46:47], v[56:57], v[116:117] op_sel:[1,0,0] op_sel_hi:[1,1,1]
	v_pk_fma_f32 v[118:119], v[46:47], v[58:59], v[118:119] op_sel:[1,0,0] op_sel_hi:[1,1,1]
	v_pk_fma_f32 v[120:121], v[46:47], v[60:61], v[120:121] op_sel:[1,0,0] op_sel_hi:[1,1,1]
	v_pk_fma_f32 v[122:123], v[46:47], v[62:63], v[122:123] op_sel:[1,0,0] op_sel_hi:[1,1,1]
	ds_read_b128 v[44:47], v74 offset:3584
	s_waitcnt lgkmcnt(2)
	v_cvt_f32_f16_e32 v56, v228
	v_cvt_f32_f16_sdwa v57, v228 dst_sel:DWORD dst_unused:UNUSED_PAD src0_sel:WORD_1
	v_cvt_f32_f16_e32 v58, v229
	v_cvt_f32_f16_sdwa v59, v229 dst_sel:DWORD dst_unused:UNUSED_PAD src0_sel:WORD_1
	v_cvt_f32_f16_e32 v60, v230
	v_cvt_f32_f16_sdwa v61, v230 dst_sel:DWORD dst_unused:UNUSED_PAD src0_sel:WORD_1
	v_cvt_f32_f16_e32 v62, v231
	v_cvt_f32_f16_sdwa v63, v231 dst_sel:DWORD dst_unused:UNUSED_PAD src0_sel:WORD_1
	v_pk_fma_f32 v[92:93], v[48:49], v[56:57], v[92:93] op_sel_hi:[0,1,1]
	v_pk_fma_f32 v[94:95], v[48:49], v[58:59], v[94:95] op_sel_hi:[0,1,1]
	v_pk_fma_f32 v[96:97], v[48:49], v[60:61], v[96:97] op_sel_hi:[0,1,1]
	v_pk_fma_f32 v[98:99], v[48:49], v[62:63], v[98:99] op_sel_hi:[0,1,1]
	v_pk_fma_f32 v[100:101], v[48:49], v[56:57], v[100:101] op_sel:[1,0,0] op_sel_hi:[1,1,1]
	v_pk_fma_f32 v[102:103], v[48:49], v[58:59], v[102:103] op_sel:[1,0,0] op_sel_hi:[1,1,1]
	v_pk_fma_f32 v[104:105], v[48:49], v[60:61], v[104:105] op_sel:[1,0,0] op_sel_hi:[1,1,1]
	v_pk_fma_f32 v[106:107], v[48:49], v[62:63], v[106:107] op_sel:[1,0,0] op_sel_hi:[1,1,1]
	v_pk_fma_f32 v[108:109], v[50:51], v[56:57], v[108:109] op_sel_hi:[0,1,1]
	v_pk_fma_f32 v[110:111], v[50:51], v[58:59], v[110:111] op_sel_hi:[0,1,1]
	v_pk_fma_f32 v[112:113], v[50:51], v[60:61], v[112:113] op_sel_hi:[0,1,1]
	v_pk_fma_f32 v[114:115], v[50:51], v[62:63], v[114:115] op_sel_hi:[0,1,1]
	v_pk_fma_f32 v[116:117], v[50:51], v[56:57], v[116:117] op_sel:[1,0,0] op_sel_hi:[1,1,1]
	v_pk_fma_f32 v[118:119], v[50:51], v[58:59], v[118:119] op_sel:[1,0,0] op_sel_hi:[1,1,1]
	v_pk_fma_f32 v[120:121], v[50:51], v[60:61], v[120:121] op_sel:[1,0,0] op_sel_hi:[1,1,1]
	v_pk_fma_f32 v[122:123], v[50:51], v[62:63], v[122:123] op_sel:[1,0,0] op_sel_hi:[1,1,1]
	ds_read_b128 v[48:51], v74 offset:3712
	s_waitcnt lgkmcnt(2)
	v_cvt_f32_f16_e32 v56, v232
	v_cvt_f32_f16_sdwa v57, v232 dst_sel:DWORD dst_unused:UNUSED_PAD src0_sel:WORD_1
	v_cvt_f32_f16_e32 v58, v233
	v_cvt_f32_f16_sdwa v59, v233 dst_sel:DWORD dst_unused:UNUSED_PAD src0_sel:WORD_1
	v_cvt_f32_f16_e32 v60, v234
	v_cvt_f32_f16_sdwa v61, v234 dst_sel:DWORD dst_unused:UNUSED_PAD src0_sel:WORD_1
	v_cvt_f32_f16_e32 v62, v235
	v_cvt_f32_f16_sdwa v63, v235 dst_sel:DWORD dst_unused:UNUSED_PAD src0_sel:WORD_1
	v_pk_fma_f32 v[92:93], v[52:53], v[56:57], v[92:93] op_sel_hi:[0,1,1]
	v_pk_fma_f32 v[94:95], v[52:53], v[58:59], v[94:95] op_sel_hi:[0,1,1]
	v_pk_fma_f32 v[96:97], v[52:53], v[60:61], v[96:97] op_sel_hi:[0,1,1]
	v_pk_fma_f32 v[98:99], v[52:53], v[62:63], v[98:99] op_sel_hi:[0,1,1]
	v_pk_fma_f32 v[100:101], v[52:53], v[56:57], v[100:101] op_sel:[1,0,0] op_sel_hi:[1,1,1]
	v_pk_fma_f32 v[102:103], v[52:53], v[58:59], v[102:103] op_sel:[1,0,0] op_sel_hi:[1,1,1]
	v_pk_fma_f32 v[104:105], v[52:53], v[60:61], v[104:105] op_sel:[1,0,0] op_sel_hi:[1,1,1]
	v_pk_fma_f32 v[106:107], v[52:53], v[62:63], v[106:107] op_sel:[1,0,0] op_sel_hi:[1,1,1]
	v_pk_fma_f32 v[108:109], v[54:55], v[56:57], v[108:109] op_sel_hi:[0,1,1]
	v_pk_fma_f32 v[110:111], v[54:55], v[58:59], v[110:111] op_sel_hi:[0,1,1]
	v_pk_fma_f32 v[112:113], v[54:55], v[60:61], v[112:113] op_sel_hi:[0,1,1]
	v_pk_fma_f32 v[114:115], v[54:55], v[62:63], v[114:115] op_sel_hi:[0,1,1]
	v_pk_fma_f32 v[116:117], v[54:55], v[56:57], v[116:117] op_sel:[1,0,0] op_sel_hi:[1,1,1]
	v_pk_fma_f32 v[118:119], v[54:55], v[58:59], v[118:119] op_sel:[1,0,0] op_sel_hi:[1,1,1]
	v_pk_fma_f32 v[120:121], v[54:55], v[60:61], v[120:121] op_sel:[1,0,0] op_sel_hi:[1,1,1]
	v_pk_fma_f32 v[122:123], v[54:55], v[62:63], v[122:123] op_sel:[1,0,0] op_sel_hi:[1,1,1]
	ds_read_b128 v[52:55], v74 offset:3840
	s_waitcnt lgkmcnt(2)
	v_cvt_f32_f16_e32 v56, v236
	v_cvt_f32_f16_sdwa v57, v236 dst_sel:DWORD dst_unused:UNUSED_PAD src0_sel:WORD_1
	v_cvt_f32_f16_e32 v58, v237
	v_cvt_f32_f16_sdwa v59, v237 dst_sel:DWORD dst_unused:UNUSED_PAD src0_sel:WORD_1
	v_cvt_f32_f16_e32 v60, v238
	v_cvt_f32_f16_sdwa v61, v238 dst_sel:DWORD dst_unused:UNUSED_PAD src0_sel:WORD_1
	v_cvt_f32_f16_e32 v62, v239
	v_cvt_f32_f16_sdwa v63, v239 dst_sel:DWORD dst_unused:UNUSED_PAD src0_sel:WORD_1
	v_pk_fma_f32 v[92:93], v[44:45], v[56:57], v[92:93] op_sel_hi:[0,1,1]
	v_pk_fma_f32 v[94:95], v[44:45], v[58:59], v[94:95] op_sel_hi:[0,1,1]
	v_pk_fma_f32 v[96:97], v[44:45], v[60:61], v[96:97] op_sel_hi:[0,1,1]
	v_pk_fma_f32 v[98:99], v[44:45], v[62:63], v[98:99] op_sel_hi:[0,1,1]
	v_pk_fma_f32 v[100:101], v[44:45], v[56:57], v[100:101] op_sel:[1,0,0] op_sel_hi:[1,1,1]
	v_pk_fma_f32 v[102:103], v[44:45], v[58:59], v[102:103] op_sel:[1,0,0] op_sel_hi:[1,1,1]
	v_pk_fma_f32 v[104:105], v[44:45], v[60:61], v[104:105] op_sel:[1,0,0] op_sel_hi:[1,1,1]
	v_pk_fma_f32 v[106:107], v[44:45], v[62:63], v[106:107] op_sel:[1,0,0] op_sel_hi:[1,1,1]
	v_pk_fma_f32 v[108:109], v[46:47], v[56:57], v[108:109] op_sel_hi:[0,1,1]
	v_pk_fma_f32 v[110:111], v[46:47], v[58:59], v[110:111] op_sel_hi:[0,1,1]
	v_pk_fma_f32 v[112:113], v[46:47], v[60:61], v[112:113] op_sel_hi:[0,1,1]
	v_pk_fma_f32 v[114:115], v[46:47], v[62:63], v[114:115] op_sel_hi:[0,1,1]
	v_pk_fma_f32 v[116:117], v[46:47], v[56:57], v[116:117] op_sel:[1,0,0] op_sel_hi:[1,1,1]
	v_pk_fma_f32 v[118:119], v[46:47], v[58:59], v[118:119] op_sel:[1,0,0] op_sel_hi:[1,1,1]
	v_pk_fma_f32 v[120:121], v[46:47], v[60:61], v[120:121] op_sel:[1,0,0] op_sel_hi:[1,1,1]
	v_pk_fma_f32 v[122:123], v[46:47], v[62:63], v[122:123] op_sel:[1,0,0] op_sel_hi:[1,1,1]
	ds_read_b128 v[44:47], v74 offset:3968
	s_waitcnt lgkmcnt(2)
	v_cvt_f32_f16_e32 v56, v240
	v_cvt_f32_f16_sdwa v57, v240 dst_sel:DWORD dst_unused:UNUSED_PAD src0_sel:WORD_1
	v_cvt_f32_f16_e32 v58, v241
	v_cvt_f32_f16_sdwa v59, v241 dst_sel:DWORD dst_unused:UNUSED_PAD src0_sel:WORD_1
	v_cvt_f32_f16_e32 v60, v242
	v_cvt_f32_f16_sdwa v61, v242 dst_sel:DWORD dst_unused:UNUSED_PAD src0_sel:WORD_1
	v_cvt_f32_f16_e32 v62, v243
	v_cvt_f32_f16_sdwa v63, v243 dst_sel:DWORD dst_unused:UNUSED_PAD src0_sel:WORD_1
	v_pk_fma_f32 v[92:93], v[48:49], v[56:57], v[92:93] op_sel_hi:[0,1,1]
	v_pk_fma_f32 v[94:95], v[48:49], v[58:59], v[94:95] op_sel_hi:[0,1,1]
	v_pk_fma_f32 v[96:97], v[48:49], v[60:61], v[96:97] op_sel_hi:[0,1,1]
	v_pk_fma_f32 v[98:99], v[48:49], v[62:63], v[98:99] op_sel_hi:[0,1,1]
	v_pk_fma_f32 v[100:101], v[48:49], v[56:57], v[100:101] op_sel:[1,0,0] op_sel_hi:[1,1,1]
	v_pk_fma_f32 v[102:103], v[48:49], v[58:59], v[102:103] op_sel:[1,0,0] op_sel_hi:[1,1,1]
	v_pk_fma_f32 v[104:105], v[48:49], v[60:61], v[104:105] op_sel:[1,0,0] op_sel_hi:[1,1,1]
	v_pk_fma_f32 v[106:107], v[48:49], v[62:63], v[106:107] op_sel:[1,0,0] op_sel_hi:[1,1,1]
	v_pk_fma_f32 v[108:109], v[50:51], v[56:57], v[108:109] op_sel_hi:[0,1,1]
	v_pk_fma_f32 v[110:111], v[50:51], v[58:59], v[110:111] op_sel_hi:[0,1,1]
	v_pk_fma_f32 v[112:113], v[50:51], v[60:61], v[112:113] op_sel_hi:[0,1,1]
	v_pk_fma_f32 v[114:115], v[50:51], v[62:63], v[114:115] op_sel_hi:[0,1,1]
	v_pk_fma_f32 v[116:117], v[50:51], v[56:57], v[116:117] op_sel:[1,0,0] op_sel_hi:[1,1,1]
	v_pk_fma_f32 v[118:119], v[50:51], v[58:59], v[118:119] op_sel:[1,0,0] op_sel_hi:[1,1,1]
	v_pk_fma_f32 v[120:121], v[50:51], v[60:61], v[120:121] op_sel:[1,0,0] op_sel_hi:[1,1,1]
	v_pk_fma_f32 v[122:123], v[50:51], v[62:63], v[122:123] op_sel:[1,0,0] op_sel_hi:[1,1,1]
	s_waitcnt lgkmcnt(1)
	v_cvt_f32_f16_e32 v56, v244
	v_cvt_f32_f16_sdwa v57, v244 dst_sel:DWORD dst_unused:UNUSED_PAD src0_sel:WORD_1
	v_cvt_f32_f16_e32 v58, v245
	v_cvt_f32_f16_sdwa v59, v245 dst_sel:DWORD dst_unused:UNUSED_PAD src0_sel:WORD_1
	v_cvt_f32_f16_e32 v60, v246
	v_cvt_f32_f16_sdwa v61, v246 dst_sel:DWORD dst_unused:UNUSED_PAD src0_sel:WORD_1
	v_cvt_f32_f16_e32 v62, v247
	v_cvt_f32_f16_sdwa v63, v247 dst_sel:DWORD dst_unused:UNUSED_PAD src0_sel:WORD_1
	v_pk_fma_f32 v[92:93], v[52:53], v[56:57], v[92:93] op_sel_hi:[0,1,1]
	v_pk_fma_f32 v[94:95], v[52:53], v[58:59], v[94:95] op_sel_hi:[0,1,1]
	v_pk_fma_f32 v[96:97], v[52:53], v[60:61], v[96:97] op_sel_hi:[0,1,1]
	v_pk_fma_f32 v[98:99], v[52:53], v[62:63], v[98:99] op_sel_hi:[0,1,1]
	v_pk_fma_f32 v[100:101], v[52:53], v[56:57], v[100:101] op_sel:[1,0,0] op_sel_hi:[1,1,1]
	v_pk_fma_f32 v[102:103], v[52:53], v[58:59], v[102:103] op_sel:[1,0,0] op_sel_hi:[1,1,1]
	v_pk_fma_f32 v[104:105], v[52:53], v[60:61], v[104:105] op_sel:[1,0,0] op_sel_hi:[1,1,1]
	v_pk_fma_f32 v[106:107], v[52:53], v[62:63], v[106:107] op_sel:[1,0,0] op_sel_hi:[1,1,1]
	v_pk_fma_f32 v[108:109], v[54:55], v[56:57], v[108:109] op_sel_hi:[0,1,1]
	v_pk_fma_f32 v[110:111], v[54:55], v[58:59], v[110:111] op_sel_hi:[0,1,1]
	v_pk_fma_f32 v[112:113], v[54:55], v[60:61], v[112:113] op_sel_hi:[0,1,1]
	v_pk_fma_f32 v[114:115], v[54:55], v[62:63], v[114:115] op_sel_hi:[0,1,1]
	v_pk_fma_f32 v[116:117], v[54:55], v[56:57], v[116:117] op_sel:[1,0,0] op_sel_hi:[1,1,1]
	v_pk_fma_f32 v[118:119], v[54:55], v[58:59], v[118:119] op_sel:[1,0,0] op_sel_hi:[1,1,1]
	v_pk_fma_f32 v[120:121], v[54:55], v[60:61], v[120:121] op_sel:[1,0,0] op_sel_hi:[1,1,1]
	v_pk_fma_f32 v[122:123], v[54:55], v[62:63], v[122:123] op_sel:[1,0,0] op_sel_hi:[1,1,1]
	s_waitcnt lgkmcnt(0)
	v_cvt_f32_f16_e32 v56, v248
	v_cvt_f32_f16_sdwa v57, v248 dst_sel:DWORD dst_unused:UNUSED_PAD src0_sel:WORD_1
	v_cvt_f32_f16_e32 v58, v249
	v_cvt_f32_f16_sdwa v59, v249 dst_sel:DWORD dst_unused:UNUSED_PAD src0_sel:WORD_1
	v_cvt_f32_f16_e32 v60, v250
	v_cvt_f32_f16_sdwa v61, v250 dst_sel:DWORD dst_unused:UNUSED_PAD src0_sel:WORD_1
	v_cvt_f32_f16_e32 v62, v251
	v_cvt_f32_f16_sdwa v63, v251 dst_sel:DWORD dst_unused:UNUSED_PAD src0_sel:WORD_1
	v_pk_fma_f32 v[92:93], v[44:45], v[56:57], v[92:93] op_sel_hi:[0,1,1]
	v_pk_fma_f32 v[94:95], v[44:45], v[58:59], v[94:95] op_sel_hi:[0,1,1]
	v_pk_fma_f32 v[96:97], v[44:45], v[60:61], v[96:97] op_sel_hi:[0,1,1]
	v_pk_fma_f32 v[98:99], v[44:45], v[62:63], v[98:99] op_sel_hi:[0,1,1]
	v_pk_fma_f32 v[100:101], v[44:45], v[56:57], v[100:101] op_sel:[1,0,0] op_sel_hi:[1,1,1]
	v_pk_fma_f32 v[102:103], v[44:45], v[58:59], v[102:103] op_sel:[1,0,0] op_sel_hi:[1,1,1]
	v_pk_fma_f32 v[104:105], v[44:45], v[60:61], v[104:105] op_sel:[1,0,0] op_sel_hi:[1,1,1]
	v_pk_fma_f32 v[106:107], v[44:45], v[62:63], v[106:107] op_sel:[1,0,0] op_sel_hi:[1,1,1]
	v_pk_fma_f32 v[108:109], v[46:47], v[56:57], v[108:109] op_sel_hi:[0,1,1]
	v_pk_fma_f32 v[110:111], v[46:47], v[58:59], v[110:111] op_sel_hi:[0,1,1]
	v_pk_fma_f32 v[112:113], v[46:47], v[60:61], v[112:113] op_sel_hi:[0,1,1]
	v_pk_fma_f32 v[114:115], v[46:47], v[62:63], v[114:115] op_sel_hi:[0,1,1]
	v_pk_fma_f32 v[116:117], v[46:47], v[56:57], v[116:117] op_sel:[1,0,0] op_sel_hi:[1,1,1]
	v_pk_fma_f32 v[118:119], v[46:47], v[58:59], v[118:119] op_sel:[1,0,0] op_sel_hi:[1,1,1]
	v_pk_fma_f32 v[120:121], v[46:47], v[60:61], v[120:121] op_sel:[1,0,0] op_sel_hi:[1,1,1]
	v_pk_fma_f32 v[122:123], v[46:47], v[62:63], v[122:123] op_sel:[1,0,0] op_sel_hi:[1,1,1]
	v_add_f32_dpp v92, v92, v92 quad_perm:[1,0,3,2] row_mask:0xf bank_mask:0xf bound_ctrl:1
	v_add_f32_dpp v93, v93, v93 quad_perm:[1,0,3,2] row_mask:0xf bank_mask:0xf bound_ctrl:1
	v_add_f32_dpp v94, v94, v94 quad_perm:[1,0,3,2] row_mask:0xf bank_mask:0xf bound_ctrl:1
	v_add_f32_dpp v95, v95, v95 quad_perm:[1,0,3,2] row_mask:0xf bank_mask:0xf bound_ctrl:1
	v_add_f32_dpp v96, v96, v96 quad_perm:[1,0,3,2] row_mask:0xf bank_mask:0xf bound_ctrl:1
	v_add_f32_dpp v97, v97, v97 quad_perm:[1,0,3,2] row_mask:0xf bank_mask:0xf bound_ctrl:1
	v_add_f32_dpp v98, v98, v98 quad_perm:[1,0,3,2] row_mask:0xf bank_mask:0xf bound_ctrl:1
	v_add_f32_dpp v99, v99, v99 quad_perm:[1,0,3,2] row_mask:0xf bank_mask:0xf bound_ctrl:1
	v_add_f32_dpp v100, v100, v100 quad_perm:[1,0,3,2] row_mask:0xf bank_mask:0xf bound_ctrl:1
	v_add_f32_dpp v101, v101, v101 quad_perm:[1,0,3,2] row_mask:0xf bank_mask:0xf bound_ctrl:1
	v_add_f32_dpp v102, v102, v102 quad_perm:[1,0,3,2] row_mask:0xf bank_mask:0xf bound_ctrl:1
	v_add_f32_dpp v103, v103, v103 quad_perm:[1,0,3,2] row_mask:0xf bank_mask:0xf bound_ctrl:1
	v_add_f32_dpp v104, v104, v104 quad_perm:[1,0,3,2] row_mask:0xf bank_mask:0xf bound_ctrl:1
	v_add_f32_dpp v105, v105, v105 quad_perm:[1,0,3,2] row_mask:0xf bank_mask:0xf bound_ctrl:1
	v_add_f32_dpp v106, v106, v106 quad_perm:[1,0,3,2] row_mask:0xf bank_mask:0xf bound_ctrl:1
	v_add_f32_dpp v107, v107, v107 quad_perm:[1,0,3,2] row_mask:0xf bank_mask:0xf bound_ctrl:1
	v_add_f32_dpp v108, v108, v108 quad_perm:[1,0,3,2] row_mask:0xf bank_mask:0xf bound_ctrl:1
	v_add_f32_dpp v109, v109, v109 quad_perm:[1,0,3,2] row_mask:0xf bank_mask:0xf bound_ctrl:1
	v_add_f32_dpp v110, v110, v110 quad_perm:[1,0,3,2] row_mask:0xf bank_mask:0xf bound_ctrl:1
	v_add_f32_dpp v111, v111, v111 quad_perm:[1,0,3,2] row_mask:0xf bank_mask:0xf bound_ctrl:1
	v_add_f32_dpp v112, v112, v112 quad_perm:[1,0,3,2] row_mask:0xf bank_mask:0xf bound_ctrl:1
	v_add_f32_dpp v113, v113, v113 quad_perm:[1,0,3,2] row_mask:0xf bank_mask:0xf bound_ctrl:1
	v_add_f32_dpp v114, v114, v114 quad_perm:[1,0,3,2] row_mask:0xf bank_mask:0xf bound_ctrl:1
	v_add_f32_dpp v115, v115, v115 quad_perm:[1,0,3,2] row_mask:0xf bank_mask:0xf bound_ctrl:1
	v_add_f32_dpp v116, v116, v116 quad_perm:[1,0,3,2] row_mask:0xf bank_mask:0xf bound_ctrl:1
	v_add_f32_dpp v117, v117, v117 quad_perm:[1,0,3,2] row_mask:0xf bank_mask:0xf bound_ctrl:1
	v_add_f32_dpp v118, v118, v118 quad_perm:[1,0,3,2] row_mask:0xf bank_mask:0xf bound_ctrl:1
	v_add_f32_dpp v119, v119, v119 quad_perm:[1,0,3,2] row_mask:0xf bank_mask:0xf bound_ctrl:1
	v_add_f32_dpp v120, v120, v120 quad_perm:[1,0,3,2] row_mask:0xf bank_mask:0xf bound_ctrl:1
	v_add_f32_dpp v121, v121, v121 quad_perm:[1,0,3,2] row_mask:0xf bank_mask:0xf bound_ctrl:1
	v_add_f32_dpp v122, v122, v122 quad_perm:[1,0,3,2] row_mask:0xf bank_mask:0xf bound_ctrl:1
	v_add_f32_dpp v123, v123, v123 quad_perm:[1,0,3,2] row_mask:0xf bank_mask:0xf bound_ctrl:1
	v_add_f32_dpp v92, v92, v92 quad_perm:[2,3,0,1] row_mask:0xf bank_mask:0xf bound_ctrl:1
	v_add_f32_dpp v93, v93, v93 quad_perm:[2,3,0,1] row_mask:0xf bank_mask:0xf bound_ctrl:1
	v_add_f32_dpp v94, v94, v94 quad_perm:[2,3,0,1] row_mask:0xf bank_mask:0xf bound_ctrl:1
	v_add_f32_dpp v95, v95, v95 quad_perm:[2,3,0,1] row_mask:0xf bank_mask:0xf bound_ctrl:1
	v_add_f32_dpp v96, v96, v96 quad_perm:[2,3,0,1] row_mask:0xf bank_mask:0xf bound_ctrl:1
	v_add_f32_dpp v97, v97, v97 quad_perm:[2,3,0,1] row_mask:0xf bank_mask:0xf bound_ctrl:1
	v_add_f32_dpp v98, v98, v98 quad_perm:[2,3,0,1] row_mask:0xf bank_mask:0xf bound_ctrl:1
	v_add_f32_dpp v99, v99, v99 quad_perm:[2,3,0,1] row_mask:0xf bank_mask:0xf bound_ctrl:1
	v_add_f32_dpp v100, v100, v100 quad_perm:[2,3,0,1] row_mask:0xf bank_mask:0xf bound_ctrl:1
	v_add_f32_dpp v101, v101, v101 quad_perm:[2,3,0,1] row_mask:0xf bank_mask:0xf bound_ctrl:1
	v_add_f32_dpp v102, v102, v102 quad_perm:[2,3,0,1] row_mask:0xf bank_mask:0xf bound_ctrl:1
	v_add_f32_dpp v103, v103, v103 quad_perm:[2,3,0,1] row_mask:0xf bank_mask:0xf bound_ctrl:1
	v_add_f32_dpp v104, v104, v104 quad_perm:[2,3,0,1] row_mask:0xf bank_mask:0xf bound_ctrl:1
	v_add_f32_dpp v105, v105, v105 quad_perm:[2,3,0,1] row_mask:0xf bank_mask:0xf bound_ctrl:1
	v_add_f32_dpp v106, v106, v106 quad_perm:[2,3,0,1] row_mask:0xf bank_mask:0xf bound_ctrl:1
	v_add_f32_dpp v107, v107, v107 quad_perm:[2,3,0,1] row_mask:0xf bank_mask:0xf bound_ctrl:1
	v_add_f32_dpp v108, v108, v108 quad_perm:[2,3,0,1] row_mask:0xf bank_mask:0xf bound_ctrl:1
	v_add_f32_dpp v109, v109, v109 quad_perm:[2,3,0,1] row_mask:0xf bank_mask:0xf bound_ctrl:1
	v_add_f32_dpp v110, v110, v110 quad_perm:[2,3,0,1] row_mask:0xf bank_mask:0xf bound_ctrl:1
	v_add_f32_dpp v111, v111, v111 quad_perm:[2,3,0,1] row_mask:0xf bank_mask:0xf bound_ctrl:1
	v_add_f32_dpp v112, v112, v112 quad_perm:[2,3,0,1] row_mask:0xf bank_mask:0xf bound_ctrl:1
	v_add_f32_dpp v113, v113, v113 quad_perm:[2,3,0,1] row_mask:0xf bank_mask:0xf bound_ctrl:1
	v_add_f32_dpp v114, v114, v114 quad_perm:[2,3,0,1] row_mask:0xf bank_mask:0xf bound_ctrl:1
	v_add_f32_dpp v115, v115, v115 quad_perm:[2,3,0,1] row_mask:0xf bank_mask:0xf bound_ctrl:1
	v_add_f32_dpp v116, v116, v116 quad_perm:[2,3,0,1] row_mask:0xf bank_mask:0xf bound_ctrl:1
	v_add_f32_dpp v117, v117, v117 quad_perm:[2,3,0,1] row_mask:0xf bank_mask:0xf bound_ctrl:1
	v_add_f32_dpp v118, v118, v118 quad_perm:[2,3,0,1] row_mask:0xf bank_mask:0xf bound_ctrl:1
	v_add_f32_dpp v119, v119, v119 quad_perm:[2,3,0,1] row_mask:0xf bank_mask:0xf bound_ctrl:1
	v_add_f32_dpp v120, v120, v120 quad_perm:[2,3,0,1] row_mask:0xf bank_mask:0xf bound_ctrl:1
	v_add_f32_dpp v121, v121, v121 quad_perm:[2,3,0,1] row_mask:0xf bank_mask:0xf bound_ctrl:1
	v_add_f32_dpp v122, v122, v122 quad_perm:[2,3,0,1] row_mask:0xf bank_mask:0xf bound_ctrl:1
	v_add_f32_dpp v123, v123, v123 quad_perm:[2,3,0,1] row_mask:0xf bank_mask:0xf bound_ctrl:1
	v_add_f32_dpp v92, v92, v92 row_half_mirror row_mask:0xf bank_mask:0xf bound_ctrl:1
	v_add_f32_dpp v93, v93, v93 row_half_mirror row_mask:0xf bank_mask:0xf bound_ctrl:1
	v_add_f32_dpp v94, v94, v94 row_half_mirror row_mask:0xf bank_mask:0xf bound_ctrl:1
	v_add_f32_dpp v95, v95, v95 row_half_mirror row_mask:0xf bank_mask:0xf bound_ctrl:1
	v_add_f32_dpp v96, v96, v96 row_half_mirror row_mask:0xf bank_mask:0xf bound_ctrl:1
	v_add_f32_dpp v97, v97, v97 row_half_mirror row_mask:0xf bank_mask:0xf bound_ctrl:1
	v_add_f32_dpp v98, v98, v98 row_half_mirror row_mask:0xf bank_mask:0xf bound_ctrl:1
	v_add_f32_dpp v99, v99, v99 row_half_mirror row_mask:0xf bank_mask:0xf bound_ctrl:1
	v_add_f32_dpp v100, v100, v100 row_half_mirror row_mask:0xf bank_mask:0xf bound_ctrl:1
	v_add_f32_dpp v101, v101, v101 row_half_mirror row_mask:0xf bank_mask:0xf bound_ctrl:1
	v_add_f32_dpp v102, v102, v102 row_half_mirror row_mask:0xf bank_mask:0xf bound_ctrl:1
	v_add_f32_dpp v103, v103, v103 row_half_mirror row_mask:0xf bank_mask:0xf bound_ctrl:1
	v_add_f32_dpp v104, v104, v104 row_half_mirror row_mask:0xf bank_mask:0xf bound_ctrl:1
	v_add_f32_dpp v105, v105, v105 row_half_mirror row_mask:0xf bank_mask:0xf bound_ctrl:1
	v_add_f32_dpp v106, v106, v106 row_half_mirror row_mask:0xf bank_mask:0xf bound_ctrl:1
	v_add_f32_dpp v107, v107, v107 row_half_mirror row_mask:0xf bank_mask:0xf bound_ctrl:1
	v_add_f32_dpp v108, v108, v108 row_half_mirror row_mask:0xf bank_mask:0xf bound_ctrl:1
	v_add_f32_dpp v109, v109, v109 row_half_mirror row_mask:0xf bank_mask:0xf bound_ctrl:1
	v_add_f32_dpp v110, v110, v110 row_half_mirror row_mask:0xf bank_mask:0xf bound_ctrl:1
	v_add_f32_dpp v111, v111, v111 row_half_mirror row_mask:0xf bank_mask:0xf bound_ctrl:1
	v_add_f32_dpp v112, v112, v112 row_half_mirror row_mask:0xf bank_mask:0xf bound_ctrl:1
	v_add_f32_dpp v113, v113, v113 row_half_mirror row_mask:0xf bank_mask:0xf bound_ctrl:1
	v_add_f32_dpp v114, v114, v114 row_half_mirror row_mask:0xf bank_mask:0xf bound_ctrl:1
	v_add_f32_dpp v115, v115, v115 row_half_mirror row_mask:0xf bank_mask:0xf bound_ctrl:1
	v_add_f32_dpp v116, v116, v116 row_half_mirror row_mask:0xf bank_mask:0xf bound_ctrl:1
	v_add_f32_dpp v117, v117, v117 row_half_mirror row_mask:0xf bank_mask:0xf bound_ctrl:1
	v_add_f32_dpp v118, v118, v118 row_half_mirror row_mask:0xf bank_mask:0xf bound_ctrl:1
	v_add_f32_dpp v119, v119, v119 row_half_mirror row_mask:0xf bank_mask:0xf bound_ctrl:1
	v_add_f32_dpp v120, v120, v120 row_half_mirror row_mask:0xf bank_mask:0xf bound_ctrl:1
	v_add_f32_dpp v121, v121, v121 row_half_mirror row_mask:0xf bank_mask:0xf bound_ctrl:1
	v_add_f32_dpp v122, v122, v122 row_half_mirror row_mask:0xf bank_mask:0xf bound_ctrl:1
	v_add_f32_dpp v123, v123, v123 row_half_mirror row_mask:0xf bank_mask:0xf bound_ctrl:1
	s_mov_b64 s[2:3], exec
	s_mov_b64 exec, s[4:5]
	v_accvgpr_read_b32 v44, a128
	v_accvgpr_read_b32 v45, a129
	v_accvgpr_read_b32 v46, a130
	v_accvgpr_read_b32 v47, a131
	v_cvt_f32_f16_e32 v56, v44
	v_cvt_f32_f16_sdwa v57, v44 dst_sel:DWORD dst_unused:UNUSED_PAD src0_sel:WORD_1
	v_cvt_f32_f16_e32 v58, v45
	v_cvt_f32_f16_sdwa v59, v45 dst_sel:DWORD dst_unused:UNUSED_PAD src0_sel:WORD_1
	v_cvt_f32_f16_e32 v60, v46
	v_cvt_f32_f16_sdwa v61, v46 dst_sel:DWORD dst_unused:UNUSED_PAD src0_sel:WORD_1
	v_cvt_f32_f16_e32 v62, v47
	v_cvt_f32_f16_sdwa v63, v47 dst_sel:DWORD dst_unused:UNUSED_PAD src0_sel:WORD_1
	v_pk_mul_f32 v[92:93], v[92:93], v[56:57]
	v_pk_mul_f32 v[94:95], v[94:95], v[58:59]
	v_pk_mul_f32 v[96:97], v[96:97], v[60:61]
	v_pk_mul_f32 v[98:99], v[98:99], v[62:63]
	v_cvt_pk_f16_f32 v64, v92, v93
	v_cvt_pk_f16_f32 v65, v94, v95
	v_cvt_pk_f16_f32 v66, v96, v97
	v_cvt_pk_f16_f32 v67, v98, v99
	global_store_dwordx4 v70, v[64:67], s[96:97] offset:1536
	v_accvgpr_read_b32 v44, a132
	v_accvgpr_read_b32 v45, a133
	v_accvgpr_read_b32 v46, a134
	v_accvgpr_read_b32 v47, a135
	v_cvt_f32_f16_e32 v56, v44
	v_cvt_f32_f16_sdwa v57, v44 dst_sel:DWORD dst_unused:UNUSED_PAD src0_sel:WORD_1
	v_cvt_f32_f16_e32 v58, v45
	v_cvt_f32_f16_sdwa v59, v45 dst_sel:DWORD dst_unused:UNUSED_PAD src0_sel:WORD_1
	v_cvt_f32_f16_e32 v60, v46
	v_cvt_f32_f16_sdwa v61, v46 dst_sel:DWORD dst_unused:UNUSED_PAD src0_sel:WORD_1
	v_cvt_f32_f16_e32 v62, v47
	v_cvt_f32_f16_sdwa v63, v47 dst_sel:DWORD dst_unused:UNUSED_PAD src0_sel:WORD_1
	v_pk_mul_f32 v[100:101], v[100:101], v[56:57]
	v_pk_mul_f32 v[102:103], v[102:103], v[58:59]
	v_pk_mul_f32 v[104:105], v[104:105], v[60:61]
	v_pk_mul_f32 v[106:107], v[106:107], v[62:63]
	v_cvt_pk_f16_f32 v48, v100, v101
	v_cvt_pk_f16_f32 v49, v102, v103
	v_cvt_pk_f16_f32 v50, v104, v105
	v_cvt_pk_f16_f32 v51, v106, v107
	global_store_dwordx4 v70, v[48:51], s[96:97] offset:1664
	v_accvgpr_read_b32 v44, a136
	v_accvgpr_read_b32 v45, a137
	v_accvgpr_read_b32 v46, a138
	v_accvgpr_read_b32 v47, a139
	v_cvt_f32_f16_e32 v56, v44
	v_cvt_f32_f16_sdwa v57, v44 dst_sel:DWORD dst_unused:UNUSED_PAD src0_sel:WORD_1
	v_cvt_f32_f16_e32 v58, v45
	v_cvt_f32_f16_sdwa v59, v45 dst_sel:DWORD dst_unused:UNUSED_PAD src0_sel:WORD_1
	v_cvt_f32_f16_e32 v60, v46
	v_cvt_f32_f16_sdwa v61, v46 dst_sel:DWORD dst_unused:UNUSED_PAD src0_sel:WORD_1
	v_cvt_f32_f16_e32 v62, v47
	v_cvt_f32_f16_sdwa v63, v47 dst_sel:DWORD dst_unused:UNUSED_PAD src0_sel:WORD_1
	v_pk_mul_f32 v[108:109], v[108:109], v[56:57]
	v_pk_mul_f32 v[110:111], v[110:111], v[58:59]
	v_pk_mul_f32 v[112:113], v[112:113], v[60:61]
	v_pk_mul_f32 v[114:115], v[114:115], v[62:63]
	v_cvt_pk_f16_f32 v64, v108, v109
	v_cvt_pk_f16_f32 v65, v110, v111
	v_cvt_pk_f16_f32 v66, v112, v113
	v_cvt_pk_f16_f32 v67, v114, v115
	global_store_dwordx4 v70, v[64:67], s[96:97] offset:1792
	v_accvgpr_read_b32 v44, a140
	v_accvgpr_read_b32 v45, a141
	v_accvgpr_read_b32 v46, a142
	v_accvgpr_read_b32 v47, a143
	v_cvt_f32_f16_e32 v56, v44
	v_cvt_f32_f16_sdwa v57, v44 dst_sel:DWORD dst_unused:UNUSED_PAD src0_sel:WORD_1
	v_cvt_f32_f16_e32 v58, v45
	v_cvt_f32_f16_sdwa v59, v45 dst_sel:DWORD dst_unused:UNUSED_PAD src0_sel:WORD_1
	v_cvt_f32_f16_e32 v60, v46
	v_cvt_f32_f16_sdwa v61, v46 dst_sel:DWORD dst_unused:UNUSED_PAD src0_sel:WORD_1
	v_cvt_f32_f16_e32 v62, v47
	v_cvt_f32_f16_sdwa v63, v47 dst_sel:DWORD dst_unused:UNUSED_PAD src0_sel:WORD_1
	v_pk_mul_f32 v[116:117], v[116:117], v[56:57]
	v_pk_mul_f32 v[118:119], v[118:119], v[58:59]
	v_pk_mul_f32 v[120:121], v[120:121], v[60:61]
	v_pk_mul_f32 v[122:123], v[122:123], v[62:63]
	v_cvt_pk_f16_f32 v48, v116, v117
	v_cvt_pk_f16_f32 v49, v118, v119
	v_cvt_pk_f16_f32 v50, v120, v121
	v_cvt_pk_f16_f32 v51, v122, v123
	global_store_dwordx4 v70, v[48:51], s[96:97] offset:1920
	s_mov_b64 exec, s[2:3]
	s_add_i32 s6, s6, 1
	v_mov_b32_e32 v70, v71
	s_cmp_lg_u32 s6, 16
	s_cbranch_scc1 .Latt_query
	v_readlane_b32 s54, v255, 38
	s_movk_i32 s58, 0x1000
	s_branch .LBB0_97
.Ltramp_733:
	s_branch .LBB0_733
.Ltramp_15:
	s_branch .LBB0_15
.Ltramp_14:
	s_branch .LBB0_14
.Ltramp_13:
	s_branch .LBB0_13
.LBB0_305:
	v_readlane_b32 s2, v254, 15
	v_readlane_b32 s3, v254, 16
	s_andn2_b64 vcc, exec, s[2:3]
	v_readlane_b32 s55, v255, 39
	s_cbranch_vccnz .LBB0_318
	v_readlane_b32 s2, v255, 47
	v_readlane_b32 s3, v255, 48
	s_mov_b32 s4, s2
	s_lshl_b32 s8, s2, 8
	s_ashr_i32 s5, s2, 31
	v_writelane_b32 v255, s2, 47
	v_readlane_b32 s12, v253, 6
	v_readlane_b32 s13, v253, 7
	v_writelane_b32 v255, s3, 48
	s_lshl_b64 s[2:3], s[4:5], 14
	s_add_u32 s9, s12, s2
	s_addc_u32 s10, s13, s3
	s_ashr_i32 s11, s8, 31
	s_mov_b32 s4, s54
	v_readlane_b32 s14, v253, 8
	v_readlane_b32 s15, v253, 9
	v_readlane_b32 s16, v253, 10
	v_readlane_b32 s17, v253, 11
	v_readlane_b32 s18, v253, 12
	v_readlane_b32 s19, v253, 13
	v_readlane_b32 s20, v253, 14
	v_readlane_b32 s21, v253, 15
	v_readlane_b32 s22, v253, 16
	v_readlane_b32 s23, v253, 17
	v_readlane_b32 s24, v253, 18
	v_readlane_b32 s25, v253, 19
	v_readlane_b32 s26, v253, 20
	v_readlane_b32 s27, v253, 21
	s_branch .LBB0_308
